# v22 + GEMM K-loops: DMA address add placed between the M0 write and the LDS-DMA load, removing the s_nop pad (64 sites)
# baseline (speedup 1.0000x reference)
; #define G_STAGE(bufoff, gbase, v0, v1) do { \
;     __builtin_amdgcn_global_load_lds((const unsigned*)((const char*)(gbase) + (v0)), (LAS unsigned*)(lds + (bufoff) + ldsw), 16, 0, 0); \
;     __builtin_amdgcn_global_load_lds((const unsigned*)((const char*)(gbase) + (v1)), (LAS unsigned*)(lds + (bufoff) + ldsw + 8192), 16, 0, 0); } while (0)
; #define G_LDA(dst, b, h) do { _Pragma("unroll") for (int m = 0; m < 4; ++m) _Pragma("unroll") for (int k = 0; k < 2; ++k) dst[m][k] = *(const LAS h8*)(lds + G_SA(b, h) + aoff + m * 2048 + k * 1024); } while (0)
; #define G_LDB(dst, b, h) do { _Pragma("unroll") for (int n = 0; n < 2; ++n) _Pragma("unroll") for (int k = 0; k < 2; ++k) dst[n][k] = *(const LAS h8*)(lds + G_SB(b, h) + boff + n * 2048 + k * 1024); } while (0)
; #define G_MMA(ai, bj, At, Bt) do { __builtin_amdgcn_s_setprio(1); _Pragma("unroll") for (int m = 0; m < 4; ++m) _Pragma("unroll") for (int n = 0; n < 2; ++n) _Pragma("unroll") for (int k = 0; k < 2; ++k) \
;     acc[ai][bj][m][n] = __builtin_amdgcn_mfma_f32_16x16x32_f16(Bt[n][k], At[m][k], acc[ai][bj][m][n], 0, 0, 0); __builtin_amdgcn_s_setprio(0); } while (0)
; #define G_WAIT_V(n) asm volatile("s_waitcnt vmcnt(" #n ")" ::: "memory")
; #define G_WAIT_L(n) asm volatile("s_waitcnt lgkmcnt(" #n ")" ::: "memory")
; #define G_BAR __builtin_amdgcn_s_barrier()
; #define G_SCHED __builtin_amdgcn_sched_barrier(0)
; template <bool PERM, class Sched, class Epi>
; DI void gemm256(LAS unsigned char* lds, const Sched& S, const Epi& E, int wv_) {
;     ...
;       const bool last = (t == nt - 2);
;       const char* a1 = cA + (size_t)(t + 1) * kstep;
;       const char* a2 = last ? nA : cA + (size_t)(t + 2) * kstep;
;       const char* b2 = last ? nB : cB + (size_t)(t + 2) * kstep;
;       const char* a3 = a2 + kstep;
;       const char* b3 = b2 + kstep;
;       G_LDB(B0, 0, 0); G_SCHED; G_LDA(At, 0, 0); G_STAGE(G_SA(1, 1), a1 + chA, cvA0, cvA1);
;       G_WAIT_L(8); G_BAR; G_WAIT_L(0); G_MMA(0, 0, At, B0); G_BAR; G_SCHED;
;       G_LDB(B1, 0, 1); G_STAGE(G_SB(0, 0), b2, cvB0, cvB1);
;       G_BAR; G_WAIT_L(0); G_MMA(0, 1, At, B1); G_BAR;
;       G_LDA(At, 0, 1); G_STAGE(G_SA(0, 0), a2, cvA0, cvA1);
;       G_BAR; G_WAIT_L(0); G_MMA(1, 0, At, B0); G_BAR; G_SCHED;
;       G_STAGE(G_SB(0, 1), b2 + chB, cvB0, cvB1);
;       G_WAIT_V(6); G_BAR; G_MMA(1, 1, At, B1); G_BAR;
.LBB0_1503:
	s_add_i32 s91, s12, 2
	ds_read_b128 v[146:149], v218
	ds_read_b128 v[150:153], v218 offset:1024
	ds_read_b128 v[154:157], v218 offset:2048
	ds_read_b128 v[158:161], v218 offset:3072
	s_add_u32 s13, s10, 0xfffc0080
	s_addc_u32 s14, s11, -1
	s_cmp_eq_u32 s75, s12
	s_cselect_b32 s12, s90, s46
	s_cselect_b32 s15, s16, s14
	s_cselect_b32 s14, s17, s13
	s_cselect_b32 s13, s85, s74
	s_mov_b32 m0, s59
	v_lshl_add_u64 v[194:195], s[10:11], 0, v[138:139]
	ds_read_b128 v[162:165], v142
	ds_read_b128 v[166:169], v142 offset:1024
	ds_read_b128 v[170:173], v142 offset:2048
	ds_read_b128 v[174:177], v142 offset:3072
	ds_read_b128 v[178:181], v142 offset:4096
	ds_read_b128 v[182:185], v142 offset:5120
	ds_read_b128 v[186:189], v142 offset:6144
	ds_read_b128 v[190:193], v142 offset:7168
	global_load_lds_dwordx4 v[194:195], off
	s_mov_b32 m0, s60
	v_lshl_add_u64 v[194:195], s[10:11], 0, v[140:141]
	global_load_lds_dwordx4 v[194:195], off
	s_waitcnt lgkmcnt(8)
	s_barrier
	s_waitcnt lgkmcnt(0)
	s_waitcnt lgkmcnt(0)
	v_mfma_f32_16x16x32_f16 v[122:125], v[146:149], v[162:165], v[122:125]
	v_mfma_f32_16x16x32_f16 v[126:129], v[154:157], v[162:165], v[126:129]
	v_mfma_f32_16x16x32_f16 v[114:117], v[146:149], v[170:173], v[114:117]
	v_mfma_f32_16x16x32_f16 v[118:121], v[154:157], v[170:173], v[118:121]
	v_mfma_f32_16x16x32_f16 v[106:109], v[146:149], v[178:181], v[106:109]
	v_mfma_f32_16x16x32_f16 v[110:113], v[154:157], v[178:181], v[110:113]
	v_mfma_f32_16x16x32_f16 v[98:101], v[146:149], v[186:189], v[98:101]
	v_mfma_f32_16x16x32_f16 v[102:105], v[154:157], v[186:189], v[102:105]
	v_mfma_f32_16x16x32_f16 v[122:125], v[150:153], v[166:169], v[122:125]
	v_mfma_f32_16x16x32_f16 v[126:129], v[158:161], v[166:169], v[126:129]
	v_mfma_f32_16x16x32_f16 v[114:117], v[150:153], v[174:177], v[114:117]
	v_mfma_f32_16x16x32_f16 v[118:121], v[158:161], v[174:177], v[118:121]
	v_mfma_f32_16x16x32_f16 v[106:109], v[150:153], v[182:185], v[106:109]
	v_mfma_f32_16x16x32_f16 v[110:113], v[158:161], v[182:185], v[110:113]
	v_mfma_f32_16x16x32_f16 v[98:101], v[150:153], v[190:193], v[98:101]
	v_mfma_f32_16x16x32_f16 v[102:105], v[158:161], v[190:193], v[102:105]
	s_barrier
	s_mov_b32 m0, s20
	v_lshl_add_u64 v[210:211], s[12:13], 0, v[132:133]
	ds_read_b128 v[194:197], v219
	ds_read_b128 v[198:201], v219 offset:1024
	ds_read_b128 v[202:205], v219 offset:2048
	ds_read_b128 v[206:209], v219 offset:3072
	global_load_lds_dwordx4 v[210:211], off
	s_mov_b32 m0, s21
	v_lshl_add_u64 v[212:213], s[12:13], 0, v[136:137]
	global_load_lds_dwordx4 v[212:213], off
	s_barrier
	s_waitcnt lgkmcnt(0)
	s_waitcnt lgkmcnt(0)
	v_mfma_f32_16x16x32_f16 v[58:61], v[194:197], v[162:165], v[58:61]
	v_mfma_f32_16x16x32_f16 v[62:65], v[202:205], v[162:165], v[62:65]
	v_mfma_f32_16x16x32_f16 v[50:53], v[194:197], v[170:173], v[50:53]
	v_mfma_f32_16x16x32_f16 v[54:57], v[202:205], v[170:173], v[54:57]
	v_mfma_f32_16x16x32_f16 v[42:45], v[194:197], v[178:181], v[42:45]
	v_mfma_f32_16x16x32_f16 v[46:49], v[202:205], v[178:181], v[46:49]
	v_mfma_f32_16x16x32_f16 v[34:37], v[194:197], v[186:189], v[34:37]
	v_mfma_f32_16x16x32_f16 v[38:41], v[202:205], v[186:189], v[38:41]
	v_mfma_f32_16x16x32_f16 v[58:61], v[198:201], v[166:169], v[58:61]
	v_mfma_f32_16x16x32_f16 v[62:65], v[206:209], v[166:169], v[62:65]
	v_mfma_f32_16x16x32_f16 v[50:53], v[198:201], v[174:177], v[50:53]
	v_mfma_f32_16x16x32_f16 v[54:57], v[206:209], v[174:177], v[54:57]
	v_mfma_f32_16x16x32_f16 v[42:45], v[198:201], v[182:185], v[42:45]
	v_mfma_f32_16x16x32_f16 v[46:49], v[206:209], v[182:185], v[46:49]
	v_mfma_f32_16x16x32_f16 v[34:37], v[198:201], v[190:193], v[34:37]
	v_mfma_f32_16x16x32_f16 v[38:41], v[206:209], v[190:193], v[38:41]
	s_mov_b32 m0, s19
	v_lshl_add_u64 v[214:215], s[14:15], 0, v[130:131]
	s_barrier
	ds_read_b128 v[162:165], v142 offset:16384
	ds_read_b128 v[166:169], v142 offset:17408
	ds_read_b128 v[170:173], v142 offset:18432
	ds_read_b128 v[174:177], v142 offset:19456
	ds_read_b128 v[178:181], v142 offset:20480
	ds_read_b128 v[182:185], v142 offset:21504
	ds_read_b128 v[186:189], v142 offset:22528
	ds_read_b128 v[190:193], v142 offset:23552
	global_load_lds_dwordx4 v[214:215], off
	s_mov_b32 m0, s22
	v_lshl_add_u64 v[216:217], s[14:15], 0, v[134:135]
	global_load_lds_dwordx4 v[216:217], off
	s_barrier
	s_waitcnt lgkmcnt(0)
	s_waitcnt lgkmcnt(0)
	v_mfma_f32_16x16x32_f16 v[90:93], v[146:149], v[162:165], v[90:93]
	v_mfma_f32_16x16x32_f16 v[94:97], v[154:157], v[162:165], v[94:97]
	v_mfma_f32_16x16x32_f16 v[82:85], v[146:149], v[170:173], v[82:85]
	v_mfma_f32_16x16x32_f16 v[86:89], v[154:157], v[170:173], v[86:89]
	v_mfma_f32_16x16x32_f16 v[74:77], v[146:149], v[178:181], v[74:77]
	v_mfma_f32_16x16x32_f16 v[78:81], v[154:157], v[178:181], v[78:81]
	v_mfma_f32_16x16x32_f16 v[66:69], v[146:149], v[186:189], v[66:69]
	v_mfma_f32_16x16x32_f16 v[70:73], v[154:157], v[186:189], v[70:73]
	v_mfma_f32_16x16x32_f16 v[90:93], v[150:153], v[166:169], v[90:93]
	v_mfma_f32_16x16x32_f16 v[94:97], v[158:161], v[166:169], v[94:97]
	v_mfma_f32_16x16x32_f16 v[82:85], v[150:153], v[174:177], v[82:85]
	v_mfma_f32_16x16x32_f16 v[86:89], v[158:161], v[174:177], v[86:89]
	v_mfma_f32_16x16x32_f16 v[74:77], v[150:153], v[182:185], v[74:77]
	v_mfma_f32_16x16x32_f16 v[78:81], v[158:161], v[182:185], v[78:81]
	v_mfma_f32_16x16x32_f16 v[66:69], v[150:153], v[190:193], v[66:69]
	v_mfma_f32_16x16x32_f16 v[70:73], v[158:161], v[190:193], v[70:73]
	s_barrier
	s_add_u32 vcc_lo, s12, 0x40000
	s_addc_u32 vcc_hi, s13, 0
	s_mov_b32 m0, s23
	v_lshl_add_u64 v[146:147], vcc, 0, v[132:133]
	global_load_lds_dwordx4 v[146:147], off
	s_mov_b32 m0, s24
	v_lshl_add_u64 v[146:147], vcc, 0, v[136:137]
	global_load_lds_dwordx4 v[146:147], off
	s_waitcnt vmcnt(6)
	s_barrier
; #define G_STAGE(bufoff, gbase, v0, v1) do { \
;     __builtin_amdgcn_global_load_lds((const unsigned*)((const char*)(gbase) + (v0)), (LAS unsigned*)(lds + (bufoff) + ldsw), 16, 0, 0); \
;     __builtin_amdgcn_global_load_lds((const unsigned*)((const char*)(gbase) + (v1)), (LAS unsigned*)(lds + (bufoff) + ldsw + 8192), 16, 0, 0); } while (0)
; #define G_LDA(dst, b, h) do { _Pragma("unroll") for (int m = 0; m < 4; ++m) _Pragma("unroll") for (int k = 0; k < 2; ++k) dst[m][k] = *(const LAS h8*)(lds + G_SA(b, h) + aoff + m * 2048 + k * 1024); } while (0)
; #define G_LDB(dst, b, h) do { _Pragma("unroll") for (int n = 0; n < 2; ++n) _Pragma("unroll") for (int k = 0; k < 2; ++k) dst[n][k] = *(const LAS h8*)(lds + G_SB(b, h) + boff + n * 2048 + k * 1024); } while (0)
; #define G_MMA(ai, bj, At, Bt) do { __builtin_amdgcn_s_setprio(1); _Pragma("unroll") for (int m = 0; m < 4; ++m) _Pragma("unroll") for (int n = 0; n < 2; ++n) _Pragma("unroll") for (int k = 0; k < 2; ++k) \
;     acc[ai][bj][m][n] = __builtin_amdgcn_mfma_f32_16x16x32_f16(Bt[n][k], At[m][k], acc[ai][bj][m][n], 0, 0, 0); __builtin_amdgcn_s_setprio(0); } while (0)
; #define G_WAIT_V(n) asm volatile("s_waitcnt vmcnt(" #n ")" ::: "memory")
; #define G_WAIT_L(n) asm volatile("s_waitcnt lgkmcnt(" #n ")" ::: "memory")
; #define G_BAR __builtin_amdgcn_s_barrier()
; #define G_SCHED __builtin_amdgcn_sched_barrier(0)
; template <bool PERM, class Sched, class Epi>
; DI void gemm256(LAS unsigned char* lds, const Sched& S, const Epi& E, int wv_) {
;     ...
;       G_WAIT_V(6); G_BAR; G_MMA(1, 1, At, B1); G_BAR;
;       G_LDB(B0, 1, 0); G_SCHED; G_LDA(At, 1, 0); G_STAGE(G_SA(0, 1), a2 + chA, cvA0, cvA1);
;       G_WAIT_L(8); G_BAR; G_WAIT_L(0); G_MMA(0, 0, At, B0); G_BAR; G_SCHED;
;       G_LDB(B1, 1, 1); G_STAGE(G_SB(1, 0), b3, cvB0, cvB1);
;       G_BAR; G_WAIT_L(0); G_MMA(0, 1, At, B1); G_BAR;
	v_mfma_f32_16x16x32_f16 v[26:29], v[194:197], v[162:165], v[26:29]
	v_mfma_f32_16x16x32_f16 v[30:33], v[202:205], v[162:165], v[30:33]
	v_mfma_f32_16x16x32_f16 v[18:21], v[194:197], v[170:173], v[18:21]
	v_mfma_f32_16x16x32_f16 v[22:25], v[202:205], v[170:173], v[22:25]
	v_mfma_f32_16x16x32_f16 v[10:13], v[194:197], v[178:181], v[10:13]
	v_mfma_f32_16x16x32_f16 v[14:17], v[202:205], v[178:181], v[14:17]
	v_mfma_f32_16x16x32_f16 v[6:9], v[194:197], v[186:189], v[6:9]
	v_mfma_f32_16x16x32_f16 v[2:5], v[202:205], v[186:189], v[2:5]
	v_mfma_f32_16x16x32_f16 v[26:29], v[198:201], v[166:169], v[26:29]
	v_mfma_f32_16x16x32_f16 v[30:33], v[206:209], v[166:169], v[30:33]
	v_mfma_f32_16x16x32_f16 v[18:21], v[198:201], v[174:177], v[18:21]
	v_mfma_f32_16x16x32_f16 v[22:25], v[206:209], v[174:177], v[22:25]
	v_mfma_f32_16x16x32_f16 v[10:13], v[198:201], v[182:185], v[10:13]
	v_mfma_f32_16x16x32_f16 v[14:17], v[206:209], v[182:185], v[14:17]
	v_mfma_f32_16x16x32_f16 v[6:9], v[198:201], v[190:193], v[6:9]
	v_mfma_f32_16x16x32_f16 v[2:5], v[206:209], v[190:193], v[2:5]
	s_barrier
	ds_read_b128 v[146:149], v220
	ds_read_b128 v[150:153], v220 offset:1024
	ds_read_b128 v[154:157], v220 offset:2048
	ds_read_b128 v[158:161], v220 offset:3072
	s_add_u32 s14, s14, 0x40000
	s_addc_u32 s15, s15, 0
	s_mov_b32 m0, s25
	v_lshl_add_u64 v[194:195], s[14:15], 0, v[130:131]
	ds_read_b128 v[162:165], v142 offset:32768
	ds_read_b128 v[166:169], v142 offset:33792
	ds_read_b128 v[170:173], v142 offset:34816
	ds_read_b128 v[174:177], v142 offset:35840
	ds_read_b128 v[178:181], v142 offset:36864
	ds_read_b128 v[182:185], v142 offset:37888
	ds_read_b128 v[186:189], v142 offset:38912
	ds_read_b128 v[190:193], v142 offset:39936
	global_load_lds_dwordx4 v[194:195], off
	s_mov_b32 m0, s26
	v_lshl_add_u64 v[194:195], s[14:15], 0, v[134:135]
	global_load_lds_dwordx4 v[194:195], off
	s_waitcnt lgkmcnt(8)
	s_barrier
	s_waitcnt lgkmcnt(0)
	s_waitcnt lgkmcnt(0)
	v_mfma_f32_16x16x32_f16 v[122:125], v[146:149], v[162:165], v[122:125]
	v_mfma_f32_16x16x32_f16 v[126:129], v[154:157], v[162:165], v[126:129]
	v_mfma_f32_16x16x32_f16 v[114:117], v[146:149], v[170:173], v[114:117]
	v_mfma_f32_16x16x32_f16 v[118:121], v[154:157], v[170:173], v[118:121]
	v_mfma_f32_16x16x32_f16 v[106:109], v[146:149], v[178:181], v[106:109]
	v_mfma_f32_16x16x32_f16 v[110:113], v[154:157], v[178:181], v[110:113]
	v_mfma_f32_16x16x32_f16 v[98:101], v[146:149], v[186:189], v[98:101]
	v_mfma_f32_16x16x32_f16 v[102:105], v[154:157], v[186:189], v[102:105]
	v_mfma_f32_16x16x32_f16 v[122:125], v[150:153], v[166:169], v[122:125]
	v_mfma_f32_16x16x32_f16 v[126:129], v[158:161], v[166:169], v[126:129]
	v_mfma_f32_16x16x32_f16 v[114:117], v[150:153], v[174:177], v[114:117]
	v_mfma_f32_16x16x32_f16 v[118:121], v[158:161], v[174:177], v[118:121]
	v_mfma_f32_16x16x32_f16 v[106:109], v[150:153], v[182:185], v[106:109]
	v_mfma_f32_16x16x32_f16 v[110:113], v[158:161], v[182:185], v[110:113]
	v_mfma_f32_16x16x32_f16 v[98:101], v[150:153], v[190:193], v[98:101]
	v_mfma_f32_16x16x32_f16 v[102:105], v[158:161], v[190:193], v[102:105]
	s_barrier
	s_mov_b32 m0, s29
	v_lshl_add_u64 v[210:211], v[210:211], 0, s[86:87]
	ds_read_b128 v[194:197], v221
	ds_read_b128 v[198:201], v221 offset:1024
	ds_read_b128 v[202:205], v221 offset:2048
	ds_read_b128 v[206:209], v221 offset:3072
	global_load_lds_dwordx4 v[210:211], off
	s_mov_b32 m0, s30
	v_lshl_add_u64 v[210:211], v[212:213], 0, s[86:87]
	global_load_lds_dwordx4 v[210:211], off
	s_barrier
; #define G_STAGE(bufoff, gbase, v0, v1) do { \
;     __builtin_amdgcn_global_load_lds((const unsigned*)((const char*)(gbase) + (v0)), (LAS unsigned*)(lds + (bufoff) + ldsw), 16, 0, 0); \
;     __builtin_amdgcn_global_load_lds((const unsigned*)((const char*)(gbase) + (v1)), (LAS unsigned*)(lds + (bufoff) + ldsw + 8192), 16, 0, 0); } while (0)
; #define G_LDA(dst, b, h) do { _Pragma("unroll") for (int m = 0; m < 4; ++m) _Pragma("unroll") for (int k = 0; k < 2; ++k) dst[m][k] = *(const LAS h8*)(lds + G_SA(b, h) + aoff + m * 2048 + k * 1024); } while (0)
; #define G_MMA(ai, bj, At, Bt) do { __builtin_amdgcn_s_setprio(1); _Pragma("unroll") for (int m = 0; m < 4; ++m) _Pragma("unroll") for (int n = 0; n < 2; ++n) _Pragma("unroll") for (int k = 0; k < 2; ++k) \
;     acc[ai][bj][m][n] = __builtin_amdgcn_mfma_f32_16x16x32_f16(Bt[n][k], At[m][k], acc[ai][bj][m][n], 0, 0, 0); __builtin_amdgcn_s_setprio(0); } while (0)
; #define G_WAIT_V(n) asm volatile("s_waitcnt vmcnt(" #n ")" ::: "memory")
; #define G_WAIT_L(n) asm volatile("s_waitcnt lgkmcnt(" #n ")" ::: "memory")
; #define G_BAR __builtin_amdgcn_s_barrier()
; #define G_SCHED __builtin_amdgcn_sched_barrier(0)
; template <bool PERM, class Sched, class Epi>
; DI void gemm256(LAS unsigned char* lds, const Sched& S, const Epi& E, int wv_) {
;     ...
;       G_BAR; G_WAIT_L(0); G_MMA(0, 1, At, B1); G_BAR;
;       G_LDA(At, 1, 1); G_STAGE(G_SA(1, 0), a3, cvA0, cvA1);
;       G_BAR; G_WAIT_L(0); G_MMA(1, 0, At, B0); G_BAR; G_SCHED;
;       G_STAGE(G_SB(1, 1), b3 + chB, cvB0, cvB1);
;       G_WAIT_V(6); G_BAR; G_MMA(1, 1, At, B1); G_BAR;
;     }
	s_waitcnt lgkmcnt(0)
	s_waitcnt lgkmcnt(0)
	v_mfma_f32_16x16x32_f16 v[58:61], v[194:197], v[162:165], v[58:61]
	v_mfma_f32_16x16x32_f16 v[62:65], v[202:205], v[162:165], v[62:65]
	v_mfma_f32_16x16x32_f16 v[50:53], v[194:197], v[170:173], v[50:53]
	v_mfma_f32_16x16x32_f16 v[54:57], v[202:205], v[170:173], v[54:57]
	v_mfma_f32_16x16x32_f16 v[42:45], v[194:197], v[178:181], v[42:45]
	v_mfma_f32_16x16x32_f16 v[46:49], v[202:205], v[178:181], v[46:49]
	v_mfma_f32_16x16x32_f16 v[34:37], v[194:197], v[186:189], v[34:37]
	v_mfma_f32_16x16x32_f16 v[38:41], v[202:205], v[186:189], v[38:41]
	v_mfma_f32_16x16x32_f16 v[58:61], v[198:201], v[166:169], v[58:61]
	v_mfma_f32_16x16x32_f16 v[62:65], v[206:209], v[166:169], v[62:65]
	v_mfma_f32_16x16x32_f16 v[50:53], v[198:201], v[174:177], v[50:53]
	v_mfma_f32_16x16x32_f16 v[54:57], v[206:209], v[174:177], v[54:57]
	v_mfma_f32_16x16x32_f16 v[42:45], v[198:201], v[182:185], v[42:45]
	v_mfma_f32_16x16x32_f16 v[46:49], v[206:209], v[182:185], v[46:49]
	v_mfma_f32_16x16x32_f16 v[34:37], v[198:201], v[190:193], v[34:37]
	v_mfma_f32_16x16x32_f16 v[38:41], v[206:209], v[190:193], v[38:41]
	s_mov_b32 m0, s31
	v_lshl_add_u64 v[210:211], v[214:215], 0, s[86:87]
	s_barrier
	ds_read_b128 v[162:165], v142 offset:49152
	ds_read_b128 v[166:169], v142 offset:50176
	ds_read_b128 v[170:173], v142 offset:51200
	ds_read_b128 v[174:177], v142 offset:52224
	ds_read_b128 v[178:181], v142 offset:53248
	ds_read_b128 v[182:185], v142 offset:54272
	ds_read_b128 v[186:189], v142 offset:55296
	ds_read_b128 v[190:193], v142 offset:56320
	global_load_lds_dwordx4 v[210:211], off
	s_mov_b32 m0, s34
	v_lshl_add_u64 v[210:211], v[216:217], 0, s[86:87]
	global_load_lds_dwordx4 v[210:211], off
	s_barrier
	s_waitcnt lgkmcnt(0)
	s_waitcnt lgkmcnt(0)
	v_mfma_f32_16x16x32_f16 v[90:93], v[146:149], v[162:165], v[90:93]
	v_mfma_f32_16x16x32_f16 v[94:97], v[154:157], v[162:165], v[94:97]
	v_mfma_f32_16x16x32_f16 v[82:85], v[146:149], v[170:173], v[82:85]
	v_mfma_f32_16x16x32_f16 v[86:89], v[154:157], v[170:173], v[86:89]
	v_mfma_f32_16x16x32_f16 v[74:77], v[146:149], v[178:181], v[74:77]
	v_mfma_f32_16x16x32_f16 v[78:81], v[154:157], v[178:181], v[78:81]
	v_mfma_f32_16x16x32_f16 v[66:69], v[146:149], v[186:189], v[66:69]
	v_mfma_f32_16x16x32_f16 v[70:73], v[154:157], v[186:189], v[70:73]
	v_mfma_f32_16x16x32_f16 v[90:93], v[150:153], v[166:169], v[90:93]
	v_mfma_f32_16x16x32_f16 v[94:97], v[158:161], v[166:169], v[94:97]
	v_mfma_f32_16x16x32_f16 v[82:85], v[150:153], v[174:177], v[82:85]
	v_mfma_f32_16x16x32_f16 v[86:89], v[158:161], v[174:177], v[86:89]
	v_mfma_f32_16x16x32_f16 v[74:77], v[150:153], v[182:185], v[74:77]
	v_mfma_f32_16x16x32_f16 v[78:81], v[158:161], v[182:185], v[78:81]
	v_mfma_f32_16x16x32_f16 v[66:69], v[150:153], v[190:193], v[66:69]
	v_mfma_f32_16x16x32_f16 v[70:73], v[158:161], v[190:193], v[70:73]
	s_barrier
	s_add_u32 s12, s12, 0x40080
	s_addc_u32 s13, s13, 0
	s_mov_b32 m0, s35
	v_lshl_add_u64 v[146:147], s[12:13], 0, v[132:133]
	global_load_lds_dwordx4 v[146:147], off
	s_mov_b32 m0, s36
	v_lshl_add_u64 v[146:147], s[12:13], 0, v[136:137]
	global_load_lds_dwordx4 v[146:147], off
	s_waitcnt vmcnt(6)
	s_barrier
	v_mfma_f32_16x16x32_f16 v[26:29], v[194:197], v[162:165], v[26:29]
	v_mfma_f32_16x16x32_f16 v[30:33], v[202:205], v[162:165], v[30:33]
	v_mfma_f32_16x16x32_f16 v[18:21], v[194:197], v[170:173], v[18:21]
	v_mfma_f32_16x16x32_f16 v[22:25], v[202:205], v[170:173], v[22:25]
	v_mfma_f32_16x16x32_f16 v[10:13], v[194:197], v[178:181], v[10:13]
	v_mfma_f32_16x16x32_f16 v[14:17], v[202:205], v[178:181], v[14:17]
	v_mfma_f32_16x16x32_f16 v[6:9], v[194:197], v[186:189], v[6:9]
	v_mfma_f32_16x16x32_f16 v[2:5], v[202:205], v[186:189], v[2:5]
	v_mfma_f32_16x16x32_f16 v[26:29], v[198:201], v[166:169], v[26:29]
	v_mfma_f32_16x16x32_f16 v[30:33], v[206:209], v[166:169], v[30:33]
	v_mfma_f32_16x16x32_f16 v[18:21], v[198:201], v[174:177], v[18:21]
	v_mfma_f32_16x16x32_f16 v[22:25], v[206:209], v[174:177], v[22:25]
	v_mfma_f32_16x16x32_f16 v[10:13], v[198:201], v[182:185], v[10:13]
	v_mfma_f32_16x16x32_f16 v[14:17], v[206:209], v[182:185], v[14:17]
	v_mfma_f32_16x16x32_f16 v[6:9], v[198:201], v[190:193], v[6:9]
	v_mfma_f32_16x16x32_f16 v[2:5], v[206:209], v[190:193], v[2:5]
	s_add_u32 s10, s10, 0x100
	s_addc_u32 s11, s11, 0
	s_add_u32 s46, s46, 0x100
	s_addc_u32 s74, s74, 0
	s_cmp_ge_i32 s91, s7
	s_mov_b32 s12, s91
	s_barrier
	s_cbranch_scc0 .LBB0_1503
	v_readlane_b32 s91, v254, 47
	s_movk_i32 s85, 0x800
	s_xor_b64 s[8:9], s[8:9], -1
	s_cmp_lg_u32 s84, 0
	s_cbranch_scc0 .LBB0_1509

; #define G_STAGE(bufoff, gbase, v0, v1) do { \
;     __builtin_amdgcn_global_load_lds((const unsigned*)((const char*)(gbase) + (v0)), (LAS unsigned*)(lds + (bufoff) + ldsw), 16, 0, 0); \
;     __builtin_amdgcn_global_load_lds((const unsigned*)((const char*)(gbase) + (v1)), (LAS unsigned*)(lds + (bufoff) + ldsw + 8192), 16, 0, 0); } while (0)
; #define G_LDA(dst, b, h) do { _Pragma("unroll") for (int m = 0; m < 4; ++m) _Pragma("unroll") for (int k = 0; k < 2; ++k) dst[m][k] = *(const LAS h8*)(lds + G_SA(b, h) + aoff + m * 2048 + k * 1024); } while (0)
; #define G_LDB(dst, b, h) do { _Pragma("unroll") for (int n = 0; n < 2; ++n) _Pragma("unroll") for (int k = 0; k < 2; ++k) dst[n][k] = *(const LAS h8*)(lds + G_SB(b, h) + boff + n * 2048 + k * 1024); } while (0)
; #define G_MMA(ai, bj, At, Bt) do { __builtin_amdgcn_s_setprio(1); _Pragma("unroll") for (int m = 0; m < 4; ++m) _Pragma("unroll") for (int n = 0; n < 2; ++n) _Pragma("unroll") for (int k = 0; k < 2; ++k) \
;     acc[ai][bj][m][n] = __builtin_amdgcn_mfma_f32_16x16x32_f16(Bt[n][k], At[m][k], acc[ai][bj][m][n], 0, 0, 0); __builtin_amdgcn_s_setprio(0); } while (0)
; #define G_WAIT_V(n) asm volatile("s_waitcnt vmcnt(" #n ")" ::: "memory")
; #define G_WAIT_L(n) asm volatile("s_waitcnt lgkmcnt(" #n ")" ::: "memory")
; #define G_BAR __builtin_amdgcn_s_barrier()
; #define G_SCHED __builtin_amdgcn_sched_barrier(0)
; template <bool PERM, class Sched, class Epi>
; DI void gemm256(LAS unsigned char* lds, const Sched& S, const Epi& E, int wv_) {
;     ...
;       const bool last = (t == nt - 2);
;       const char* a1 = cA + (size_t)(t + 1) * kstep;
;       const char* a2 = last ? nA : cA + (size_t)(t + 2) * kstep;
;       const char* b2 = last ? nB : cB + (size_t)(t + 2) * kstep;
;       const char* a3 = a2 + kstep;
;       const char* b3 = b2 + kstep;
;       G_LDB(B0, 0, 0); G_SCHED; G_LDA(At, 0, 0); G_STAGE(G_SA(1, 1), a1 + chA, cvA0, cvA1);
;       G_WAIT_L(8); G_BAR; G_WAIT_L(0); G_MMA(0, 0, At, B0); G_BAR; G_SCHED;
;       G_LDB(B1, 0, 1); G_STAGE(G_SB(0, 0), b2, cvB0, cvB1);
;       G_BAR; G_WAIT_L(0); G_MMA(0, 1, At, B1); G_BAR;
;       G_LDA(At, 0, 1); G_STAGE(G_SA(0, 0), a2, cvA0, cvA1);
;       G_BAR; G_WAIT_L(0); G_MMA(1, 0, At, B0); G_BAR; G_SCHED;
;       G_STAGE(G_SB(0, 1), b2 + chB, cvB0, cvB1);
;       G_WAIT_V(6); G_BAR; G_MMA(1, 1, At, B1); G_BAR;
.LBB0_1718:
	s_add_i32 s74, s12, 2
	ds_read_b128 v[144:147], v216
	ds_read_b128 v[148:151], v216 offset:1024
	ds_read_b128 v[152:155], v216 offset:2048
	ds_read_b128 v[156:159], v216 offset:3072
	s_add_u32 s13, s10, 0xfffea080
	s_addc_u32 s14, s11, -1
	s_cmp_eq_u32 vcc_lo, s12
	s_cselect_b32 s12, s93, s75
	s_cselect_b32 s15, s84, s14
	s_cselect_b32 s14, s85, s13
	s_cselect_b32 s13, s90, s46
	v_lshl_add_u64 v[192:193], s[10:11], 0, v[138:139]
	s_add_i32 m0, s19, 0xc000
	ds_read_b128 v[160:163], v1
	ds_read_b128 v[164:167], v1 offset:1024
	ds_read_b128 v[168:171], v1 offset:2048
	ds_read_b128 v[172:175], v1 offset:3072
	ds_read_b128 v[176:179], v1 offset:4096
	ds_read_b128 v[180:183], v1 offset:5120
	ds_read_b128 v[184:187], v1 offset:6144
	ds_read_b128 v[188:191], v1 offset:7168
	global_load_lds_dwordx4 v[192:193], off
	s_add_i32 m0, s19, 0xe000
	v_lshl_add_u64 v[192:193], s[10:11], 0, v[140:141]
	global_load_lds_dwordx4 v[192:193], off
	s_waitcnt lgkmcnt(8)
	s_barrier
	s_waitcnt lgkmcnt(0)
	s_waitcnt lgkmcnt(0)
	v_mfma_f32_16x16x32_f16 v[122:125], v[144:147], v[160:163], v[122:125]
	v_mfma_f32_16x16x32_f16 v[126:129], v[152:155], v[160:163], v[126:129]
	v_mfma_f32_16x16x32_f16 v[114:117], v[144:147], v[168:171], v[114:117]
	v_mfma_f32_16x16x32_f16 v[118:121], v[152:155], v[168:171], v[118:121]
	v_mfma_f32_16x16x32_f16 v[106:109], v[144:147], v[176:179], v[106:109]
	v_mfma_f32_16x16x32_f16 v[110:113], v[152:155], v[176:179], v[110:113]
	v_mfma_f32_16x16x32_f16 v[98:101], v[144:147], v[184:187], v[98:101]
	v_mfma_f32_16x16x32_f16 v[102:105], v[152:155], v[184:187], v[102:105]
	v_mfma_f32_16x16x32_f16 v[122:125], v[148:151], v[164:167], v[122:125]
	v_mfma_f32_16x16x32_f16 v[126:129], v[156:159], v[164:167], v[126:129]
	v_mfma_f32_16x16x32_f16 v[114:117], v[148:151], v[172:175], v[114:117]
	v_mfma_f32_16x16x32_f16 v[118:121], v[156:159], v[172:175], v[118:121]
	v_mfma_f32_16x16x32_f16 v[106:109], v[148:151], v[180:183], v[106:109]
	v_mfma_f32_16x16x32_f16 v[110:113], v[156:159], v[180:183], v[110:113]
	v_mfma_f32_16x16x32_f16 v[98:101], v[148:151], v[188:191], v[98:101]
	v_mfma_f32_16x16x32_f16 v[102:105], v[156:159], v[188:191], v[102:105]
	s_barrier
	s_mov_b32 m0, s20
	v_lshl_add_u64 v[208:209], s[12:13], 0, v[132:133]
	ds_read_b128 v[192:195], v217
	ds_read_b128 v[196:199], v217 offset:1024
	ds_read_b128 v[200:203], v217 offset:2048
	ds_read_b128 v[204:207], v217 offset:3072
	global_load_lds_dwordx4 v[208:209], off
	s_mov_b32 m0, s21
	v_lshl_add_u64 v[210:211], s[12:13], 0, v[136:137]
	global_load_lds_dwordx4 v[210:211], off
	s_barrier
	s_waitcnt lgkmcnt(0)
	s_waitcnt lgkmcnt(0)
	v_mfma_f32_16x16x32_f16 v[58:61], v[192:195], v[160:163], v[58:61]
	v_mfma_f32_16x16x32_f16 v[62:65], v[200:203], v[160:163], v[62:65]
	v_mfma_f32_16x16x32_f16 v[50:53], v[192:195], v[168:171], v[50:53]
	v_mfma_f32_16x16x32_f16 v[54:57], v[200:203], v[168:171], v[54:57]
	v_mfma_f32_16x16x32_f16 v[42:45], v[192:195], v[176:179], v[42:45]
	v_mfma_f32_16x16x32_f16 v[46:49], v[200:203], v[176:179], v[46:49]
	v_mfma_f32_16x16x32_f16 v[34:37], v[192:195], v[184:187], v[34:37]
	v_mfma_f32_16x16x32_f16 v[38:41], v[200:203], v[184:187], v[38:41]
	v_mfma_f32_16x16x32_f16 v[58:61], v[196:199], v[164:167], v[58:61]
	v_mfma_f32_16x16x32_f16 v[62:65], v[204:207], v[164:167], v[62:65]
	v_mfma_f32_16x16x32_f16 v[50:53], v[196:199], v[172:175], v[50:53]
	v_mfma_f32_16x16x32_f16 v[54:57], v[204:207], v[172:175], v[54:57]
	v_mfma_f32_16x16x32_f16 v[42:45], v[196:199], v[180:183], v[42:45]
	v_mfma_f32_16x16x32_f16 v[46:49], v[204:207], v[180:183], v[46:49]
	v_mfma_f32_16x16x32_f16 v[34:37], v[196:199], v[188:191], v[34:37]
	v_mfma_f32_16x16x32_f16 v[38:41], v[204:207], v[188:191], v[38:41]
	s_mov_b32 m0, s19
	v_lshl_add_u64 v[212:213], s[14:15], 0, v[130:131]
	s_barrier
	ds_read_b128 v[160:163], v1 offset:16384
	ds_read_b128 v[164:167], v1 offset:17408
	ds_read_b128 v[168:171], v1 offset:18432
	ds_read_b128 v[172:175], v1 offset:19456
	ds_read_b128 v[176:179], v1 offset:20480
	ds_read_b128 v[180:183], v1 offset:21504
	ds_read_b128 v[184:187], v1 offset:22528
	ds_read_b128 v[188:191], v1 offset:23552
	global_load_lds_dwordx4 v[212:213], off
	s_mov_b32 m0, s22
	v_lshl_add_u64 v[214:215], s[14:15], 0, v[134:135]
	global_load_lds_dwordx4 v[214:215], off
	s_barrier
	s_waitcnt lgkmcnt(0)
	s_waitcnt lgkmcnt(0)
	v_mfma_f32_16x16x32_f16 v[90:93], v[144:147], v[160:163], v[90:93]
	v_mfma_f32_16x16x32_f16 v[94:97], v[152:155], v[160:163], v[94:97]
	v_mfma_f32_16x16x32_f16 v[82:85], v[144:147], v[168:171], v[82:85]
	v_mfma_f32_16x16x32_f16 v[86:89], v[152:155], v[168:171], v[86:89]
	v_mfma_f32_16x16x32_f16 v[74:77], v[144:147], v[176:179], v[74:77]
	v_mfma_f32_16x16x32_f16 v[78:81], v[152:155], v[176:179], v[78:81]
	v_mfma_f32_16x16x32_f16 v[66:69], v[144:147], v[184:187], v[66:69]
	v_mfma_f32_16x16x32_f16 v[70:73], v[152:155], v[184:187], v[70:73]
	v_mfma_f32_16x16x32_f16 v[90:93], v[148:151], v[164:167], v[90:93]
	v_mfma_f32_16x16x32_f16 v[94:97], v[156:159], v[164:167], v[94:97]
	v_mfma_f32_16x16x32_f16 v[82:85], v[148:151], v[172:175], v[82:85]
	v_mfma_f32_16x16x32_f16 v[86:89], v[156:159], v[172:175], v[86:89]
	v_mfma_f32_16x16x32_f16 v[74:77], v[148:151], v[180:183], v[74:77]
	v_mfma_f32_16x16x32_f16 v[78:81], v[156:159], v[180:183], v[78:81]
	v_mfma_f32_16x16x32_f16 v[66:69], v[148:151], v[188:191], v[66:69]
	v_mfma_f32_16x16x32_f16 v[70:73], v[156:159], v[188:191], v[70:73]
	s_barrier
	s_add_u32 s68, s12, 0x10000
	s_addc_u32 s69, s13, 0
	s_mov_b32 m0, s23
	v_lshl_add_u64 v[144:145], s[68:69], 0, v[132:133]
	global_load_lds_dwordx4 v[144:145], off
	s_mov_b32 m0, s24
	v_lshl_add_u64 v[144:145], s[68:69], 0, v[136:137]
	global_load_lds_dwordx4 v[144:145], off
	s_waitcnt vmcnt(6)
	s_barrier
; #define G_STAGE(bufoff, gbase, v0, v1) do { \
;     __builtin_amdgcn_global_load_lds((const unsigned*)((const char*)(gbase) + (v0)), (LAS unsigned*)(lds + (bufoff) + ldsw), 16, 0, 0); \
;     __builtin_amdgcn_global_load_lds((const unsigned*)((const char*)(gbase) + (v1)), (LAS unsigned*)(lds + (bufoff) + ldsw + 8192), 16, 0, 0); } while (0)
; #define G_LDA(dst, b, h) do { _Pragma("unroll") for (int m = 0; m < 4; ++m) _Pragma("unroll") for (int k = 0; k < 2; ++k) dst[m][k] = *(const LAS h8*)(lds + G_SA(b, h) + aoff + m * 2048 + k * 1024); } while (0)
; #define G_LDB(dst, b, h) do { _Pragma("unroll") for (int n = 0; n < 2; ++n) _Pragma("unroll") for (int k = 0; k < 2; ++k) dst[n][k] = *(const LAS h8*)(lds + G_SB(b, h) + boff + n * 2048 + k * 1024); } while (0)
; #define G_MMA(ai, bj, At, Bt) do { __builtin_amdgcn_s_setprio(1); _Pragma("unroll") for (int m = 0; m < 4; ++m) _Pragma("unroll") for (int n = 0; n < 2; ++n) _Pragma("unroll") for (int k = 0; k < 2; ++k) \
;     acc[ai][bj][m][n] = __builtin_amdgcn_mfma_f32_16x16x32_f16(Bt[n][k], At[m][k], acc[ai][bj][m][n], 0, 0, 0); __builtin_amdgcn_s_setprio(0); } while (0)
; #define G_WAIT_V(n) asm volatile("s_waitcnt vmcnt(" #n ")" ::: "memory")
; #define G_WAIT_L(n) asm volatile("s_waitcnt lgkmcnt(" #n ")" ::: "memory")
; #define G_BAR __builtin_amdgcn_s_barrier()
; #define G_SCHED __builtin_amdgcn_sched_barrier(0)
; template <bool PERM, class Sched, class Epi>
; DI void gemm256(LAS unsigned char* lds, const Sched& S, const Epi& E, int wv_) {
;     ...
;       G_WAIT_V(6); G_BAR; G_MMA(1, 1, At, B1); G_BAR;
;       G_LDB(B0, 1, 0); G_SCHED; G_LDA(At, 1, 0); G_STAGE(G_SA(0, 1), a2 + chA, cvA0, cvA1);
;       G_WAIT_L(8); G_BAR; G_WAIT_L(0); G_MMA(0, 0, At, B0); G_BAR; G_SCHED;
;       G_LDB(B1, 1, 1); G_STAGE(G_SB(1, 0), b3, cvB0, cvB1);
	v_mfma_f32_16x16x32_f16 v[26:29], v[192:195], v[160:163], v[26:29]
	v_mfma_f32_16x16x32_f16 v[30:33], v[200:203], v[160:163], v[30:33]
	v_mfma_f32_16x16x32_f16 v[18:21], v[192:195], v[168:171], v[18:21]
	v_mfma_f32_16x16x32_f16 v[22:25], v[200:203], v[168:171], v[22:25]
	v_mfma_f32_16x16x32_f16 v[10:13], v[192:195], v[176:179], v[10:13]
	v_mfma_f32_16x16x32_f16 v[14:17], v[200:203], v[176:179], v[14:17]
	v_mfma_f32_16x16x32_f16 v[6:9], v[192:195], v[184:187], v[6:9]
	v_mfma_f32_16x16x32_f16 v[2:5], v[200:203], v[184:187], v[2:5]
	v_mfma_f32_16x16x32_f16 v[26:29], v[196:199], v[164:167], v[26:29]
	v_mfma_f32_16x16x32_f16 v[30:33], v[204:207], v[164:167], v[30:33]
	v_mfma_f32_16x16x32_f16 v[18:21], v[196:199], v[172:175], v[18:21]
	v_mfma_f32_16x16x32_f16 v[22:25], v[204:207], v[172:175], v[22:25]
	v_mfma_f32_16x16x32_f16 v[10:13], v[196:199], v[180:183], v[10:13]
	v_mfma_f32_16x16x32_f16 v[14:17], v[204:207], v[180:183], v[14:17]
	v_mfma_f32_16x16x32_f16 v[6:9], v[196:199], v[188:191], v[6:9]
	v_mfma_f32_16x16x32_f16 v[2:5], v[204:207], v[188:191], v[2:5]
	s_barrier
	ds_read_b128 v[144:147], v218
	ds_read_b128 v[148:151], v218 offset:1024
	ds_read_b128 v[152:155], v218 offset:2048
	ds_read_b128 v[156:159], v218 offset:3072
	s_add_u32 s14, s14, 0x16000
	s_addc_u32 s15, s15, 0
	s_mov_b32 m0, s25
	v_lshl_add_u64 v[192:193], s[14:15], 0, v[130:131]
	ds_read_b128 v[160:163], v1 offset:32768
	ds_read_b128 v[164:167], v1 offset:33792
	ds_read_b128 v[168:171], v1 offset:34816
	ds_read_b128 v[172:175], v1 offset:35840
	ds_read_b128 v[176:179], v1 offset:36864
	ds_read_b128 v[180:183], v1 offset:37888
	ds_read_b128 v[184:187], v1 offset:38912
	ds_read_b128 v[188:191], v1 offset:39936
	global_load_lds_dwordx4 v[192:193], off
	s_mov_b32 m0, s26
	v_lshl_add_u64 v[192:193], s[14:15], 0, v[134:135]
	global_load_lds_dwordx4 v[192:193], off
	s_waitcnt lgkmcnt(8)
	s_barrier
	s_waitcnt lgkmcnt(0)
	s_waitcnt lgkmcnt(0)
	v_mfma_f32_16x16x32_f16 v[122:125], v[144:147], v[160:163], v[122:125]
	v_mfma_f32_16x16x32_f16 v[126:129], v[152:155], v[160:163], v[126:129]
	v_mfma_f32_16x16x32_f16 v[114:117], v[144:147], v[168:171], v[114:117]
	v_mfma_f32_16x16x32_f16 v[118:121], v[152:155], v[168:171], v[118:121]
	v_mfma_f32_16x16x32_f16 v[106:109], v[144:147], v[176:179], v[106:109]
	v_mfma_f32_16x16x32_f16 v[110:113], v[152:155], v[176:179], v[110:113]
	v_mfma_f32_16x16x32_f16 v[98:101], v[144:147], v[184:187], v[98:101]
	v_mfma_f32_16x16x32_f16 v[102:105], v[152:155], v[184:187], v[102:105]
	v_mfma_f32_16x16x32_f16 v[122:125], v[148:151], v[164:167], v[122:125]
	v_mfma_f32_16x16x32_f16 v[126:129], v[156:159], v[164:167], v[126:129]
	v_mfma_f32_16x16x32_f16 v[114:117], v[148:151], v[172:175], v[114:117]
	v_mfma_f32_16x16x32_f16 v[118:121], v[156:159], v[172:175], v[118:121]
	v_mfma_f32_16x16x32_f16 v[106:109], v[148:151], v[180:183], v[106:109]
	v_mfma_f32_16x16x32_f16 v[110:113], v[156:159], v[180:183], v[110:113]
	v_mfma_f32_16x16x32_f16 v[98:101], v[148:151], v[188:191], v[98:101]
	v_mfma_f32_16x16x32_f16 v[102:105], v[156:159], v[188:191], v[102:105]
	s_barrier
	s_mov_b32 m0, s29
	v_lshl_add_u64 v[208:209], v[208:209], 0, s[86:87]
	ds_read_b128 v[192:195], v219
	ds_read_b128 v[196:199], v219 offset:1024
	ds_read_b128 v[200:203], v219 offset:2048
	ds_read_b128 v[204:207], v219 offset:3072
	global_load_lds_dwordx4 v[208:209], off
	s_mov_b32 m0, s30
	v_lshl_add_u64 v[208:209], v[210:211], 0, s[86:87]
	global_load_lds_dwordx4 v[208:209], off
	s_barrier
; #define G_STAGE(bufoff, gbase, v0, v1) do { \
;     __builtin_amdgcn_global_load_lds((const unsigned*)((const char*)(gbase) + (v0)), (LAS unsigned*)(lds + (bufoff) + ldsw), 16, 0, 0); \
;     __builtin_amdgcn_global_load_lds((const unsigned*)((const char*)(gbase) + (v1)), (LAS unsigned*)(lds + (bufoff) + ldsw + 8192), 16, 0, 0); } while (0)
; #define G_LDA(dst, b, h) do { _Pragma("unroll") for (int m = 0; m < 4; ++m) _Pragma("unroll") for (int k = 0; k < 2; ++k) dst[m][k] = *(const LAS h8*)(lds + G_SA(b, h) + aoff + m * 2048 + k * 1024); } while (0)
; #define G_MMA(ai, bj, At, Bt) do { __builtin_amdgcn_s_setprio(1); _Pragma("unroll") for (int m = 0; m < 4; ++m) _Pragma("unroll") for (int n = 0; n < 2; ++n) _Pragma("unroll") for (int k = 0; k < 2; ++k) \
;     acc[ai][bj][m][n] = __builtin_amdgcn_mfma_f32_16x16x32_f16(Bt[n][k], At[m][k], acc[ai][bj][m][n], 0, 0, 0); __builtin_amdgcn_s_setprio(0); } while (0)
; #define G_WAIT_V(n) asm volatile("s_waitcnt vmcnt(" #n ")" ::: "memory")
; #define G_WAIT_L(n) asm volatile("s_waitcnt lgkmcnt(" #n ")" ::: "memory")
; #define G_BAR __builtin_amdgcn_s_barrier()
; #define G_SCHED __builtin_amdgcn_sched_barrier(0)
; template <bool PERM, class Sched, class Epi>
; DI void gemm256(LAS unsigned char* lds, const Sched& S, const Epi& E, int wv_) {
;     ...
;       G_BAR; G_WAIT_L(0); G_MMA(0, 1, At, B1); G_BAR;
;       G_LDA(At, 1, 1); G_STAGE(G_SA(1, 0), a3, cvA0, cvA1);
;       G_BAR; G_WAIT_L(0); G_MMA(1, 0, At, B0); G_BAR; G_SCHED;
;       G_STAGE(G_SB(1, 1), b3 + chB, cvB0, cvB1);
;       G_WAIT_V(6); G_BAR; G_MMA(1, 1, At, B1); G_BAR;
;     }
	s_waitcnt lgkmcnt(0)
	s_waitcnt lgkmcnt(0)
	v_mfma_f32_16x16x32_f16 v[58:61], v[192:195], v[160:163], v[58:61]
	v_mfma_f32_16x16x32_f16 v[62:65], v[200:203], v[160:163], v[62:65]
	v_mfma_f32_16x16x32_f16 v[50:53], v[192:195], v[168:171], v[50:53]
	v_mfma_f32_16x16x32_f16 v[54:57], v[200:203], v[168:171], v[54:57]
	v_mfma_f32_16x16x32_f16 v[42:45], v[192:195], v[176:179], v[42:45]
	v_mfma_f32_16x16x32_f16 v[46:49], v[200:203], v[176:179], v[46:49]
	v_mfma_f32_16x16x32_f16 v[34:37], v[192:195], v[184:187], v[34:37]
	v_mfma_f32_16x16x32_f16 v[38:41], v[200:203], v[184:187], v[38:41]
	v_mfma_f32_16x16x32_f16 v[58:61], v[196:199], v[164:167], v[58:61]
	v_mfma_f32_16x16x32_f16 v[62:65], v[204:207], v[164:167], v[62:65]
	v_mfma_f32_16x16x32_f16 v[50:53], v[196:199], v[172:175], v[50:53]
	v_mfma_f32_16x16x32_f16 v[54:57], v[204:207], v[172:175], v[54:57]
	v_mfma_f32_16x16x32_f16 v[42:45], v[196:199], v[180:183], v[42:45]
	v_mfma_f32_16x16x32_f16 v[46:49], v[204:207], v[180:183], v[46:49]
	v_mfma_f32_16x16x32_f16 v[34:37], v[196:199], v[188:191], v[34:37]
	v_mfma_f32_16x16x32_f16 v[38:41], v[204:207], v[188:191], v[38:41]
	s_mov_b32 m0, s31
	v_lshl_add_u64 v[208:209], v[212:213], 0, s[86:87]
	s_barrier
	ds_read_b128 v[160:163], v1 offset:49152
	ds_read_b128 v[164:167], v1 offset:50176
	ds_read_b128 v[168:171], v1 offset:51200
	ds_read_b128 v[172:175], v1 offset:52224
	ds_read_b128 v[176:179], v1 offset:53248
	ds_read_b128 v[180:183], v1 offset:54272
	ds_read_b128 v[184:187], v1 offset:55296
	ds_read_b128 v[188:191], v1 offset:56320
	global_load_lds_dwordx4 v[208:209], off
	s_mov_b32 m0, s34
	v_lshl_add_u64 v[208:209], v[214:215], 0, s[86:87]
	global_load_lds_dwordx4 v[208:209], off
	s_barrier
	s_waitcnt lgkmcnt(0)
	s_waitcnt lgkmcnt(0)
	v_mfma_f32_16x16x32_f16 v[90:93], v[144:147], v[160:163], v[90:93]
	v_mfma_f32_16x16x32_f16 v[94:97], v[152:155], v[160:163], v[94:97]
	v_mfma_f32_16x16x32_f16 v[82:85], v[144:147], v[168:171], v[82:85]
	v_mfma_f32_16x16x32_f16 v[86:89], v[152:155], v[168:171], v[86:89]
	v_mfma_f32_16x16x32_f16 v[74:77], v[144:147], v[176:179], v[74:77]
	v_mfma_f32_16x16x32_f16 v[78:81], v[152:155], v[176:179], v[78:81]
	v_mfma_f32_16x16x32_f16 v[66:69], v[144:147], v[184:187], v[66:69]
	v_mfma_f32_16x16x32_f16 v[70:73], v[152:155], v[184:187], v[70:73]
	v_mfma_f32_16x16x32_f16 v[90:93], v[148:151], v[164:167], v[90:93]
	v_mfma_f32_16x16x32_f16 v[94:97], v[156:159], v[164:167], v[94:97]
	v_mfma_f32_16x16x32_f16 v[82:85], v[148:151], v[172:175], v[82:85]
	v_mfma_f32_16x16x32_f16 v[86:89], v[156:159], v[172:175], v[86:89]
	v_mfma_f32_16x16x32_f16 v[74:77], v[148:151], v[180:183], v[74:77]
	v_mfma_f32_16x16x32_f16 v[78:81], v[156:159], v[180:183], v[78:81]
	v_mfma_f32_16x16x32_f16 v[66:69], v[148:151], v[188:191], v[66:69]
	v_mfma_f32_16x16x32_f16 v[70:73], v[156:159], v[188:191], v[70:73]
	s_barrier
	s_add_u32 s12, s12, 0x10080
	s_addc_u32 s13, s13, 0
	s_mov_b32 m0, s35
	v_lshl_add_u64 v[144:145], s[12:13], 0, v[132:133]
	global_load_lds_dwordx4 v[144:145], off
	s_mov_b32 m0, s37
	v_lshl_add_u64 v[144:145], s[12:13], 0, v[136:137]
	global_load_lds_dwordx4 v[144:145], off
	s_waitcnt vmcnt(6)
	s_barrier
	v_mfma_f32_16x16x32_f16 v[26:29], v[192:195], v[160:163], v[26:29]
	v_mfma_f32_16x16x32_f16 v[30:33], v[200:203], v[160:163], v[30:33]
	v_mfma_f32_16x16x32_f16 v[18:21], v[192:195], v[168:171], v[18:21]
	v_mfma_f32_16x16x32_f16 v[22:25], v[200:203], v[168:171], v[22:25]
	v_mfma_f32_16x16x32_f16 v[10:13], v[192:195], v[176:179], v[10:13]
	v_mfma_f32_16x16x32_f16 v[14:17], v[200:203], v[176:179], v[14:17]
	v_mfma_f32_16x16x32_f16 v[6:9], v[192:195], v[184:187], v[6:9]
	v_mfma_f32_16x16x32_f16 v[2:5], v[200:203], v[184:187], v[2:5]
	v_mfma_f32_16x16x32_f16 v[26:29], v[196:199], v[164:167], v[26:29]
	v_mfma_f32_16x16x32_f16 v[30:33], v[204:207], v[164:167], v[30:33]
	v_mfma_f32_16x16x32_f16 v[18:21], v[196:199], v[172:175], v[18:21]
	v_mfma_f32_16x16x32_f16 v[22:25], v[204:207], v[172:175], v[22:25]
	v_mfma_f32_16x16x32_f16 v[10:13], v[196:199], v[180:183], v[10:13]
	v_mfma_f32_16x16x32_f16 v[14:17], v[204:207], v[180:183], v[14:17]
	v_mfma_f32_16x16x32_f16 v[6:9], v[196:199], v[188:191], v[6:9]
	v_mfma_f32_16x16x32_f16 v[2:5], v[204:207], v[188:191], v[2:5]
	s_add_u32 s10, s10, 0x100
	s_addc_u32 s11, s11, 0
	s_add_u32 s75, s75, 0x100
	s_addc_u32 s46, s46, 0
	s_cmp_ge_i32 s74, s79
	s_mov_b32 s12, s74
	s_barrier
	s_cbranch_scc0 .LBB0_1718
	s_mov_b32 s93, 0x23fff
	s_movk_i32 s85, 0x800
	s_branch .LBB0_1721

; #define G_STAGE(bufoff, gbase, v0, v1) do { \
;     __builtin_amdgcn_global_load_lds((const unsigned*)((const char*)(gbase) + (v0)), (LAS unsigned*)(lds + (bufoff) + ldsw), 16, 0, 0); \
;     __builtin_amdgcn_global_load_lds((const unsigned*)((const char*)(gbase) + (v1)), (LAS unsigned*)(lds + (bufoff) + ldsw + 8192), 16, 0, 0); } while (0)
; #define G_LDA(dst, b, h) do { _Pragma("unroll") for (int m = 0; m < 4; ++m) _Pragma("unroll") for (int k = 0; k < 2; ++k) dst[m][k] = *(const LAS h8*)(lds + G_SA(b, h) + aoff + m * 2048 + k * 1024); } while (0)
; #define G_LDB(dst, b, h) do { _Pragma("unroll") for (int n = 0; n < 2; ++n) _Pragma("unroll") for (int k = 0; k < 2; ++k) dst[n][k] = *(const LAS h8*)(lds + G_SB(b, h) + boff + n * 2048 + k * 1024); } while (0)
; #define G_MMA(ai, bj, At, Bt) do { __builtin_amdgcn_s_setprio(1); _Pragma("unroll") for (int m = 0; m < 4; ++m) _Pragma("unroll") for (int n = 0; n < 2; ++n) _Pragma("unroll") for (int k = 0; k < 2; ++k) \
;     acc[ai][bj][m][n] = __builtin_amdgcn_mfma_f32_16x16x32_f16(Bt[n][k], At[m][k], acc[ai][bj][m][n], 0, 0, 0); __builtin_amdgcn_s_setprio(0); } while (0)
; #define G_WAIT_L(n) asm volatile("s_waitcnt lgkmcnt(" #n ")" ::: "memory")
; #define G_BAR __builtin_amdgcn_s_barrier()
; #define G_SCHED __builtin_amdgcn_sched_barrier(0)
; template <bool PERM, class Sched, class Epi>
; DI void gemm256(LAS unsigned char* lds, const Sched& S, const Epi& E, int wv_) {
;     ...
;       const bool last = (t == nt - 2);
;       const char* a1 = cA + (size_t)(t + 1) * kstep;
;       const char* a2 = last ? nA : cA + (size_t)(t + 2) * kstep;
;       const char* b2 = last ? nB : cB + (size_t)(t + 2) * kstep;
;       const char* a3 = a2 + kstep;
;       const char* b3 = b2 + kstep;
;       G_LDB(B0, 0, 0); G_SCHED; G_LDA(At, 0, 0); G_STAGE(G_SA(1, 1), a1 + chA, cvA0, cvA1);
;       G_WAIT_L(8); G_BAR; G_WAIT_L(0); G_MMA(0, 0, At, B0); G_BAR; G_SCHED;
;       G_LDB(B1, 0, 1); G_STAGE(G_SB(0, 0), b2, cvB0, cvB1);
;       G_BAR; G_WAIT_L(0); G_MMA(0, 1, At, B1); G_BAR;
;       G_LDA(At, 0, 1); G_STAGE(G_SA(0, 0), a2, cvA0, cvA1);
;       G_BAR; G_WAIT_L(0); G_MMA(1, 0, At, B0); G_BAR; G_SCHED;
.LBB0_1748:
	s_add_i32 s60, s12, 2
	s_add_u32 s10, s8, 0x100
	s_addc_u32 s11, s9, 0
	s_add_u32 s13, s58, s8
	ds_read_b128 v[144:147], v216
	ds_read_b128 v[148:151], v216 offset:1024
	ds_read_b128 v[152:155], v216 offset:2048
	ds_read_b128 v[156:159], v216 offset:3072
	s_addc_u32 s14, s59, s9
	s_cmp_eq_u32 s56, s12
	s_cselect_b32 s40, 0, s10
	s_cselect_b32 s15, 0, s11
	s_cselect_b32 s12, s4, s13
	s_cselect_b32 s13, s5, s14
	s_add_u32 s14, s2, s40
	s_addc_u32 s15, s3, s15
	v_lshl_add_u64 v[192:193], v[138:139], 0, s[8:9]
	s_add_i32 m0, s17, 0xc000
	ds_read_b128 v[160:163], v1
	ds_read_b128 v[164:167], v1 offset:1024
	ds_read_b128 v[168:171], v1 offset:2048
	ds_read_b128 v[172:175], v1 offset:3072
	ds_read_b128 v[176:179], v1 offset:4096
	ds_read_b128 v[180:183], v1 offset:5120
	ds_read_b128 v[184:187], v1 offset:6144
	ds_read_b128 v[188:191], v1 offset:7168
	global_load_lds_dwordx4 v[192:193], off
	s_add_i32 m0, s17, 0xe000
	v_lshl_add_u64 v[192:193], v[140:141], 0, s[8:9]
	global_load_lds_dwordx4 v[192:193], off
	s_waitcnt lgkmcnt(8)
	s_barrier
	s_waitcnt lgkmcnt(0)
	s_waitcnt lgkmcnt(0)
	v_mfma_f32_16x16x32_f16 v[122:125], v[144:147], v[160:163], v[122:125]
	v_mfma_f32_16x16x32_f16 v[126:129], v[152:155], v[160:163], v[126:129]
	v_mfma_f32_16x16x32_f16 v[106:109], v[144:147], v[168:171], v[106:109]
	v_mfma_f32_16x16x32_f16 v[110:113], v[152:155], v[168:171], v[110:113]
	v_mfma_f32_16x16x32_f16 v[90:93], v[144:147], v[176:179], v[90:93]
	v_mfma_f32_16x16x32_f16 v[94:97], v[152:155], v[176:179], v[94:97]
	v_mfma_f32_16x16x32_f16 v[74:77], v[144:147], v[184:187], v[74:77]
	v_mfma_f32_16x16x32_f16 v[78:81], v[152:155], v[184:187], v[78:81]
	v_mfma_f32_16x16x32_f16 v[122:125], v[148:151], v[164:167], v[122:125]
	v_mfma_f32_16x16x32_f16 v[126:129], v[156:159], v[164:167], v[126:129]
	v_mfma_f32_16x16x32_f16 v[106:109], v[148:151], v[172:175], v[106:109]
	v_mfma_f32_16x16x32_f16 v[110:113], v[156:159], v[172:175], v[110:113]
	v_mfma_f32_16x16x32_f16 v[90:93], v[148:151], v[180:183], v[90:93]
	v_mfma_f32_16x16x32_f16 v[94:97], v[156:159], v[180:183], v[94:97]
	v_mfma_f32_16x16x32_f16 v[74:77], v[148:151], v[188:191], v[74:77]
	v_mfma_f32_16x16x32_f16 v[78:81], v[156:159], v[188:191], v[78:81]
	s_barrier
	s_mov_b32 m0, s18
	v_lshl_add_u64 v[208:209], s[12:13], 0, v[134:135]
	ds_read_b128 v[192:195], v217
	ds_read_b128 v[196:199], v217 offset:1024
	ds_read_b128 v[200:203], v217 offset:2048
	ds_read_b128 v[204:207], v217 offset:3072
	global_load_lds_dwordx4 v[208:209], off
	s_mov_b32 m0, s19
	v_lshl_add_u64 v[210:211], s[12:13], 0, v[130:131]
	global_load_lds_dwordx4 v[210:211], off
	s_barrier
	s_waitcnt lgkmcnt(0)
	s_waitcnt lgkmcnt(0)
	v_mfma_f32_16x16x32_f16 v[114:117], v[192:195], v[160:163], v[114:117]
	v_mfma_f32_16x16x32_f16 v[118:121], v[200:203], v[160:163], v[118:121]
	v_mfma_f32_16x16x32_f16 v[98:101], v[192:195], v[168:171], v[98:101]
	v_mfma_f32_16x16x32_f16 v[102:105], v[200:203], v[168:171], v[102:105]
	v_mfma_f32_16x16x32_f16 v[82:85], v[192:195], v[176:179], v[82:85]
	v_mfma_f32_16x16x32_f16 v[86:89], v[200:203], v[176:179], v[86:89]
	v_mfma_f32_16x16x32_f16 v[66:69], v[192:195], v[184:187], v[66:69]
	v_mfma_f32_16x16x32_f16 v[70:73], v[200:203], v[184:187], v[70:73]
	v_mfma_f32_16x16x32_f16 v[114:117], v[196:199], v[164:167], v[114:117]
	v_mfma_f32_16x16x32_f16 v[118:121], v[204:207], v[164:167], v[118:121]
	v_mfma_f32_16x16x32_f16 v[98:101], v[196:199], v[172:175], v[98:101]
	v_mfma_f32_16x16x32_f16 v[102:105], v[204:207], v[172:175], v[102:105]
	v_mfma_f32_16x16x32_f16 v[82:85], v[196:199], v[180:183], v[82:85]
	v_mfma_f32_16x16x32_f16 v[86:89], v[204:207], v[180:183], v[86:89]
	v_mfma_f32_16x16x32_f16 v[66:69], v[196:199], v[188:191], v[66:69]
	v_mfma_f32_16x16x32_f16 v[70:73], v[204:207], v[188:191], v[70:73]
	s_mov_b32 m0, s17
	v_lshl_add_u64 v[212:213], s[14:15], 0, v[136:137]
	s_barrier
	ds_read_b128 v[160:163], v1 offset:16384
	ds_read_b128 v[164:167], v1 offset:17408
	ds_read_b128 v[168:171], v1 offset:18432
	ds_read_b128 v[172:175], v1 offset:19456
	ds_read_b128 v[176:179], v1 offset:20480
	ds_read_b128 v[180:183], v1 offset:21504
	ds_read_b128 v[184:187], v1 offset:22528
	ds_read_b128 v[188:191], v1 offset:23552
	global_load_lds_dwordx4 v[212:213], off
	s_mov_b32 m0, s20
	v_lshl_add_u64 v[214:215], s[14:15], 0, v[132:133]
	global_load_lds_dwordx4 v[214:215], off
	s_barrier
	s_waitcnt lgkmcnt(0)
	s_waitcnt lgkmcnt(0)
	v_mfma_f32_16x16x32_f16 v[58:61], v[144:147], v[160:163], v[58:61]
	v_mfma_f32_16x16x32_f16 v[62:65], v[152:155], v[160:163], v[62:65]
	v_mfma_f32_16x16x32_f16 v[42:45], v[144:147], v[168:171], v[42:45]
	v_mfma_f32_16x16x32_f16 v[46:49], v[152:155], v[168:171], v[46:49]
	v_mfma_f32_16x16x32_f16 v[26:29], v[144:147], v[176:179], v[26:29]
	v_mfma_f32_16x16x32_f16 v[30:33], v[152:155], v[176:179], v[30:33]
	v_mfma_f32_16x16x32_f16 v[10:13], v[144:147], v[184:187], v[10:13]
	v_mfma_f32_16x16x32_f16 v[14:17], v[152:155], v[184:187], v[14:17]
	v_mfma_f32_16x16x32_f16 v[58:61], v[148:151], v[164:167], v[58:61]
	v_mfma_f32_16x16x32_f16 v[62:65], v[156:159], v[164:167], v[62:65]
	v_mfma_f32_16x16x32_f16 v[42:45], v[148:151], v[172:175], v[42:45]
	v_mfma_f32_16x16x32_f16 v[46:49], v[156:159], v[172:175], v[46:49]
	v_mfma_f32_16x16x32_f16 v[26:29], v[148:151], v[180:183], v[26:29]
	v_mfma_f32_16x16x32_f16 v[30:33], v[156:159], v[180:183], v[30:33]
	v_mfma_f32_16x16x32_f16 v[10:13], v[148:151], v[188:191], v[10:13]
	v_mfma_f32_16x16x32_f16 v[14:17], v[156:159], v[188:191], v[14:17]
	s_barrier
; #define G_STAGE(bufoff, gbase, v0, v1) do { \
;     __builtin_amdgcn_global_load_lds((const unsigned*)((const char*)(gbase) + (v0)), (LAS unsigned*)(lds + (bufoff) + ldsw), 16, 0, 0); \
;     __builtin_amdgcn_global_load_lds((const unsigned*)((const char*)(gbase) + (v1)), (LAS unsigned*)(lds + (bufoff) + ldsw + 8192), 16, 0, 0); } while (0)
; #define G_LDA(dst, b, h) do { _Pragma("unroll") for (int m = 0; m < 4; ++m) _Pragma("unroll") for (int k = 0; k < 2; ++k) dst[m][k] = *(const LAS h8*)(lds + G_SA(b, h) + aoff + m * 2048 + k * 1024); } while (0)
; #define G_LDB(dst, b, h) do { _Pragma("unroll") for (int n = 0; n < 2; ++n) _Pragma("unroll") for (int k = 0; k < 2; ++k) dst[n][k] = *(const LAS h8*)(lds + G_SB(b, h) + boff + n * 2048 + k * 1024); } while (0)
; #define G_MMA(ai, bj, At, Bt) do { __builtin_amdgcn_s_setprio(1); _Pragma("unroll") for (int m = 0; m < 4; ++m) _Pragma("unroll") for (int n = 0; n < 2; ++n) _Pragma("unroll") for (int k = 0; k < 2; ++k) \
;     acc[ai][bj][m][n] = __builtin_amdgcn_mfma_f32_16x16x32_f16(Bt[n][k], At[m][k], acc[ai][bj][m][n], 0, 0, 0); __builtin_amdgcn_s_setprio(0); } while (0)
; #define G_WAIT_V(n) asm volatile("s_waitcnt vmcnt(" #n ")" ::: "memory")
; #define G_WAIT_L(n) asm volatile("s_waitcnt lgkmcnt(" #n ")" ::: "memory")
; #define G_BAR __builtin_amdgcn_s_barrier()
; #define G_SCHED __builtin_amdgcn_sched_barrier(0)
; template <bool PERM, class Sched, class Epi>
; DI void gemm256(LAS unsigned char* lds, const Sched& S, const Epi& E, int wv_) {
;     ...
;       G_STAGE(G_SB(0, 1), b2 + chB, cvB0, cvB1);
;       G_WAIT_V(6); G_BAR; G_MMA(1, 1, At, B1); G_BAR;
;       G_LDB(B0, 1, 0); G_SCHED; G_LDA(At, 1, 0); G_STAGE(G_SA(0, 1), a2 + chA, cvA0, cvA1);
;       G_WAIT_L(8); G_BAR; G_WAIT_L(0); G_MMA(0, 0, At, B0); G_BAR; G_SCHED;
;       G_LDB(B1, 1, 1); G_STAGE(G_SB(1, 0), b3, cvB0, cvB1);
	s_add_u32 s8, s12, 0x16000
	s_addc_u32 s9, s13, 0
	s_mov_b32 m0, s21
	v_lshl_add_u64 v[144:145], s[8:9], 0, v[134:135]
	global_load_lds_dwordx4 v[144:145], off
	s_mov_b32 m0, s22
	v_lshl_add_u64 v[144:145], s[8:9], 0, v[130:131]
	global_load_lds_dwordx4 v[144:145], off
	s_waitcnt vmcnt(6)
	s_barrier
	v_mfma_f32_16x16x32_f16 v[50:53], v[192:195], v[160:163], v[50:53]
	v_mfma_f32_16x16x32_f16 v[54:57], v[200:203], v[160:163], v[54:57]
	v_mfma_f32_16x16x32_f16 v[34:37], v[192:195], v[168:171], v[34:37]
	v_mfma_f32_16x16x32_f16 v[38:41], v[200:203], v[168:171], v[38:41]
	v_mfma_f32_16x16x32_f16 v[18:21], v[192:195], v[176:179], v[18:21]
	v_mfma_f32_16x16x32_f16 v[22:25], v[200:203], v[176:179], v[22:25]
	v_mfma_f32_16x16x32_f16 v[6:9], v[192:195], v[184:187], v[6:9]
	v_mfma_f32_16x16x32_f16 v[2:5], v[200:203], v[184:187], v[2:5]
	v_mfma_f32_16x16x32_f16 v[50:53], v[196:199], v[164:167], v[50:53]
	v_mfma_f32_16x16x32_f16 v[54:57], v[204:207], v[164:167], v[54:57]
	v_mfma_f32_16x16x32_f16 v[34:37], v[196:199], v[172:175], v[34:37]
	v_mfma_f32_16x16x32_f16 v[38:41], v[204:207], v[172:175], v[38:41]
	v_mfma_f32_16x16x32_f16 v[18:21], v[196:199], v[180:183], v[18:21]
	v_mfma_f32_16x16x32_f16 v[22:25], v[204:207], v[180:183], v[22:25]
	v_mfma_f32_16x16x32_f16 v[6:9], v[196:199], v[188:191], v[6:9]
	v_mfma_f32_16x16x32_f16 v[2:5], v[204:207], v[188:191], v[2:5]
	s_barrier
	ds_read_b128 v[144:147], v218
	ds_read_b128 v[148:151], v218 offset:1024
	ds_read_b128 v[152:155], v218 offset:2048
	ds_read_b128 v[156:159], v218 offset:3072
	s_add_u32 s8, s14, 0x10000
	s_addc_u32 s9, s15, 0
	s_mov_b32 m0, s23
	v_lshl_add_u64 v[192:193], s[8:9], 0, v[136:137]
	ds_read_b128 v[160:163], v1 offset:32768
	ds_read_b128 v[164:167], v1 offset:33792
	ds_read_b128 v[168:171], v1 offset:34816
	ds_read_b128 v[172:175], v1 offset:35840
	ds_read_b128 v[176:179], v1 offset:36864
	ds_read_b128 v[180:183], v1 offset:37888
	ds_read_b128 v[184:187], v1 offset:38912
	ds_read_b128 v[188:191], v1 offset:39936
	global_load_lds_dwordx4 v[192:193], off
	s_mov_b32 m0, s24
	v_lshl_add_u64 v[192:193], s[8:9], 0, v[132:133]
	global_load_lds_dwordx4 v[192:193], off
	s_waitcnt lgkmcnt(8)
	s_barrier
	s_waitcnt lgkmcnt(0)
	s_waitcnt lgkmcnt(0)
	v_mfma_f32_16x16x32_f16 v[122:125], v[144:147], v[160:163], v[122:125]
	v_mfma_f32_16x16x32_f16 v[126:129], v[152:155], v[160:163], v[126:129]
	v_mfma_f32_16x16x32_f16 v[106:109], v[144:147], v[168:171], v[106:109]
	v_mfma_f32_16x16x32_f16 v[110:113], v[152:155], v[168:171], v[110:113]
	v_mfma_f32_16x16x32_f16 v[90:93], v[144:147], v[176:179], v[90:93]
	v_mfma_f32_16x16x32_f16 v[94:97], v[152:155], v[176:179], v[94:97]
	v_mfma_f32_16x16x32_f16 v[74:77], v[144:147], v[184:187], v[74:77]
	v_mfma_f32_16x16x32_f16 v[78:81], v[152:155], v[184:187], v[78:81]
	v_mfma_f32_16x16x32_f16 v[122:125], v[148:151], v[164:167], v[122:125]
	v_mfma_f32_16x16x32_f16 v[126:129], v[156:159], v[164:167], v[126:129]
	v_mfma_f32_16x16x32_f16 v[106:109], v[148:151], v[172:175], v[106:109]
	v_mfma_f32_16x16x32_f16 v[110:113], v[156:159], v[172:175], v[110:113]
	v_mfma_f32_16x16x32_f16 v[90:93], v[148:151], v[180:183], v[90:93]
	v_mfma_f32_16x16x32_f16 v[94:97], v[156:159], v[180:183], v[94:97]
	v_mfma_f32_16x16x32_f16 v[74:77], v[148:151], v[188:191], v[74:77]
	v_mfma_f32_16x16x32_f16 v[78:81], v[156:159], v[188:191], v[78:81]
	s_barrier
	s_mov_b32 m0, s25
	v_lshl_add_u64 v[208:209], v[208:209], 0, s[86:87]
	ds_read_b128 v[192:195], v219
	ds_read_b128 v[196:199], v219 offset:1024
	ds_read_b128 v[200:203], v219 offset:2048
	ds_read_b128 v[204:207], v219 offset:3072
	global_load_lds_dwordx4 v[208:209], off
	s_mov_b32 m0, s26
	v_lshl_add_u64 v[208:209], v[210:211], 0, s[86:87]
	global_load_lds_dwordx4 v[208:209], off
	s_barrier
; #define G_STAGE(bufoff, gbase, v0, v1) do { \
;     __builtin_amdgcn_global_load_lds((const unsigned*)((const char*)(gbase) + (v0)), (LAS unsigned*)(lds + (bufoff) + ldsw), 16, 0, 0); \
;     __builtin_amdgcn_global_load_lds((const unsigned*)((const char*)(gbase) + (v1)), (LAS unsigned*)(lds + (bufoff) + ldsw + 8192), 16, 0, 0); } while (0)
; #define G_LDA(dst, b, h) do { _Pragma("unroll") for (int m = 0; m < 4; ++m) _Pragma("unroll") for (int k = 0; k < 2; ++k) dst[m][k] = *(const LAS h8*)(lds + G_SA(b, h) + aoff + m * 2048 + k * 1024); } while (0)
; #define G_MMA(ai, bj, At, Bt) do { __builtin_amdgcn_s_setprio(1); _Pragma("unroll") for (int m = 0; m < 4; ++m) _Pragma("unroll") for (int n = 0; n < 2; ++n) _Pragma("unroll") for (int k = 0; k < 2; ++k) \
;     acc[ai][bj][m][n] = __builtin_amdgcn_mfma_f32_16x16x32_f16(Bt[n][k], At[m][k], acc[ai][bj][m][n], 0, 0, 0); __builtin_amdgcn_s_setprio(0); } while (0)
; #define G_WAIT_V(n) asm volatile("s_waitcnt vmcnt(" #n ")" ::: "memory")
; #define G_WAIT_L(n) asm volatile("s_waitcnt lgkmcnt(" #n ")" ::: "memory")
; #define G_BAR __builtin_amdgcn_s_barrier()
; #define G_SCHED __builtin_amdgcn_sched_barrier(0)
; template <bool PERM, class Sched, class Epi>
; DI void gemm256(LAS unsigned char* lds, const Sched& S, const Epi& E, int wv_) {
;     ...
;       G_BAR; G_WAIT_L(0); G_MMA(0, 1, At, B1); G_BAR;
;       G_LDA(At, 1, 1); G_STAGE(G_SA(1, 0), a3, cvA0, cvA1);
;       G_BAR; G_WAIT_L(0); G_MMA(1, 0, At, B0); G_BAR; G_SCHED;
;       G_STAGE(G_SB(1, 1), b3 + chB, cvB0, cvB1);
;       G_WAIT_V(6); G_BAR; G_MMA(1, 1, At, B1); G_BAR;
;     }
	s_waitcnt lgkmcnt(0)
	s_waitcnt lgkmcnt(0)
	v_mfma_f32_16x16x32_f16 v[114:117], v[192:195], v[160:163], v[114:117]
	v_mfma_f32_16x16x32_f16 v[118:121], v[200:203], v[160:163], v[118:121]
	v_mfma_f32_16x16x32_f16 v[98:101], v[192:195], v[168:171], v[98:101]
	v_mfma_f32_16x16x32_f16 v[102:105], v[200:203], v[168:171], v[102:105]
	v_mfma_f32_16x16x32_f16 v[82:85], v[192:195], v[176:179], v[82:85]
	v_mfma_f32_16x16x32_f16 v[86:89], v[200:203], v[176:179], v[86:89]
	v_mfma_f32_16x16x32_f16 v[66:69], v[192:195], v[184:187], v[66:69]
	v_mfma_f32_16x16x32_f16 v[70:73], v[200:203], v[184:187], v[70:73]
	v_mfma_f32_16x16x32_f16 v[114:117], v[196:199], v[164:167], v[114:117]
	v_mfma_f32_16x16x32_f16 v[118:121], v[204:207], v[164:167], v[118:121]
	v_mfma_f32_16x16x32_f16 v[98:101], v[196:199], v[172:175], v[98:101]
	v_mfma_f32_16x16x32_f16 v[102:105], v[204:207], v[172:175], v[102:105]
	v_mfma_f32_16x16x32_f16 v[82:85], v[196:199], v[180:183], v[82:85]
	v_mfma_f32_16x16x32_f16 v[86:89], v[204:207], v[180:183], v[86:89]
	v_mfma_f32_16x16x32_f16 v[66:69], v[196:199], v[188:191], v[66:69]
	v_mfma_f32_16x16x32_f16 v[70:73], v[204:207], v[188:191], v[70:73]
	s_mov_b32 m0, s27
	v_lshl_add_u64 v[208:209], v[212:213], 0, s[86:87]
	s_barrier
	ds_read_b128 v[160:163], v1 offset:49152
	ds_read_b128 v[164:167], v1 offset:50176
	ds_read_b128 v[168:171], v1 offset:51200
	ds_read_b128 v[172:175], v1 offset:52224
	ds_read_b128 v[176:179], v1 offset:53248
	ds_read_b128 v[180:183], v1 offset:54272
	ds_read_b128 v[184:187], v1 offset:55296
	ds_read_b128 v[188:191], v1 offset:56320
	global_load_lds_dwordx4 v[208:209], off
	s_mov_b32 m0, s28
	v_lshl_add_u64 v[208:209], v[214:215], 0, s[86:87]
	global_load_lds_dwordx4 v[208:209], off
	s_barrier
	s_waitcnt lgkmcnt(0)
	s_waitcnt lgkmcnt(0)
	v_mfma_f32_16x16x32_f16 v[58:61], v[144:147], v[160:163], v[58:61]
	v_mfma_f32_16x16x32_f16 v[62:65], v[152:155], v[160:163], v[62:65]
	v_mfma_f32_16x16x32_f16 v[42:45], v[144:147], v[168:171], v[42:45]
	v_mfma_f32_16x16x32_f16 v[46:49], v[152:155], v[168:171], v[46:49]
	v_mfma_f32_16x16x32_f16 v[26:29], v[144:147], v[176:179], v[26:29]
	v_mfma_f32_16x16x32_f16 v[30:33], v[152:155], v[176:179], v[30:33]
	v_mfma_f32_16x16x32_f16 v[10:13], v[144:147], v[184:187], v[10:13]
	v_mfma_f32_16x16x32_f16 v[14:17], v[152:155], v[184:187], v[14:17]
	v_mfma_f32_16x16x32_f16 v[58:61], v[148:151], v[164:167], v[58:61]
	v_mfma_f32_16x16x32_f16 v[62:65], v[156:159], v[164:167], v[62:65]
	v_mfma_f32_16x16x32_f16 v[42:45], v[148:151], v[172:175], v[42:45]
	v_mfma_f32_16x16x32_f16 v[46:49], v[156:159], v[172:175], v[46:49]
	v_mfma_f32_16x16x32_f16 v[26:29], v[148:151], v[180:183], v[26:29]
	v_mfma_f32_16x16x32_f16 v[30:33], v[156:159], v[180:183], v[30:33]
	v_mfma_f32_16x16x32_f16 v[10:13], v[148:151], v[188:191], v[10:13]
	v_mfma_f32_16x16x32_f16 v[14:17], v[156:159], v[188:191], v[14:17]
	s_barrier
	s_add_u32 s8, s12, 0x16080
	s_addc_u32 s9, s13, 0
	s_mov_b32 m0, s29
	v_lshl_add_u64 v[144:145], s[8:9], 0, v[134:135]
	global_load_lds_dwordx4 v[144:145], off
	s_mov_b32 m0, s30
	v_lshl_add_u64 v[144:145], s[8:9], 0, v[130:131]
	global_load_lds_dwordx4 v[144:145], off
	s_waitcnt vmcnt(6)
	s_barrier
	v_mfma_f32_16x16x32_f16 v[50:53], v[192:195], v[160:163], v[50:53]
	v_mfma_f32_16x16x32_f16 v[54:57], v[200:203], v[160:163], v[54:57]
	v_mfma_f32_16x16x32_f16 v[34:37], v[192:195], v[168:171], v[34:37]
	v_mfma_f32_16x16x32_f16 v[38:41], v[200:203], v[168:171], v[38:41]
	v_mfma_f32_16x16x32_f16 v[18:21], v[192:195], v[176:179], v[18:21]
	v_mfma_f32_16x16x32_f16 v[22:25], v[200:203], v[176:179], v[22:25]
	v_mfma_f32_16x16x32_f16 v[6:9], v[192:195], v[184:187], v[6:9]
	v_mfma_f32_16x16x32_f16 v[2:5], v[200:203], v[184:187], v[2:5]
	v_mfma_f32_16x16x32_f16 v[50:53], v[196:199], v[164:167], v[50:53]
	v_mfma_f32_16x16x32_f16 v[54:57], v[204:207], v[164:167], v[54:57]
	v_mfma_f32_16x16x32_f16 v[34:37], v[196:199], v[172:175], v[34:37]
	v_mfma_f32_16x16x32_f16 v[38:41], v[204:207], v[172:175], v[38:41]
	v_mfma_f32_16x16x32_f16 v[18:21], v[196:199], v[180:183], v[18:21]
	v_mfma_f32_16x16x32_f16 v[22:25], v[204:207], v[180:183], v[22:25]
	v_mfma_f32_16x16x32_f16 v[6:9], v[196:199], v[188:191], v[6:9]
	v_mfma_f32_16x16x32_f16 v[2:5], v[204:207], v[188:191], v[2:5]
	s_cmp_ge_i32 s60, s46
	s_mov_b64 s[8:9], s[10:11]
	s_mov_b32 s12, s60
	s_barrier
	s_cbranch_scc0 .LBB0_1748
	s_branch .LBB0_1743

; #define G_STAGE(bufoff, gbase, v0, v1) do { \
;     __builtin_amdgcn_global_load_lds((const unsigned*)((const char*)(gbase) + (v0)), (LAS unsigned*)(lds + (bufoff) + ldsw), 16, 0, 0); \
;     __builtin_amdgcn_global_load_lds((const unsigned*)((const char*)(gbase) + (v1)), (LAS unsigned*)(lds + (bufoff) + ldsw + 8192), 16, 0, 0); } while (0)
; #define G_LDA(dst, b, h) do { _Pragma("unroll") for (int m = 0; m < 4; ++m) _Pragma("unroll") for (int k = 0; k < 2; ++k) dst[m][k] = *(const LAS h8*)(lds + G_SA(b, h) + aoff + m * 2048 + k * 1024); } while (0)
; #define G_LDB(dst, b, h) do { _Pragma("unroll") for (int n = 0; n < 2; ++n) _Pragma("unroll") for (int k = 0; k < 2; ++k) dst[n][k] = *(const LAS h8*)(lds + G_SB(b, h) + boff + n * 2048 + k * 1024); } while (0)
; #define G_MMA(ai, bj, At, Bt) do { __builtin_amdgcn_s_setprio(1); _Pragma("unroll") for (int m = 0; m < 4; ++m) _Pragma("unroll") for (int n = 0; n < 2; ++n) _Pragma("unroll") for (int k = 0; k < 2; ++k) \
;     acc[ai][bj][m][n] = __builtin_amdgcn_mfma_f32_16x16x32_f16(Bt[n][k], At[m][k], acc[ai][bj][m][n], 0, 0, 0); __builtin_amdgcn_s_setprio(0); } while (0)
; #define G_WAIT_V(n) asm volatile("s_waitcnt vmcnt(" #n ")" ::: "memory")
; #define G_WAIT_L(n) asm volatile("s_waitcnt lgkmcnt(" #n ")" ::: "memory")
; #define G_BAR __builtin_amdgcn_s_barrier()
; #define G_SCHED __builtin_amdgcn_sched_barrier(0)
; template <bool PERM, class Sched, class Epi>
; DI void gemm256(LAS unsigned char* lds, const Sched& S, const Epi& E, int wv_) {
;     ...
;       const bool last = (t == nt - 2);
;       const char* a1 = cA + (size_t)(t + 1) * kstep;
;       const char* a2 = last ? nA : cA + (size_t)(t + 2) * kstep;
;       const char* b2 = last ? nB : cB + (size_t)(t + 2) * kstep;
;       const char* a3 = a2 + kstep;
;       const char* b3 = b2 + kstep;
;       G_LDB(B0, 0, 0); G_SCHED; G_LDA(At, 0, 0); G_STAGE(G_SA(1, 1), a1 + chA, cvA0, cvA1);
;       G_WAIT_L(8); G_BAR; G_WAIT_L(0); G_MMA(0, 0, At, B0); G_BAR; G_SCHED;
;       G_LDB(B1, 0, 1); G_STAGE(G_SB(0, 0), b2, cvB0, cvB1);
;       G_BAR; G_WAIT_L(0); G_MMA(0, 1, At, B1); G_BAR;
;       G_LDA(At, 0, 1); G_STAGE(G_SA(0, 0), a2, cvA0, cvA1);
;       G_BAR; G_WAIT_L(0); G_MMA(1, 0, At, B0); G_BAR; G_SCHED;
;       G_STAGE(G_SB(0, 1), b2 + chB, cvB0, cvB1);
;       G_WAIT_V(6); G_BAR; G_MMA(1, 1, At, B1); G_BAR;
.LBB0_2281:
	ds_read_b128 v[148:151], v239
	ds_read_b128 v[152:155], v239 offset:1024
	s_add_i32 s85, s14, 2
	ds_read_b128 v[156:159], v239 offset:2048
	ds_read_b128 v[160:163], v239 offset:3072
	s_add_u32 s15, s12, 0xfffc0080
	s_addc_u32 s16, s13, -1
	s_cmp_eq_u32 s75, s14
	s_cselect_b32 s14, s8, s46
	s_cselect_b32 s17, s7, s16
	s_cselect_b32 s16, s6, s15
	s_cselect_b32 s15, s9, s74
	v_lshl_add_u64 v[144:145], s[12:13], 0, v[140:141]
	s_add_i32 m0, s20, 0xc000
	ds_read_b128 v[164:167], v1
	ds_read_b128 v[168:171], v1 offset:1024
	ds_read_b128 v[172:175], v1 offset:2048
	ds_read_b128 v[176:179], v1 offset:3072
	ds_read_b128 v[180:183], v1 offset:4096
	ds_read_b128 v[184:187], v1 offset:5120
	ds_read_b128 v[188:191], v1 offset:6144
	ds_read_b128 v[192:195], v1 offset:7168
	global_load_lds_dwordx4 v[144:145], off
	s_add_i32 m0, s20, 0xe000
	v_lshl_add_u64 v[144:145], s[12:13], 0, v[142:143]
	global_load_lds_dwordx4 v[144:145], off
	s_waitcnt lgkmcnt(8)
	s_barrier
	s_waitcnt lgkmcnt(0)
	s_waitcnt lgkmcnt(0)
	v_mfma_f32_16x16x32_f16 v[114:117], v[148:151], v[164:167], v[114:117]
	v_mfma_f32_16x16x32_f16 v[126:129], v[156:159], v[164:167], v[126:129]
	v_mfma_f32_16x16x32_f16 v[98:101], v[148:151], v[172:175], v[98:101]
	v_mfma_f32_16x16x32_f16 v[110:113], v[156:159], v[172:175], v[110:113]
	v_mfma_f32_16x16x32_f16 v[82:85], v[148:151], v[180:183], v[82:85]
	v_mfma_f32_16x16x32_f16 v[94:97], v[156:159], v[180:183], v[94:97]
	v_mfma_f32_16x16x32_f16 v[66:69], v[148:151], v[188:191], v[66:69]
	v_mfma_f32_16x16x32_f16 v[78:81], v[156:159], v[188:191], v[78:81]
	v_mfma_f32_16x16x32_f16 v[114:117], v[152:155], v[168:171], v[114:117]
	v_mfma_f32_16x16x32_f16 v[126:129], v[160:163], v[168:171], v[126:129]
	v_mfma_f32_16x16x32_f16 v[98:101], v[152:155], v[176:179], v[98:101]
	v_mfma_f32_16x16x32_f16 v[110:113], v[160:163], v[176:179], v[110:113]
	v_mfma_f32_16x16x32_f16 v[82:85], v[152:155], v[184:187], v[82:85]
	v_mfma_f32_16x16x32_f16 v[94:97], v[160:163], v[184:187], v[94:97]
	v_mfma_f32_16x16x32_f16 v[66:69], v[152:155], v[192:195], v[66:69]
	v_mfma_f32_16x16x32_f16 v[78:81], v[160:163], v[192:195], v[78:81]
	s_barrier
	ds_read_b128 v[196:199], v243
	ds_read_b128 v[200:203], v243 offset:1024
	s_mov_b32 m0, s11
	ds_read_b128 v[204:207], v243 offset:2048
	ds_read_b128 v[208:211], v243 offset:3072
	v_lshl_add_u64 v[144:145], s[14:15], 0, v[132:133]
	global_load_lds_dwordx4 v[144:145], off
	s_mov_b32 m0, s21
	v_lshl_add_u64 v[212:213], s[14:15], 0, v[136:137]
	global_load_lds_dwordx4 v[212:213], off
	s_barrier
	s_waitcnt lgkmcnt(0)
	s_waitcnt lgkmcnt(0)
	v_mfma_f32_16x16x32_f16 v[122:125], v[196:199], v[164:167], v[122:125]
	v_mfma_f32_16x16x32_f16 v[118:121], v[204:207], v[164:167], v[118:121]
	v_mfma_f32_16x16x32_f16 v[106:109], v[196:199], v[172:175], v[106:109]
	v_mfma_f32_16x16x32_f16 v[102:105], v[204:207], v[172:175], v[102:105]
	v_mfma_f32_16x16x32_f16 v[90:93], v[196:199], v[180:183], v[90:93]
	v_mfma_f32_16x16x32_f16 v[86:89], v[204:207], v[180:183], v[86:89]
	v_mfma_f32_16x16x32_f16 v[74:77], v[196:199], v[188:191], v[74:77]
	v_mfma_f32_16x16x32_f16 v[70:73], v[204:207], v[188:191], v[70:73]
	v_mfma_f32_16x16x32_f16 v[122:125], v[200:203], v[168:171], v[122:125]
	v_mfma_f32_16x16x32_f16 v[118:121], v[208:211], v[168:171], v[118:121]
	v_mfma_f32_16x16x32_f16 v[106:109], v[200:203], v[176:179], v[106:109]
	v_mfma_f32_16x16x32_f16 v[102:105], v[208:211], v[176:179], v[102:105]
	v_mfma_f32_16x16x32_f16 v[90:93], v[200:203], v[184:187], v[90:93]
	v_mfma_f32_16x16x32_f16 v[86:89], v[208:211], v[184:187], v[86:89]
	v_mfma_f32_16x16x32_f16 v[74:77], v[200:203], v[192:195], v[74:77]
	v_mfma_f32_16x16x32_f16 v[70:73], v[208:211], v[192:195], v[70:73]
	s_mov_b32 m0, s20
	v_lshl_add_u64 v[214:215], s[16:17], 0, v[130:131]
	s_barrier
	ds_read_b128 v[164:167], v1 offset:16384
	ds_read_b128 v[168:171], v1 offset:17408
	ds_read_b128 v[172:175], v1 offset:18432
	ds_read_b128 v[176:179], v1 offset:19456
	ds_read_b128 v[180:183], v1 offset:20480
	ds_read_b128 v[184:187], v1 offset:21504
	ds_read_b128 v[188:191], v1 offset:22528
	ds_read_b128 v[192:195], v1 offset:23552
	global_load_lds_dwordx4 v[214:215], off
	s_mov_b32 m0, s22
	v_lshl_add_u64 v[216:217], s[16:17], 0, v[134:135]
	global_load_lds_dwordx4 v[216:217], off
	s_barrier
	s_waitcnt lgkmcnt(0)
	s_waitcnt lgkmcnt(0)
	v_mfma_f32_16x16x32_f16 v[50:53], v[148:151], v[164:167], v[50:53]
	v_mfma_f32_16x16x32_f16 v[62:65], v[156:159], v[164:167], v[62:65]
	v_mfma_f32_16x16x32_f16 v[34:37], v[148:151], v[172:175], v[34:37]
	v_mfma_f32_16x16x32_f16 v[46:49], v[156:159], v[172:175], v[46:49]
	v_mfma_f32_16x16x32_f16 v[18:21], v[148:151], v[180:183], v[18:21]
	v_mfma_f32_16x16x32_f16 v[30:33], v[156:159], v[180:183], v[30:33]
	v_mfma_f32_16x16x32_f16 v[2:5], v[148:151], v[188:191], v[2:5]
	v_mfma_f32_16x16x32_f16 v[14:17], v[156:159], v[188:191], v[14:17]
	v_mfma_f32_16x16x32_f16 v[50:53], v[152:155], v[168:171], v[50:53]
	v_mfma_f32_16x16x32_f16 v[62:65], v[160:163], v[168:171], v[62:65]
	v_mfma_f32_16x16x32_f16 v[34:37], v[152:155], v[176:179], v[34:37]
	v_mfma_f32_16x16x32_f16 v[46:49], v[160:163], v[176:179], v[46:49]
	v_mfma_f32_16x16x32_f16 v[18:21], v[152:155], v[184:187], v[18:21]
	v_mfma_f32_16x16x32_f16 v[30:33], v[160:163], v[184:187], v[30:33]
	v_mfma_f32_16x16x32_f16 v[2:5], v[152:155], v[192:195], v[2:5]
	v_mfma_f32_16x16x32_f16 v[14:17], v[160:163], v[192:195], v[14:17]
	s_barrier
	s_add_u32 s40, s14, 0x400000
	s_addc_u32 s41, s15, 0
	s_mov_b32 m0, s23
	v_lshl_add_u64 v[148:149], s[40:41], 0, v[132:133]
	global_load_lds_dwordx4 v[148:149], off
	s_mov_b32 m0, s24
	v_lshl_add_u64 v[148:149], s[40:41], 0, v[136:137]
	global_load_lds_dwordx4 v[148:149], off
	s_waitcnt vmcnt(6)
	s_barrier
; #define G_STAGE(bufoff, gbase, v0, v1) do { \
;     __builtin_amdgcn_global_load_lds((const unsigned*)((const char*)(gbase) + (v0)), (LAS unsigned*)(lds + (bufoff) + ldsw), 16, 0, 0); \
;     __builtin_amdgcn_global_load_lds((const unsigned*)((const char*)(gbase) + (v1)), (LAS unsigned*)(lds + (bufoff) + ldsw + 8192), 16, 0, 0); } while (0)
; #define G_LDA(dst, b, h) do { _Pragma("unroll") for (int m = 0; m < 4; ++m) _Pragma("unroll") for (int k = 0; k < 2; ++k) dst[m][k] = *(const LAS h8*)(lds + G_SA(b, h) + aoff + m * 2048 + k * 1024); } while (0)
; #define G_LDB(dst, b, h) do { _Pragma("unroll") for (int n = 0; n < 2; ++n) _Pragma("unroll") for (int k = 0; k < 2; ++k) dst[n][k] = *(const LAS h8*)(lds + G_SB(b, h) + boff + n * 2048 + k * 1024); } while (0)
; #define G_MMA(ai, bj, At, Bt) do { __builtin_amdgcn_s_setprio(1); _Pragma("unroll") for (int m = 0; m < 4; ++m) _Pragma("unroll") for (int n = 0; n < 2; ++n) _Pragma("unroll") for (int k = 0; k < 2; ++k) \
;     acc[ai][bj][m][n] = __builtin_amdgcn_mfma_f32_16x16x32_f16(Bt[n][k], At[m][k], acc[ai][bj][m][n], 0, 0, 0); __builtin_amdgcn_s_setprio(0); } while (0)
; #define G_WAIT_V(n) asm volatile("s_waitcnt vmcnt(" #n ")" ::: "memory")
; #define G_WAIT_L(n) asm volatile("s_waitcnt lgkmcnt(" #n ")" ::: "memory")
; #define G_BAR __builtin_amdgcn_s_barrier()
; #define G_SCHED __builtin_amdgcn_sched_barrier(0)
; template <bool PERM, class Sched, class Epi>
; DI void gemm256(LAS unsigned char* lds, const Sched& S, const Epi& E, int wv_) {
;     ...
;       G_WAIT_V(6); G_BAR; G_MMA(1, 1, At, B1); G_BAR;
;       G_LDB(B0, 1, 0); G_SCHED; G_LDA(At, 1, 0); G_STAGE(G_SA(0, 1), a2 + chA, cvA0, cvA1);
;       G_WAIT_L(8); G_BAR; G_WAIT_L(0); G_MMA(0, 0, At, B0); G_BAR; G_SCHED;
;       G_LDB(B1, 1, 1); G_STAGE(G_SB(1, 0), b3, cvB0, cvB1);
	v_mfma_f32_16x16x32_f16 v[58:61], v[196:199], v[164:167], v[58:61]
	v_mfma_f32_16x16x32_f16 v[54:57], v[204:207], v[164:167], v[54:57]
	v_mfma_f32_16x16x32_f16 v[42:45], v[196:199], v[172:175], v[42:45]
	v_mfma_f32_16x16x32_f16 v[38:41], v[204:207], v[172:175], v[38:41]
	v_mfma_f32_16x16x32_f16 v[26:29], v[196:199], v[180:183], v[26:29]
	v_mfma_f32_16x16x32_f16 v[22:25], v[204:207], v[180:183], v[22:25]
	v_mfma_f32_16x16x32_f16 v[10:13], v[196:199], v[188:191], v[10:13]
	v_mfma_f32_16x16x32_f16 v[6:9], v[204:207], v[188:191], v[6:9]
	v_mfma_f32_16x16x32_f16 v[58:61], v[200:203], v[168:171], v[58:61]
	v_mfma_f32_16x16x32_f16 v[54:57], v[208:211], v[168:171], v[54:57]
	v_mfma_f32_16x16x32_f16 v[42:45], v[200:203], v[176:179], v[42:45]
	v_mfma_f32_16x16x32_f16 v[38:41], v[208:211], v[176:179], v[38:41]
	v_mfma_f32_16x16x32_f16 v[26:29], v[200:203], v[184:187], v[26:29]
	v_mfma_f32_16x16x32_f16 v[22:25], v[208:211], v[184:187], v[22:25]
	v_mfma_f32_16x16x32_f16 v[10:13], v[200:203], v[192:195], v[10:13]
	v_mfma_f32_16x16x32_f16 v[6:9], v[208:211], v[192:195], v[6:9]
	s_barrier
	ds_read_b128 v[148:151], v244
	ds_read_b128 v[152:155], v244 offset:1024
	ds_read_b128 v[156:159], v244 offset:2048
	ds_read_b128 v[160:163], v244 offset:3072
	s_add_u32 s16, s16, 0x40000
	s_addc_u32 s17, s17, 0
	s_mov_b32 m0, s25
	v_lshl_add_u64 v[196:197], s[16:17], 0, v[130:131]
	ds_read_b128 v[164:167], v1 offset:32768
	ds_read_b128 v[168:171], v1 offset:33792
	ds_read_b128 v[172:175], v1 offset:34816
	ds_read_b128 v[176:179], v1 offset:35840
	ds_read_b128 v[180:183], v1 offset:36864
	ds_read_b128 v[184:187], v1 offset:37888
	ds_read_b128 v[188:191], v1 offset:38912
	ds_read_b128 v[192:195], v1 offset:39936
	global_load_lds_dwordx4 v[196:197], off
	s_mov_b32 m0, s26
	v_lshl_add_u64 v[196:197], s[16:17], 0, v[134:135]
	global_load_lds_dwordx4 v[196:197], off
	s_waitcnt lgkmcnt(8)
	s_barrier
	s_waitcnt lgkmcnt(0)
	s_waitcnt lgkmcnt(0)
	v_mfma_f32_16x16x32_f16 v[114:117], v[148:151], v[164:167], v[114:117]
	v_mfma_f32_16x16x32_f16 v[126:129], v[156:159], v[164:167], v[126:129]
	v_mfma_f32_16x16x32_f16 v[98:101], v[148:151], v[172:175], v[98:101]
	v_mfma_f32_16x16x32_f16 v[110:113], v[156:159], v[172:175], v[110:113]
	v_mfma_f32_16x16x32_f16 v[82:85], v[148:151], v[180:183], v[82:85]
	v_mfma_f32_16x16x32_f16 v[94:97], v[156:159], v[180:183], v[94:97]
	v_mfma_f32_16x16x32_f16 v[66:69], v[148:151], v[188:191], v[66:69]
	v_mfma_f32_16x16x32_f16 v[78:81], v[156:159], v[188:191], v[78:81]
	v_mfma_f32_16x16x32_f16 v[114:117], v[152:155], v[168:171], v[114:117]
	v_mfma_f32_16x16x32_f16 v[126:129], v[160:163], v[168:171], v[126:129]
	v_mfma_f32_16x16x32_f16 v[98:101], v[152:155], v[176:179], v[98:101]
	v_mfma_f32_16x16x32_f16 v[110:113], v[160:163], v[176:179], v[110:113]
	v_mfma_f32_16x16x32_f16 v[82:85], v[152:155], v[184:187], v[82:85]
	v_mfma_f32_16x16x32_f16 v[94:97], v[160:163], v[184:187], v[94:97]
	v_mfma_f32_16x16x32_f16 v[66:69], v[152:155], v[192:195], v[66:69]
	v_mfma_f32_16x16x32_f16 v[78:81], v[160:163], v[192:195], v[78:81]
	s_barrier
	s_mov_b32 m0, s28
	ds_read_b128 v[196:199], v246
	ds_read_b128 v[200:203], v246 offset:1024
	v_lshl_add_u64 v[144:145], v[144:145], 0, s[86:87]
	ds_read_b128 v[204:207], v246 offset:2048
	ds_read_b128 v[208:211], v246 offset:3072
	global_load_lds_dwordx4 v[144:145], off
	s_mov_b32 m0, s29
	v_lshl_add_u64 v[144:145], v[212:213], 0, s[86:87]
	global_load_lds_dwordx4 v[144:145], off
	s_barrier
; #define G_STAGE(bufoff, gbase, v0, v1) do { \
;     __builtin_amdgcn_global_load_lds((const unsigned*)((const char*)(gbase) + (v0)), (LAS unsigned*)(lds + (bufoff) + ldsw), 16, 0, 0); \
;     __builtin_amdgcn_global_load_lds((const unsigned*)((const char*)(gbase) + (v1)), (LAS unsigned*)(lds + (bufoff) + ldsw + 8192), 16, 0, 0); } while (0)
; #define G_LDA(dst, b, h) do { _Pragma("unroll") for (int m = 0; m < 4; ++m) _Pragma("unroll") for (int k = 0; k < 2; ++k) dst[m][k] = *(const LAS h8*)(lds + G_SA(b, h) + aoff + m * 2048 + k * 1024); } while (0)
; #define G_MMA(ai, bj, At, Bt) do { __builtin_amdgcn_s_setprio(1); _Pragma("unroll") for (int m = 0; m < 4; ++m) _Pragma("unroll") for (int n = 0; n < 2; ++n) _Pragma("unroll") for (int k = 0; k < 2; ++k) \
;     acc[ai][bj][m][n] = __builtin_amdgcn_mfma_f32_16x16x32_f16(Bt[n][k], At[m][k], acc[ai][bj][m][n], 0, 0, 0); __builtin_amdgcn_s_setprio(0); } while (0)
; #define G_WAIT_V(n) asm volatile("s_waitcnt vmcnt(" #n ")" ::: "memory")
; #define G_WAIT_L(n) asm volatile("s_waitcnt lgkmcnt(" #n ")" ::: "memory")
; #define G_BAR __builtin_amdgcn_s_barrier()
; #define G_SCHED __builtin_amdgcn_sched_barrier(0)
; template <bool PERM, class Sched, class Epi>
; DI void gemm256(LAS unsigned char* lds, const Sched& S, const Epi& E, int wv_) {
;     ...
;       G_BAR; G_WAIT_L(0); G_MMA(0, 1, At, B1); G_BAR;
;       G_LDA(At, 1, 1); G_STAGE(G_SA(1, 0), a3, cvA0, cvA1);
;       G_BAR; G_WAIT_L(0); G_MMA(1, 0, At, B0); G_BAR; G_SCHED;
;       G_STAGE(G_SB(1, 1), b3 + chB, cvB0, cvB1);
;       G_WAIT_V(6); G_BAR; G_MMA(1, 1, At, B1); G_BAR;
;     }
	s_waitcnt lgkmcnt(0)
	s_waitcnt lgkmcnt(0)
	v_mfma_f32_16x16x32_f16 v[122:125], v[196:199], v[164:167], v[122:125]
	v_mfma_f32_16x16x32_f16 v[118:121], v[204:207], v[164:167], v[118:121]
	v_mfma_f32_16x16x32_f16 v[106:109], v[196:199], v[172:175], v[106:109]
	v_mfma_f32_16x16x32_f16 v[102:105], v[204:207], v[172:175], v[102:105]
	v_mfma_f32_16x16x32_f16 v[90:93], v[196:199], v[180:183], v[90:93]
	v_mfma_f32_16x16x32_f16 v[86:89], v[204:207], v[180:183], v[86:89]
	v_mfma_f32_16x16x32_f16 v[74:77], v[196:199], v[188:191], v[74:77]
	v_mfma_f32_16x16x32_f16 v[70:73], v[204:207], v[188:191], v[70:73]
	v_mfma_f32_16x16x32_f16 v[122:125], v[200:203], v[168:171], v[122:125]
	v_mfma_f32_16x16x32_f16 v[118:121], v[208:211], v[168:171], v[118:121]
	v_mfma_f32_16x16x32_f16 v[106:109], v[200:203], v[176:179], v[106:109]
	v_mfma_f32_16x16x32_f16 v[102:105], v[208:211], v[176:179], v[102:105]
	v_mfma_f32_16x16x32_f16 v[90:93], v[200:203], v[184:187], v[90:93]
	v_mfma_f32_16x16x32_f16 v[86:89], v[208:211], v[184:187], v[86:89]
	v_mfma_f32_16x16x32_f16 v[74:77], v[200:203], v[192:195], v[74:77]
	v_mfma_f32_16x16x32_f16 v[70:73], v[208:211], v[192:195], v[70:73]
	s_mov_b32 m0, s30
	v_lshl_add_u64 v[144:145], v[214:215], 0, s[86:87]
	s_barrier
	ds_read_b128 v[164:167], v1 offset:49152
	ds_read_b128 v[168:171], v1 offset:50176
	ds_read_b128 v[172:175], v1 offset:51200
	ds_read_b128 v[176:179], v1 offset:52224
	ds_read_b128 v[180:183], v1 offset:53248
	ds_read_b128 v[184:187], v1 offset:54272
	ds_read_b128 v[188:191], v1 offset:55296
	ds_read_b128 v[192:195], v1 offset:56320
	global_load_lds_dwordx4 v[144:145], off
	s_mov_b32 m0, s31
	v_lshl_add_u64 v[144:145], v[216:217], 0, s[86:87]
	global_load_lds_dwordx4 v[144:145], off
	s_barrier
	s_waitcnt lgkmcnt(0)
	s_waitcnt lgkmcnt(0)
	v_mfma_f32_16x16x32_f16 v[50:53], v[148:151], v[164:167], v[50:53]
	v_mfma_f32_16x16x32_f16 v[62:65], v[156:159], v[164:167], v[62:65]
	v_mfma_f32_16x16x32_f16 v[34:37], v[148:151], v[172:175], v[34:37]
	v_mfma_f32_16x16x32_f16 v[46:49], v[156:159], v[172:175], v[46:49]
	v_mfma_f32_16x16x32_f16 v[18:21], v[148:151], v[180:183], v[18:21]
	v_mfma_f32_16x16x32_f16 v[30:33], v[156:159], v[180:183], v[30:33]
	v_mfma_f32_16x16x32_f16 v[2:5], v[148:151], v[188:191], v[2:5]
	v_mfma_f32_16x16x32_f16 v[14:17], v[156:159], v[188:191], v[14:17]
	v_mfma_f32_16x16x32_f16 v[50:53], v[152:155], v[168:171], v[50:53]
	v_mfma_f32_16x16x32_f16 v[62:65], v[160:163], v[168:171], v[62:65]
	v_mfma_f32_16x16x32_f16 v[34:37], v[152:155], v[176:179], v[34:37]
	v_mfma_f32_16x16x32_f16 v[46:49], v[160:163], v[176:179], v[46:49]
	v_mfma_f32_16x16x32_f16 v[18:21], v[152:155], v[184:187], v[18:21]
	v_mfma_f32_16x16x32_f16 v[30:33], v[160:163], v[184:187], v[30:33]
	v_mfma_f32_16x16x32_f16 v[2:5], v[152:155], v[192:195], v[2:5]
	v_mfma_f32_16x16x32_f16 v[14:17], v[160:163], v[192:195], v[14:17]
	s_barrier
	s_add_u32 s14, s14, 0x400080
	s_addc_u32 s15, s15, 0
	s_mov_b32 m0, s34
	v_lshl_add_u64 v[144:145], s[14:15], 0, v[132:133]
	global_load_lds_dwordx4 v[144:145], off
	s_mov_b32 m0, s35
	v_lshl_add_u64 v[144:145], s[14:15], 0, v[136:137]
	global_load_lds_dwordx4 v[144:145], off
	s_waitcnt vmcnt(6)
	s_barrier
	v_mfma_f32_16x16x32_f16 v[58:61], v[196:199], v[164:167], v[58:61]
	v_mfma_f32_16x16x32_f16 v[54:57], v[204:207], v[164:167], v[54:57]
	v_mfma_f32_16x16x32_f16 v[42:45], v[196:199], v[172:175], v[42:45]
	v_mfma_f32_16x16x32_f16 v[38:41], v[204:207], v[172:175], v[38:41]
	v_mfma_f32_16x16x32_f16 v[26:29], v[196:199], v[180:183], v[26:29]
	v_mfma_f32_16x16x32_f16 v[22:25], v[204:207], v[180:183], v[22:25]
	v_mfma_f32_16x16x32_f16 v[10:13], v[196:199], v[188:191], v[10:13]
	v_mfma_f32_16x16x32_f16 v[6:9], v[204:207], v[188:191], v[6:9]
	v_mfma_f32_16x16x32_f16 v[58:61], v[200:203], v[168:171], v[58:61]
	v_mfma_f32_16x16x32_f16 v[54:57], v[208:211], v[168:171], v[54:57]
	v_mfma_f32_16x16x32_f16 v[42:45], v[200:203], v[176:179], v[42:45]
	v_mfma_f32_16x16x32_f16 v[38:41], v[208:211], v[176:179], v[38:41]
	v_mfma_f32_16x16x32_f16 v[26:29], v[200:203], v[184:187], v[26:29]
	v_mfma_f32_16x16x32_f16 v[22:25], v[208:211], v[184:187], v[22:25]
	v_mfma_f32_16x16x32_f16 v[10:13], v[200:203], v[192:195], v[10:13]
	v_mfma_f32_16x16x32_f16 v[6:9], v[208:211], v[192:195], v[6:9]
	s_add_u32 s12, s12, 0x100
	s_addc_u32 s13, s13, 0
	s_add_u32 s46, s46, 0x100
	s_addc_u32 s74, s74, 0
	s_cmp_ge_i32 s85, s5
	s_mov_b32 s14, s85
	s_barrier
	s_cbranch_scc0 .LBB0_2281
	s_branch .LBB0_2268

; #define G_STAGE(bufoff, gbase, v0, v1) do { \
;     __builtin_amdgcn_global_load_lds((const unsigned*)((const char*)(gbase) + (v0)), (LAS unsigned*)(lds + (bufoff) + ldsw), 16, 0, 0); \
;     __builtin_amdgcn_global_load_lds((const unsigned*)((const char*)(gbase) + (v1)), (LAS unsigned*)(lds + (bufoff) + ldsw + 8192), 16, 0, 0); } while (0)
; #define G_LDA(dst, b, h) do { _Pragma("unroll") for (int m = 0; m < 4; ++m) _Pragma("unroll") for (int k = 0; k < 2; ++k) dst[m][k] = *(const LAS h8*)(lds + G_SA(b, h) + aoff + m * 2048 + k * 1024); } while (0)
; #define G_LDB(dst, b, h) do { _Pragma("unroll") for (int n = 0; n < 2; ++n) _Pragma("unroll") for (int k = 0; k < 2; ++k) dst[n][k] = *(const LAS h8*)(lds + G_SB(b, h) + boff + n * 2048 + k * 1024); } while (0)
; #define G_MMA(ai, bj, At, Bt) do { __builtin_amdgcn_s_setprio(1); _Pragma("unroll") for (int m = 0; m < 4; ++m) _Pragma("unroll") for (int n = 0; n < 2; ++n) _Pragma("unroll") for (int k = 0; k < 2; ++k) \
;     acc[ai][bj][m][n] = __builtin_amdgcn_mfma_f32_16x16x32_f16(Bt[n][k], At[m][k], acc[ai][bj][m][n], 0, 0, 0); __builtin_amdgcn_s_setprio(0); } while (0)
; #define G_WAIT_V(n) asm volatile("s_waitcnt vmcnt(" #n ")" ::: "memory")
; #define G_WAIT_L(n) asm volatile("s_waitcnt lgkmcnt(" #n ")" ::: "memory")
; #define G_BAR __builtin_amdgcn_s_barrier()
; #define G_SCHED __builtin_amdgcn_sched_barrier(0)
; template <bool PERM, class Sched, class Epi>
; DI void gemm256(LAS unsigned char* lds, const Sched& S, const Epi& E, int wv_) {
;     ...
;       const bool last = (t == nt - 2);
;       const char* a1 = cA + (size_t)(t + 1) * kstep;
;       const char* a2 = last ? nA : cA + (size_t)(t + 2) * kstep;
;       const char* b2 = last ? nB : cB + (size_t)(t + 2) * kstep;
;       const char* a3 = a2 + kstep;
;       const char* b3 = b2 + kstep;
;       G_LDB(B0, 0, 0); G_SCHED; G_LDA(At, 0, 0); G_STAGE(G_SA(1, 1), a1 + chA, cvA0, cvA1);
;       G_WAIT_L(8); G_BAR; G_WAIT_L(0); G_MMA(0, 0, At, B0); G_BAR; G_SCHED;
;       G_LDB(B1, 0, 1); G_STAGE(G_SB(0, 0), b2, cvB0, cvB1);
;       G_BAR; G_WAIT_L(0); G_MMA(0, 1, At, B1); G_BAR;
;       G_LDA(At, 0, 1); G_STAGE(G_SA(0, 0), a2, cvA0, cvA1);
;       G_BAR; G_WAIT_L(0); G_MMA(1, 0, At, B0); G_BAR; G_SCHED;
;       G_STAGE(G_SB(0, 1), b2 + chB, cvB0, cvB1);
;       G_WAIT_V(6); G_BAR; G_MMA(1, 1, At, B1); G_BAR;
.LBB0_2355:
	ds_read_b128 v[132:135], v201
	ds_read_b128 v[136:139], v201 offset:1024
	s_add_i32 s85, s10, 2
	ds_read_b128 v[140:143], v201 offset:2048
	ds_read_b128 v[144:147], v201 offset:3072
	s_add_u32 s11, s8, 0xfffc0080
	s_addc_u32 s12, s9, -1
	s_cmp_eq_u32 s69, s10
	s_cselect_b32 s10, s4, s74
	s_cselect_b32 s13, s3, s12
	s_cselect_b32 s12, s2, s11
	s_cselect_b32 s11, s5, s75
	v_lshl_add_u64 v[2:3], s[8:9], 0, v[196:197]
	s_add_i32 m0, s16, 0xc000
	ds_read_b128 v[148:151], v184
	ds_read_b128 v[152:155], v184 offset:1024
	ds_read_b128 v[156:159], v184 offset:2048
	ds_read_b128 v[160:163], v184 offset:3072
	ds_read_b128 v[164:167], v184 offset:4096
	ds_read_b128 v[168:171], v184 offset:5120
	ds_read_b128 v[172:175], v184 offset:6144
	ds_read_b128 v[176:179], v184 offset:7168
	global_load_lds_dwordx4 v[2:3], off
	s_add_i32 m0, s16, 0xe000
	v_lshl_add_u64 v[2:3], s[8:9], 0, v[198:199]
	global_load_lds_dwordx4 v[2:3], off
	s_waitcnt lgkmcnt(8)
	s_barrier
	s_waitcnt lgkmcnt(0)
	s_waitcnt lgkmcnt(0)
	v_mfma_f32_16x16x32_f16 v[128:131], v[132:135], v[148:151], v[128:131]
	v_mfma_f32_16x16x32_f16 v[124:127], v[140:143], v[148:151], v[124:127]
	v_mfma_f32_16x16x32_f16 v[120:123], v[132:135], v[156:159], v[120:123]
	v_mfma_f32_16x16x32_f16 v[116:119], v[140:143], v[156:159], v[116:119]
	v_mfma_f32_16x16x32_f16 v[112:115], v[132:135], v[164:167], v[112:115]
	v_mfma_f32_16x16x32_f16 v[108:111], v[140:143], v[164:167], v[108:111]
	v_mfma_f32_16x16x32_f16 v[104:107], v[132:135], v[172:175], v[104:107]
	v_mfma_f32_16x16x32_f16 v[100:103], v[140:143], v[172:175], v[100:103]
	v_mfma_f32_16x16x32_f16 v[128:131], v[136:139], v[152:155], v[128:131]
	v_mfma_f32_16x16x32_f16 v[124:127], v[144:147], v[152:155], v[124:127]
	v_mfma_f32_16x16x32_f16 v[120:123], v[136:139], v[160:163], v[120:123]
	v_mfma_f32_16x16x32_f16 v[116:119], v[144:147], v[160:163], v[116:119]
	v_mfma_f32_16x16x32_f16 v[112:115], v[136:139], v[168:171], v[112:115]
	v_mfma_f32_16x16x32_f16 v[108:111], v[144:147], v[168:171], v[108:111]
	v_mfma_f32_16x16x32_f16 v[104:107], v[136:139], v[176:179], v[104:107]
	v_mfma_f32_16x16x32_f16 v[100:103], v[144:147], v[176:179], v[100:103]
	s_barrier
	s_mov_b32 m0, s17
	ds_read_b128 v[180:183], v239
	ds_read_b128 v[202:205], v239 offset:1024
	v_lshl_add_u64 v[214:215], s[10:11], 0, v[188:189]
	ds_read_b128 v[206:209], v239 offset:2048
	ds_read_b128 v[210:213], v239 offset:3072
	global_load_lds_dwordx4 v[214:215], off
	s_mov_b32 m0, s18
	v_lshl_add_u64 v[216:217], s[10:11], 0, v[192:193]
	global_load_lds_dwordx4 v[216:217], off
	s_barrier
	s_waitcnt lgkmcnt(0)
	s_waitcnt lgkmcnt(0)
	v_mfma_f32_16x16x32_f16 v[96:99], v[180:183], v[148:151], v[96:99]
	v_mfma_f32_16x16x32_f16 v[92:95], v[206:209], v[148:151], v[92:95]
	v_mfma_f32_16x16x32_f16 v[88:91], v[180:183], v[156:159], v[88:91]
	v_mfma_f32_16x16x32_f16 v[84:87], v[206:209], v[156:159], v[84:87]
	v_mfma_f32_16x16x32_f16 v[80:83], v[180:183], v[164:167], v[80:83]
	v_mfma_f32_16x16x32_f16 v[76:79], v[206:209], v[164:167], v[76:79]
	v_mfma_f32_16x16x32_f16 v[72:75], v[180:183], v[172:175], v[72:75]
	v_mfma_f32_16x16x32_f16 v[68:71], v[206:209], v[172:175], v[68:71]
	v_mfma_f32_16x16x32_f16 v[96:99], v[202:205], v[152:155], v[96:99]
	v_mfma_f32_16x16x32_f16 v[92:95], v[210:213], v[152:155], v[92:95]
	v_mfma_f32_16x16x32_f16 v[88:91], v[202:205], v[160:163], v[88:91]
	v_mfma_f32_16x16x32_f16 v[84:87], v[210:213], v[160:163], v[84:87]
	v_mfma_f32_16x16x32_f16 v[80:83], v[202:205], v[168:171], v[80:83]
	v_mfma_f32_16x16x32_f16 v[76:79], v[210:213], v[168:171], v[76:79]
	v_mfma_f32_16x16x32_f16 v[72:75], v[202:205], v[176:179], v[72:75]
	v_mfma_f32_16x16x32_f16 v[68:71], v[210:213], v[176:179], v[68:71]
	s_mov_b32 m0, s16
	v_lshl_add_u64 v[218:219], s[12:13], 0, v[186:187]
	s_barrier
	ds_read_b128 v[148:151], v184 offset:16384
	ds_read_b128 v[152:155], v184 offset:17408
	ds_read_b128 v[156:159], v184 offset:18432
	ds_read_b128 v[160:163], v184 offset:19456
	ds_read_b128 v[164:167], v184 offset:20480
	ds_read_b128 v[168:171], v184 offset:21504
	ds_read_b128 v[172:175], v184 offset:22528
	ds_read_b128 v[176:179], v184 offset:23552
	global_load_lds_dwordx4 v[218:219], off
	s_mov_b32 m0, s19
	v_lshl_add_u64 v[220:221], s[12:13], 0, v[190:191]
	global_load_lds_dwordx4 v[220:221], off
	s_barrier
	s_waitcnt lgkmcnt(0)
	s_waitcnt lgkmcnt(0)
	v_mfma_f32_16x16x32_f16 v[64:67], v[132:135], v[148:151], v[64:67]
	v_mfma_f32_16x16x32_f16 v[60:63], v[140:143], v[148:151], v[60:63]
	v_mfma_f32_16x16x32_f16 v[56:59], v[132:135], v[156:159], v[56:59]
	v_mfma_f32_16x16x32_f16 v[52:55], v[140:143], v[156:159], v[52:55]
	v_mfma_f32_16x16x32_f16 v[48:51], v[132:135], v[164:167], v[48:51]
	v_mfma_f32_16x16x32_f16 v[44:47], v[140:143], v[164:167], v[44:47]
	v_mfma_f32_16x16x32_f16 v[40:43], v[132:135], v[172:175], v[40:43]
	v_mfma_f32_16x16x32_f16 v[36:39], v[140:143], v[172:175], v[36:39]
	v_mfma_f32_16x16x32_f16 v[64:67], v[136:139], v[152:155], v[64:67]
	v_mfma_f32_16x16x32_f16 v[60:63], v[144:147], v[152:155], v[60:63]
	v_mfma_f32_16x16x32_f16 v[56:59], v[136:139], v[160:163], v[56:59]
	v_mfma_f32_16x16x32_f16 v[52:55], v[144:147], v[160:163], v[52:55]
	v_mfma_f32_16x16x32_f16 v[48:51], v[136:139], v[168:171], v[48:51]
	v_mfma_f32_16x16x32_f16 v[44:47], v[144:147], v[168:171], v[44:47]
	v_mfma_f32_16x16x32_f16 v[40:43], v[136:139], v[176:179], v[40:43]
	v_mfma_f32_16x16x32_f16 v[36:39], v[144:147], v[176:179], v[36:39]
	s_barrier
	s_add_u32 s40, s10, 0x10000
	s_addc_u32 s41, s11, 0
	s_mov_b32 m0, s20
	v_lshl_add_u64 v[2:3], s[40:41], 0, v[188:189]
	global_load_lds_dwordx4 v[2:3], off
	s_mov_b32 m0, s21
	v_lshl_add_u64 v[2:3], s[40:41], 0, v[192:193]
	global_load_lds_dwordx4 v[2:3], off
	s_waitcnt vmcnt(6)
	s_barrier
; #define G_STAGE(bufoff, gbase, v0, v1) do { \
;     __builtin_amdgcn_global_load_lds((const unsigned*)((const char*)(gbase) + (v0)), (LAS unsigned*)(lds + (bufoff) + ldsw), 16, 0, 0); \
;     __builtin_amdgcn_global_load_lds((const unsigned*)((const char*)(gbase) + (v1)), (LAS unsigned*)(lds + (bufoff) + ldsw + 8192), 16, 0, 0); } while (0)
; #define G_LDA(dst, b, h) do { _Pragma("unroll") for (int m = 0; m < 4; ++m) _Pragma("unroll") for (int k = 0; k < 2; ++k) dst[m][k] = *(const LAS h8*)(lds + G_SA(b, h) + aoff + m * 2048 + k * 1024); } while (0)
; #define G_LDB(dst, b, h) do { _Pragma("unroll") for (int n = 0; n < 2; ++n) _Pragma("unroll") for (int k = 0; k < 2; ++k) dst[n][k] = *(const LAS h8*)(lds + G_SB(b, h) + boff + n * 2048 + k * 1024); } while (0)
; #define G_MMA(ai, bj, At, Bt) do { __builtin_amdgcn_s_setprio(1); _Pragma("unroll") for (int m = 0; m < 4; ++m) _Pragma("unroll") for (int n = 0; n < 2; ++n) _Pragma("unroll") for (int k = 0; k < 2; ++k) \
;     acc[ai][bj][m][n] = __builtin_amdgcn_mfma_f32_16x16x32_f16(Bt[n][k], At[m][k], acc[ai][bj][m][n], 0, 0, 0); __builtin_amdgcn_s_setprio(0); } while (0)
; #define G_WAIT_V(n) asm volatile("s_waitcnt vmcnt(" #n ")" ::: "memory")
; #define G_WAIT_L(n) asm volatile("s_waitcnt lgkmcnt(" #n ")" ::: "memory")
; #define G_BAR __builtin_amdgcn_s_barrier()
; #define G_SCHED __builtin_amdgcn_sched_barrier(0)
; template <bool PERM, class Sched, class Epi>
; DI void gemm256(LAS unsigned char* lds, const Sched& S, const Epi& E, int wv_) {
;     ...
;       G_WAIT_V(6); G_BAR; G_MMA(1, 1, At, B1); G_BAR;
;       G_LDB(B0, 1, 0); G_SCHED; G_LDA(At, 1, 0); G_STAGE(G_SA(0, 1), a2 + chA, cvA0, cvA1);
;       G_WAIT_L(8); G_BAR; G_WAIT_L(0); G_MMA(0, 0, At, B0); G_BAR; G_SCHED;
;       G_LDB(B1, 1, 1); G_STAGE(G_SB(1, 0), b3, cvB0, cvB1);
	v_mfma_f32_16x16x32_f16 v[32:35], v[180:183], v[148:151], v[32:35]
	v_mfma_f32_16x16x32_f16 v[28:31], v[206:209], v[148:151], v[28:31]
	v_mfma_f32_16x16x32_f16 v[24:27], v[180:183], v[156:159], v[24:27]
	v_mfma_f32_16x16x32_f16 v[20:23], v[206:209], v[156:159], v[20:23]
	v_mfma_f32_16x16x32_f16 v[16:19], v[180:183], v[164:167], v[16:19]
	v_mfma_f32_16x16x32_f16 v[12:15], v[206:209], v[164:167], v[12:15]
	v_mfma_f32_16x16x32_f16 v[8:11], v[180:183], v[172:175], v[8:11]
	v_mfma_f32_16x16x32_f16 v[2:5], v[206:209], v[172:175], v[4:7]
	v_mfma_f32_16x16x32_f16 v[32:35], v[202:205], v[152:155], v[32:35]
	v_mfma_f32_16x16x32_f16 v[28:31], v[210:213], v[152:155], v[28:31]
	v_mfma_f32_16x16x32_f16 v[24:27], v[202:205], v[160:163], v[24:27]
	v_mfma_f32_16x16x32_f16 v[20:23], v[210:213], v[160:163], v[20:23]
	v_mfma_f32_16x16x32_f16 v[16:19], v[202:205], v[168:171], v[16:19]
	v_mfma_f32_16x16x32_f16 v[12:15], v[210:213], v[168:171], v[12:15]
	v_mfma_f32_16x16x32_f16 v[8:11], v[202:205], v[176:179], v[8:11]
	v_mfma_f32_16x16x32_f16 v[2:5], v[210:213], v[176:179], v[2:5]
	s_barrier
	ds_read_b128 v[132:135], v243
	ds_read_b128 v[136:139], v243 offset:1024
	ds_read_b128 v[140:143], v243 offset:2048
	ds_read_b128 v[144:147], v243 offset:3072
	s_add_u32 s12, s12, 0x40000
	s_addc_u32 s13, s13, 0
	s_mov_b32 m0, s22
	v_lshl_add_u64 v[6:7], s[12:13], 0, v[186:187]
	ds_read_b128 v[148:151], v184 offset:32768
	ds_read_b128 v[152:155], v184 offset:33792
	ds_read_b128 v[156:159], v184 offset:34816
	ds_read_b128 v[160:163], v184 offset:35840
	ds_read_b128 v[164:167], v184 offset:36864
	ds_read_b128 v[168:171], v184 offset:37888
	ds_read_b128 v[172:175], v184 offset:38912
	ds_read_b128 v[176:179], v184 offset:39936
	global_load_lds_dwordx4 v[6:7], off
	s_mov_b32 m0, s23
	v_lshl_add_u64 v[6:7], s[12:13], 0, v[190:191]
	global_load_lds_dwordx4 v[6:7], off
	s_waitcnt lgkmcnt(8)
	s_barrier
	s_waitcnt lgkmcnt(0)
	s_waitcnt lgkmcnt(0)
	v_mfma_f32_16x16x32_f16 v[128:131], v[132:135], v[148:151], v[128:131]
	v_mfma_f32_16x16x32_f16 v[124:127], v[140:143], v[148:151], v[124:127]
	v_mfma_f32_16x16x32_f16 v[120:123], v[132:135], v[156:159], v[120:123]
	v_mfma_f32_16x16x32_f16 v[116:119], v[140:143], v[156:159], v[116:119]
	v_mfma_f32_16x16x32_f16 v[112:115], v[132:135], v[164:167], v[112:115]
	v_mfma_f32_16x16x32_f16 v[108:111], v[140:143], v[164:167], v[108:111]
	v_mfma_f32_16x16x32_f16 v[104:107], v[132:135], v[172:175], v[104:107]
	v_mfma_f32_16x16x32_f16 v[100:103], v[140:143], v[172:175], v[100:103]
	v_mfma_f32_16x16x32_f16 v[128:131], v[136:139], v[152:155], v[128:131]
	v_mfma_f32_16x16x32_f16 v[124:127], v[144:147], v[152:155], v[124:127]
	v_mfma_f32_16x16x32_f16 v[120:123], v[136:139], v[160:163], v[120:123]
	v_mfma_f32_16x16x32_f16 v[116:119], v[144:147], v[160:163], v[116:119]
	v_mfma_f32_16x16x32_f16 v[112:115], v[136:139], v[168:171], v[112:115]
	v_mfma_f32_16x16x32_f16 v[108:111], v[144:147], v[168:171], v[108:111]
	v_mfma_f32_16x16x32_f16 v[104:107], v[136:139], v[176:179], v[104:107]
	v_mfma_f32_16x16x32_f16 v[100:103], v[144:147], v[176:179], v[100:103]
	s_barrier
	ds_read_b128 v[180:183], v244
	ds_read_b128 v[202:205], v244 offset:1024
	s_mov_b32 m0, s26
	ds_read_b128 v[206:209], v244 offset:2048
	ds_read_b128 v[210:213], v244 offset:3072
	v_lshl_add_u64 v[6:7], v[214:215], 0, s[86:87]
	global_load_lds_dwordx4 v[6:7], off
	s_mov_b32 m0, s27
	v_lshl_add_u64 v[6:7], v[216:217], 0, s[86:87]
	global_load_lds_dwordx4 v[6:7], off
	s_barrier
; #define G_STAGE(bufoff, gbase, v0, v1) do { \
;     __builtin_amdgcn_global_load_lds((const unsigned*)((const char*)(gbase) + (v0)), (LAS unsigned*)(lds + (bufoff) + ldsw), 16, 0, 0); \
;     __builtin_amdgcn_global_load_lds((const unsigned*)((const char*)(gbase) + (v1)), (LAS unsigned*)(lds + (bufoff) + ldsw + 8192), 16, 0, 0); } while (0)
; #define G_LDA(dst, b, h) do { _Pragma("unroll") for (int m = 0; m < 4; ++m) _Pragma("unroll") for (int k = 0; k < 2; ++k) dst[m][k] = *(const LAS h8*)(lds + G_SA(b, h) + aoff + m * 2048 + k * 1024); } while (0)
; #define G_MMA(ai, bj, At, Bt) do { __builtin_amdgcn_s_setprio(1); _Pragma("unroll") for (int m = 0; m < 4; ++m) _Pragma("unroll") for (int n = 0; n < 2; ++n) _Pragma("unroll") for (int k = 0; k < 2; ++k) \
;     acc[ai][bj][m][n] = __builtin_amdgcn_mfma_f32_16x16x32_f16(Bt[n][k], At[m][k], acc[ai][bj][m][n], 0, 0, 0); __builtin_amdgcn_s_setprio(0); } while (0)
; #define G_WAIT_V(n) asm volatile("s_waitcnt vmcnt(" #n ")" ::: "memory")
; #define G_WAIT_L(n) asm volatile("s_waitcnt lgkmcnt(" #n ")" ::: "memory")
; #define G_BAR __builtin_amdgcn_s_barrier()
; #define G_SCHED __builtin_amdgcn_sched_barrier(0)
; template <bool PERM, class Sched, class Epi>
; DI void gemm256(LAS unsigned char* lds, const Sched& S, const Epi& E, int wv_) {
;     ...
;       G_BAR; G_WAIT_L(0); G_MMA(0, 1, At, B1); G_BAR;
;       G_LDA(At, 1, 1); G_STAGE(G_SA(1, 0), a3, cvA0, cvA1);
;       G_BAR; G_WAIT_L(0); G_MMA(1, 0, At, B0); G_BAR; G_SCHED;
;       G_STAGE(G_SB(1, 1), b3 + chB, cvB0, cvB1);
;       G_WAIT_V(6); G_BAR; G_MMA(1, 1, At, B1); G_BAR;
;     }
	s_waitcnt lgkmcnt(0)
	s_waitcnt lgkmcnt(0)
	v_mfma_f32_16x16x32_f16 v[96:99], v[180:183], v[148:151], v[96:99]
	v_mfma_f32_16x16x32_f16 v[92:95], v[206:209], v[148:151], v[92:95]
	v_mfma_f32_16x16x32_f16 v[88:91], v[180:183], v[156:159], v[88:91]
	v_mfma_f32_16x16x32_f16 v[84:87], v[206:209], v[156:159], v[84:87]
	v_mfma_f32_16x16x32_f16 v[80:83], v[180:183], v[164:167], v[80:83]
	v_mfma_f32_16x16x32_f16 v[76:79], v[206:209], v[164:167], v[76:79]
	v_mfma_f32_16x16x32_f16 v[72:75], v[180:183], v[172:175], v[72:75]
	v_mfma_f32_16x16x32_f16 v[68:71], v[206:209], v[172:175], v[68:71]
	v_mfma_f32_16x16x32_f16 v[96:99], v[202:205], v[152:155], v[96:99]
	v_mfma_f32_16x16x32_f16 v[92:95], v[210:213], v[152:155], v[92:95]
	v_mfma_f32_16x16x32_f16 v[88:91], v[202:205], v[160:163], v[88:91]
	v_mfma_f32_16x16x32_f16 v[84:87], v[210:213], v[160:163], v[84:87]
	v_mfma_f32_16x16x32_f16 v[80:83], v[202:205], v[168:171], v[80:83]
	v_mfma_f32_16x16x32_f16 v[76:79], v[210:213], v[168:171], v[76:79]
	v_mfma_f32_16x16x32_f16 v[72:75], v[202:205], v[176:179], v[72:75]
	v_mfma_f32_16x16x32_f16 v[68:71], v[210:213], v[176:179], v[68:71]
	s_mov_b32 m0, s28
	v_lshl_add_u64 v[6:7], v[218:219], 0, s[86:87]
	s_barrier
	ds_read_b128 v[148:151], v184 offset:49152
	ds_read_b128 v[152:155], v184 offset:50176
	ds_read_b128 v[156:159], v184 offset:51200
	ds_read_b128 v[160:163], v184 offset:52224
	ds_read_b128 v[164:167], v184 offset:53248
	ds_read_b128 v[168:171], v184 offset:54272
	ds_read_b128 v[172:175], v184 offset:55296
	ds_read_b128 v[176:179], v184 offset:56320
	global_load_lds_dwordx4 v[6:7], off
	s_mov_b32 m0, s29
	v_lshl_add_u64 v[6:7], v[220:221], 0, s[86:87]
	global_load_lds_dwordx4 v[6:7], off
	s_barrier
	s_waitcnt lgkmcnt(0)
	s_waitcnt lgkmcnt(0)
	v_mfma_f32_16x16x32_f16 v[64:67], v[132:135], v[148:151], v[64:67]
	v_mfma_f32_16x16x32_f16 v[60:63], v[140:143], v[148:151], v[60:63]
	v_mfma_f32_16x16x32_f16 v[56:59], v[132:135], v[156:159], v[56:59]
	v_mfma_f32_16x16x32_f16 v[52:55], v[140:143], v[156:159], v[52:55]
	v_mfma_f32_16x16x32_f16 v[48:51], v[132:135], v[164:167], v[48:51]
	v_mfma_f32_16x16x32_f16 v[44:47], v[140:143], v[164:167], v[44:47]
	v_mfma_f32_16x16x32_f16 v[40:43], v[132:135], v[172:175], v[40:43]
	v_mfma_f32_16x16x32_f16 v[36:39], v[140:143], v[172:175], v[36:39]
	v_mfma_f32_16x16x32_f16 v[64:67], v[136:139], v[152:155], v[64:67]
	v_mfma_f32_16x16x32_f16 v[60:63], v[144:147], v[152:155], v[60:63]
	v_mfma_f32_16x16x32_f16 v[56:59], v[136:139], v[160:163], v[56:59]
	v_mfma_f32_16x16x32_f16 v[52:55], v[144:147], v[160:163], v[52:55]
	v_mfma_f32_16x16x32_f16 v[48:51], v[136:139], v[168:171], v[48:51]
	v_mfma_f32_16x16x32_f16 v[44:47], v[144:147], v[168:171], v[44:47]
	v_mfma_f32_16x16x32_f16 v[40:43], v[136:139], v[176:179], v[40:43]
	v_mfma_f32_16x16x32_f16 v[36:39], v[144:147], v[176:179], v[36:39]
	s_barrier
	s_add_u32 s10, s10, 0x10080
	s_addc_u32 s11, s11, 0
	s_mov_b32 m0, s30
	v_lshl_add_u64 v[6:7], s[10:11], 0, v[188:189]
	global_load_lds_dwordx4 v[6:7], off
	s_mov_b32 m0, s31
	v_lshl_add_u64 v[6:7], s[10:11], 0, v[192:193]
	global_load_lds_dwordx4 v[6:7], off
	s_waitcnt vmcnt(6)
	s_barrier
	v_mfma_f32_16x16x32_f16 v[32:35], v[180:183], v[148:151], v[32:35]
	v_mfma_f32_16x16x32_f16 v[28:31], v[206:209], v[148:151], v[28:31]
	v_mfma_f32_16x16x32_f16 v[24:27], v[180:183], v[156:159], v[24:27]
	v_mfma_f32_16x16x32_f16 v[20:23], v[206:209], v[156:159], v[20:23]
	v_mfma_f32_16x16x32_f16 v[16:19], v[180:183], v[164:167], v[16:19]
	v_mfma_f32_16x16x32_f16 v[12:15], v[206:209], v[164:167], v[12:15]
	v_mfma_f32_16x16x32_f16 v[6:9], v[180:183], v[172:175], v[8:11]
	v_mfma_f32_16x16x32_f16 v[2:5], v[206:209], v[172:175], v[2:5]
	v_mfma_f32_16x16x32_f16 v[32:35], v[202:205], v[152:155], v[32:35]
	v_mfma_f32_16x16x32_f16 v[28:31], v[210:213], v[152:155], v[28:31]
	v_mfma_f32_16x16x32_f16 v[24:27], v[202:205], v[160:163], v[24:27]
	v_mfma_f32_16x16x32_f16 v[20:23], v[210:213], v[160:163], v[20:23]
	v_mfma_f32_16x16x32_f16 v[16:19], v[202:205], v[168:171], v[16:19]
	v_mfma_f32_16x16x32_f16 v[12:15], v[210:213], v[168:171], v[12:15]
	v_mfma_f32_16x16x32_f16 v[8:11], v[202:205], v[176:179], v[6:9]
	v_mfma_f32_16x16x32_f16 v[4:7], v[210:213], v[176:179], v[2:5]
	s_add_u32 s8, s8, 0x100
	s_addc_u32 s9, s9, 0
	s_add_u32 s74, s74, 0x100
	s_addc_u32 s75, s75, 0
	s_cmp_ge_i32 s85, s46
	s_mov_b32 s10, s85
	s_barrier
	s_cbranch_scc0 .LBB0_2355

; #define G_STAGE(bufoff, gbase, v0, v1) do { \
;     __builtin_amdgcn_global_load_lds((const unsigned*)((const char*)(gbase) + (v0)), (LAS unsigned*)(lds + (bufoff) + ldsw), 16, 0, 0); \
;     __builtin_amdgcn_global_load_lds((const unsigned*)((const char*)(gbase) + (v1)), (LAS unsigned*)(lds + (bufoff) + ldsw + 8192), 16, 0, 0); } while (0)
; #define G_LDA(dst, b, h) do { _Pragma("unroll") for (int m = 0; m < 4; ++m) _Pragma("unroll") for (int k = 0; k < 2; ++k) dst[m][k] = *(const LAS h8*)(lds + G_SA(b, h) + aoff + m * 2048 + k * 1024); } while (0)
; #define G_LDB(dst, b, h) do { _Pragma("unroll") for (int n = 0; n < 2; ++n) _Pragma("unroll") for (int k = 0; k < 2; ++k) dst[n][k] = *(const LAS h8*)(lds + G_SB(b, h) + boff + n * 2048 + k * 1024); } while (0)
; #define G_MMA(ai, bj, At, Bt) do { __builtin_amdgcn_s_setprio(1); _Pragma("unroll") for (int m = 0; m < 4; ++m) _Pragma("unroll") for (int n = 0; n < 2; ++n) _Pragma("unroll") for (int k = 0; k < 2; ++k) \
;     acc[ai][bj][m][n] = __builtin_amdgcn_mfma_f32_16x16x32_f16(Bt[n][k], At[m][k], acc[ai][bj][m][n], 0, 0, 0); __builtin_amdgcn_s_setprio(0); } while (0)
; #define G_WAIT_V(n) asm volatile("s_waitcnt vmcnt(" #n ")" ::: "memory")
; #define G_WAIT_L(n) asm volatile("s_waitcnt lgkmcnt(" #n ")" ::: "memory")
; #define G_BAR __builtin_amdgcn_s_barrier()
; #define G_SCHED __builtin_amdgcn_sched_barrier(0)
; template <bool PERM, class Sched, class Epi>
; DI void gemm256(LAS unsigned char* lds, const Sched& S, const Epi& E, int wv_) {
;     ...
;       const bool last = (t == nt - 2);
;       const char* a1 = cA + (size_t)(t + 1) * kstep;
;       const char* a2 = last ? nA : cA + (size_t)(t + 2) * kstep;
;       const char* b2 = last ? nB : cB + (size_t)(t + 2) * kstep;
;       const char* a3 = a2 + kstep;
;       const char* b3 = b2 + kstep;
;       G_LDB(B0, 0, 0); G_SCHED; G_LDA(At, 0, 0); G_STAGE(G_SA(1, 1), a1 + chA, cvA0, cvA1);
;       G_WAIT_L(8); G_BAR; G_WAIT_L(0); G_MMA(0, 0, At, B0); G_BAR; G_SCHED;
;       G_LDB(B1, 0, 1); G_STAGE(G_SB(0, 0), b2, cvB0, cvB1);
;       G_BAR; G_WAIT_L(0); G_MMA(0, 1, At, B1); G_BAR;
;       G_LDA(At, 0, 1); G_STAGE(G_SA(0, 0), a2, cvA0, cvA1);
;       G_BAR; G_WAIT_L(0); G_MMA(1, 0, At, B0); G_BAR; G_SCHED;
;       G_STAGE(G_SB(0, 1), b2 + chB, cvB0, cvB1);
;       G_WAIT_V(6); G_BAR; G_MMA(1, 1, At, B1); G_BAR;
.LBB0_2433:
	s_waitcnt vmcnt(0)
	s_add_i32 s74, s20, 2
	ds_read_b128 v[130:133], v216
	ds_read_b128 v[134:137], v216 offset:1024
	ds_read_b128 v[138:141], v216 offset:2048
	ds_read_b128 v[142:145], v216 offset:3072
	s_add_u32 s21, s18, 0xfffc0080
	s_addc_u32 s22, s19, -1
	s_cmp_eq_u32 vcc_lo, s20
	s_cselect_b32 s20, s85, s75
	s_cselect_b32 s23, s9, s22
	s_cselect_b32 s22, s27, s21
	s_cselect_b32 s21, s56, s46
	v_lshl_add_u64 v[192:193], s[18:19], 0, v[158:159]
	s_add_i32 m0, s31, 0xc000
	ds_read_b128 v[146:149], v1
	ds_read_b128 v[164:167], v1 offset:1024
	ds_read_b128 v[168:171], v1 offset:2048
	ds_read_b128 v[172:175], v1 offset:3072
	ds_read_b128 v[176:179], v1 offset:4096
	ds_read_b128 v[180:183], v1 offset:5120
	ds_read_b128 v[184:187], v1 offset:6144
	ds_read_b128 v[188:191], v1 offset:7168
	global_load_lds_dwordx4 v[192:193], off
	s_add_i32 m0, s31, 0xe000
	v_lshl_add_u64 v[192:193], s[18:19], 0, v[160:161]
	global_load_lds_dwordx4 v[192:193], off
	s_waitcnt lgkmcnt(8)
	s_barrier
	s_waitcnt lgkmcnt(0)
	s_waitcnt lgkmcnt(0)
	v_mfma_f32_16x16x32_f16 v[126:129], v[130:133], v[146:149], v[126:129]
	v_mfma_f32_16x16x32_f16 v[122:125], v[138:141], v[146:149], v[122:125]
	v_mfma_f32_16x16x32_f16 v[110:113], v[130:133], v[168:171], v[110:113]
	v_mfma_f32_16x16x32_f16 v[106:109], v[138:141], v[168:171], v[106:109]
	v_mfma_f32_16x16x32_f16 v[94:97], v[130:133], v[176:179], v[94:97]
	v_mfma_f32_16x16x32_f16 v[90:93], v[138:141], v[176:179], v[90:93]
	v_mfma_f32_16x16x32_f16 v[78:81], v[130:133], v[184:187], v[78:81]
	v_mfma_f32_16x16x32_f16 v[74:77], v[138:141], v[184:187], v[74:77]
	v_mfma_f32_16x16x32_f16 v[126:129], v[134:137], v[164:167], v[126:129]
	v_mfma_f32_16x16x32_f16 v[122:125], v[142:145], v[164:167], v[122:125]
	v_mfma_f32_16x16x32_f16 v[110:113], v[134:137], v[172:175], v[110:113]
	v_mfma_f32_16x16x32_f16 v[106:109], v[142:145], v[172:175], v[106:109]
	v_mfma_f32_16x16x32_f16 v[94:97], v[134:137], v[180:183], v[94:97]
	v_mfma_f32_16x16x32_f16 v[90:93], v[142:145], v[180:183], v[90:93]
	v_mfma_f32_16x16x32_f16 v[78:81], v[134:137], v[188:191], v[78:81]
	v_mfma_f32_16x16x32_f16 v[74:77], v[142:145], v[188:191], v[74:77]
	s_barrier
	s_mov_b32 m0, s34
	ds_read_b128 v[192:195], v217
	ds_read_b128 v[196:199], v217 offset:1024
	v_lshl_add_u64 v[208:209], s[20:21], 0, v[150:151]
	ds_read_b128 v[200:203], v217 offset:2048
	ds_read_b128 v[204:207], v217 offset:3072
	global_load_lds_dwordx4 v[208:209], off
	s_mov_b32 m0, s35
	v_lshl_add_u64 v[210:211], s[20:21], 0, v[152:153]
	global_load_lds_dwordx4 v[210:211], off
	s_barrier
	s_waitcnt lgkmcnt(0)
	s_waitcnt lgkmcnt(0)
	v_mfma_f32_16x16x32_f16 v[118:121], v[192:195], v[146:149], v[118:121]
	v_mfma_f32_16x16x32_f16 v[114:117], v[200:203], v[146:149], v[114:117]
	v_mfma_f32_16x16x32_f16 v[102:105], v[192:195], v[168:171], v[102:105]
	v_mfma_f32_16x16x32_f16 v[98:101], v[200:203], v[168:171], v[98:101]
	v_mfma_f32_16x16x32_f16 v[86:89], v[192:195], v[176:179], v[86:89]
	v_mfma_f32_16x16x32_f16 v[82:85], v[200:203], v[176:179], v[82:85]
	v_mfma_f32_16x16x32_f16 v[70:73], v[192:195], v[184:187], v[70:73]
	v_mfma_f32_16x16x32_f16 v[66:69], v[200:203], v[184:187], v[66:69]
	v_mfma_f32_16x16x32_f16 v[118:121], v[196:199], v[164:167], v[118:121]
	v_mfma_f32_16x16x32_f16 v[114:117], v[204:207], v[164:167], v[114:117]
	v_mfma_f32_16x16x32_f16 v[102:105], v[196:199], v[172:175], v[102:105]
	v_mfma_f32_16x16x32_f16 v[98:101], v[204:207], v[172:175], v[98:101]
	v_mfma_f32_16x16x32_f16 v[86:89], v[196:199], v[180:183], v[86:89]
	v_mfma_f32_16x16x32_f16 v[82:85], v[204:207], v[180:183], v[82:85]
	v_mfma_f32_16x16x32_f16 v[70:73], v[196:199], v[188:191], v[70:73]
	v_mfma_f32_16x16x32_f16 v[66:69], v[204:207], v[188:191], v[66:69]
	s_mov_b32 m0, s31
	v_lshl_add_u64 v[212:213], s[22:23], 0, v[150:151]
	s_barrier
	ds_read_b128 v[146:149], v1 offset:16384
	ds_read_b128 v[164:167], v1 offset:17408
	ds_read_b128 v[168:171], v1 offset:18432
	ds_read_b128 v[172:175], v1 offset:19456
	ds_read_b128 v[176:179], v1 offset:20480
	ds_read_b128 v[180:183], v1 offset:21504
	ds_read_b128 v[184:187], v1 offset:22528
	ds_read_b128 v[188:191], v1 offset:23552
	global_load_lds_dwordx4 v[212:213], off
	s_mov_b32 m0, s36
	v_lshl_add_u64 v[214:215], s[22:23], 0, v[152:153]
	global_load_lds_dwordx4 v[214:215], off
	s_barrier
	s_waitcnt lgkmcnt(0)
	s_waitcnt lgkmcnt(0)
	v_mfma_f32_16x16x32_f16 v[62:65], v[130:133], v[146:149], v[62:65]
	v_mfma_f32_16x16x32_f16 v[58:61], v[138:141], v[146:149], v[58:61]
	v_mfma_f32_16x16x32_f16 v[46:49], v[130:133], v[168:171], v[46:49]
	v_mfma_f32_16x16x32_f16 v[42:45], v[138:141], v[168:171], v[42:45]
	v_mfma_f32_16x16x32_f16 v[30:33], v[130:133], v[176:179], v[30:33]
	v_mfma_f32_16x16x32_f16 v[26:29], v[138:141], v[176:179], v[26:29]
	v_mfma_f32_16x16x32_f16 v[14:17], v[130:133], v[184:187], v[14:17]
	v_mfma_f32_16x16x32_f16 v[10:13], v[138:141], v[184:187], v[10:13]
	v_mfma_f32_16x16x32_f16 v[62:65], v[134:137], v[164:167], v[62:65]
	v_mfma_f32_16x16x32_f16 v[58:61], v[142:145], v[164:167], v[58:61]
	v_mfma_f32_16x16x32_f16 v[46:49], v[134:137], v[172:175], v[46:49]
	v_mfma_f32_16x16x32_f16 v[42:45], v[142:145], v[172:175], v[42:45]
	v_mfma_f32_16x16x32_f16 v[30:33], v[134:137], v[180:183], v[30:33]
	v_mfma_f32_16x16x32_f16 v[26:29], v[142:145], v[180:183], v[26:29]
	v_mfma_f32_16x16x32_f16 v[14:17], v[134:137], v[188:191], v[14:17]
	v_mfma_f32_16x16x32_f16 v[10:13], v[142:145], v[188:191], v[10:13]
	s_barrier
	s_add_u32 s40, s20, 0x40000
	s_addc_u32 s41, s21, 0
	s_mov_b32 m0, s37
	v_lshl_add_u64 v[130:131], s[40:41], 0, v[150:151]
	global_load_lds_dwordx4 v[130:131], off
	s_mov_b32 m0, s58
	v_lshl_add_u64 v[130:131], s[40:41], 0, v[152:153]
	global_load_lds_dwordx4 v[130:131], off
	s_waitcnt vmcnt(6)
	s_barrier
; #define G_STAGE(bufoff, gbase, v0, v1) do { \
;     __builtin_amdgcn_global_load_lds((const unsigned*)((const char*)(gbase) + (v0)), (LAS unsigned*)(lds + (bufoff) + ldsw), 16, 0, 0); \
;     __builtin_amdgcn_global_load_lds((const unsigned*)((const char*)(gbase) + (v1)), (LAS unsigned*)(lds + (bufoff) + ldsw + 8192), 16, 0, 0); } while (0)
; #define G_LDA(dst, b, h) do { _Pragma("unroll") for (int m = 0; m < 4; ++m) _Pragma("unroll") for (int k = 0; k < 2; ++k) dst[m][k] = *(const LAS h8*)(lds + G_SA(b, h) + aoff + m * 2048 + k * 1024); } while (0)
; #define G_LDB(dst, b, h) do { _Pragma("unroll") for (int n = 0; n < 2; ++n) _Pragma("unroll") for (int k = 0; k < 2; ++k) dst[n][k] = *(const LAS h8*)(lds + G_SB(b, h) + boff + n * 2048 + k * 1024); } while (0)
; #define G_MMA(ai, bj, At, Bt) do { __builtin_amdgcn_s_setprio(1); _Pragma("unroll") for (int m = 0; m < 4; ++m) _Pragma("unroll") for (int n = 0; n < 2; ++n) _Pragma("unroll") for (int k = 0; k < 2; ++k) \
;     acc[ai][bj][m][n] = __builtin_amdgcn_mfma_f32_16x16x32_f16(Bt[n][k], At[m][k], acc[ai][bj][m][n], 0, 0, 0); __builtin_amdgcn_s_setprio(0); } while (0)
; #define G_WAIT_V(n) asm volatile("s_waitcnt vmcnt(" #n ")" ::: "memory")
; #define G_WAIT_L(n) asm volatile("s_waitcnt lgkmcnt(" #n ")" ::: "memory")
; #define G_BAR __builtin_amdgcn_s_barrier()
; #define G_SCHED __builtin_amdgcn_sched_barrier(0)
; template <bool PERM, class Sched, class Epi>
; DI void gemm256(LAS unsigned char* lds, const Sched& S, const Epi& E, int wv_) {
;     ...
;       G_WAIT_V(6); G_BAR; G_MMA(1, 1, At, B1); G_BAR;
;       G_LDB(B0, 1, 0); G_SCHED; G_LDA(At, 1, 0); G_STAGE(G_SA(0, 1), a2 + chA, cvA0, cvA1);
;       G_WAIT_L(8); G_BAR; G_WAIT_L(0); G_MMA(0, 0, At, B0); G_BAR; G_SCHED;
;       G_LDB(B1, 1, 1); G_STAGE(G_SB(1, 0), b3, cvB0, cvB1);
	v_mfma_f32_16x16x32_f16 v[54:57], v[192:195], v[146:149], v[54:57]
	v_mfma_f32_16x16x32_f16 v[50:53], v[200:203], v[146:149], v[50:53]
	v_mfma_f32_16x16x32_f16 v[38:41], v[192:195], v[168:171], v[38:41]
	v_mfma_f32_16x16x32_f16 v[34:37], v[200:203], v[168:171], v[34:37]
	v_mfma_f32_16x16x32_f16 v[22:25], v[192:195], v[176:179], v[22:25]
	v_mfma_f32_16x16x32_f16 v[18:21], v[200:203], v[176:179], v[18:21]
	v_mfma_f32_16x16x32_f16 v[6:9], v[192:195], v[184:187], v[6:9]
	v_mfma_f32_16x16x32_f16 v[2:5], v[200:203], v[184:187], v[2:5]
	v_mfma_f32_16x16x32_f16 v[54:57], v[196:199], v[164:167], v[54:57]
	v_mfma_f32_16x16x32_f16 v[50:53], v[204:207], v[164:167], v[50:53]
	v_mfma_f32_16x16x32_f16 v[38:41], v[196:199], v[172:175], v[38:41]
	v_mfma_f32_16x16x32_f16 v[34:37], v[204:207], v[172:175], v[34:37]
	v_mfma_f32_16x16x32_f16 v[22:25], v[196:199], v[180:183], v[22:25]
	v_mfma_f32_16x16x32_f16 v[18:21], v[204:207], v[180:183], v[18:21]
	v_mfma_f32_16x16x32_f16 v[6:9], v[196:199], v[188:191], v[6:9]
	v_mfma_f32_16x16x32_f16 v[2:5], v[204:207], v[188:191], v[2:5]
	s_barrier
	ds_read_b128 v[130:133], v218
	ds_read_b128 v[134:137], v218 offset:1024
	ds_read_b128 v[138:141], v218 offset:2048
	ds_read_b128 v[142:145], v218 offset:3072
	s_add_u32 s22, s22, 0x40000
	s_addc_u32 s23, s23, 0
	s_mov_b32 m0, s59
	v_lshl_add_u64 v[192:193], s[22:23], 0, v[150:151]
	ds_read_b128 v[146:149], v1 offset:32768
	ds_read_b128 v[164:167], v1 offset:33792
	ds_read_b128 v[168:171], v1 offset:34816
	ds_read_b128 v[172:175], v1 offset:35840
	ds_read_b128 v[176:179], v1 offset:36864
	ds_read_b128 v[180:183], v1 offset:37888
	ds_read_b128 v[184:187], v1 offset:38912
	ds_read_b128 v[188:191], v1 offset:39936
	global_load_lds_dwordx4 v[192:193], off
	s_mov_b32 m0, s61
	v_lshl_add_u64 v[192:193], s[22:23], 0, v[152:153]
	global_load_lds_dwordx4 v[192:193], off
	s_waitcnt lgkmcnt(8)
	s_barrier
	s_waitcnt lgkmcnt(0)
	s_waitcnt lgkmcnt(0)
	v_mfma_f32_16x16x32_f16 v[126:129], v[130:133], v[146:149], v[126:129]
	v_mfma_f32_16x16x32_f16 v[122:125], v[138:141], v[146:149], v[122:125]
	v_mfma_f32_16x16x32_f16 v[110:113], v[130:133], v[168:171], v[110:113]
	v_mfma_f32_16x16x32_f16 v[106:109], v[138:141], v[168:171], v[106:109]
	v_mfma_f32_16x16x32_f16 v[94:97], v[130:133], v[176:179], v[94:97]
	v_mfma_f32_16x16x32_f16 v[90:93], v[138:141], v[176:179], v[90:93]
	v_mfma_f32_16x16x32_f16 v[78:81], v[130:133], v[184:187], v[78:81]
	v_mfma_f32_16x16x32_f16 v[74:77], v[138:141], v[184:187], v[74:77]
	v_mfma_f32_16x16x32_f16 v[126:129], v[134:137], v[164:167], v[126:129]
	v_mfma_f32_16x16x32_f16 v[122:125], v[142:145], v[164:167], v[122:125]
	v_mfma_f32_16x16x32_f16 v[110:113], v[134:137], v[172:175], v[110:113]
	v_mfma_f32_16x16x32_f16 v[106:109], v[142:145], v[172:175], v[106:109]
	v_mfma_f32_16x16x32_f16 v[94:97], v[134:137], v[180:183], v[94:97]
	v_mfma_f32_16x16x32_f16 v[90:93], v[142:145], v[180:183], v[90:93]
	v_mfma_f32_16x16x32_f16 v[78:81], v[134:137], v[188:191], v[78:81]
	v_mfma_f32_16x16x32_f16 v[74:77], v[142:145], v[188:191], v[74:77]
	s_barrier
	s_mov_b32 m0, s69
	ds_read_b128 v[192:195], v219
	ds_read_b128 v[196:199], v219 offset:1024
	v_lshl_add_u64 v[208:209], v[208:209], 0, s[86:87]
	ds_read_b128 v[200:203], v219 offset:2048
	ds_read_b128 v[204:207], v219 offset:3072
	global_load_lds_dwordx4 v[208:209], off
	s_mov_b32 m0, s78
	v_lshl_add_u64 v[208:209], v[210:211], 0, s[86:87]
	global_load_lds_dwordx4 v[208:209], off
	s_barrier
; #define G_STAGE(bufoff, gbase, v0, v1) do { \
;     __builtin_amdgcn_global_load_lds((const unsigned*)((const char*)(gbase) + (v0)), (LAS unsigned*)(lds + (bufoff) + ldsw), 16, 0, 0); \
;     __builtin_amdgcn_global_load_lds((const unsigned*)((const char*)(gbase) + (v1)), (LAS unsigned*)(lds + (bufoff) + ldsw + 8192), 16, 0, 0); } while (0)
; #define G_LDA(dst, b, h) do { _Pragma("unroll") for (int m = 0; m < 4; ++m) _Pragma("unroll") for (int k = 0; k < 2; ++k) dst[m][k] = *(const LAS h8*)(lds + G_SA(b, h) + aoff + m * 2048 + k * 1024); } while (0)
; #define G_MMA(ai, bj, At, Bt) do { __builtin_amdgcn_s_setprio(1); _Pragma("unroll") for (int m = 0; m < 4; ++m) _Pragma("unroll") for (int n = 0; n < 2; ++n) _Pragma("unroll") for (int k = 0; k < 2; ++k) \
;     acc[ai][bj][m][n] = __builtin_amdgcn_mfma_f32_16x16x32_f16(Bt[n][k], At[m][k], acc[ai][bj][m][n], 0, 0, 0); __builtin_amdgcn_s_setprio(0); } while (0)
; #define G_WAIT_V(n) asm volatile("s_waitcnt vmcnt(" #n ")" ::: "memory")
; #define G_WAIT_L(n) asm volatile("s_waitcnt lgkmcnt(" #n ")" ::: "memory")
; #define G_BAR __builtin_amdgcn_s_barrier()
; #define G_SCHED __builtin_amdgcn_sched_barrier(0)
; template <bool PERM, class Sched, class Epi>
; DI void gemm256(LAS unsigned char* lds, const Sched& S, const Epi& E, int wv_) {
;     ...
;       G_BAR; G_WAIT_L(0); G_MMA(0, 1, At, B1); G_BAR;
;       G_LDA(At, 1, 1); G_STAGE(G_SA(1, 0), a3, cvA0, cvA1);
;       G_BAR; G_WAIT_L(0); G_MMA(1, 0, At, B0); G_BAR; G_SCHED;
;       G_STAGE(G_SB(1, 1), b3 + chB, cvB0, cvB1);
;       G_WAIT_V(6); G_BAR; G_MMA(1, 1, At, B1); G_BAR;
;     }
	s_waitcnt lgkmcnt(0)
	s_waitcnt lgkmcnt(0)
	v_mfma_f32_16x16x32_f16 v[118:121], v[192:195], v[146:149], v[118:121]
	v_mfma_f32_16x16x32_f16 v[114:117], v[200:203], v[146:149], v[114:117]
	v_mfma_f32_16x16x32_f16 v[102:105], v[192:195], v[168:171], v[102:105]
	v_mfma_f32_16x16x32_f16 v[98:101], v[200:203], v[168:171], v[98:101]
	v_mfma_f32_16x16x32_f16 v[86:89], v[192:195], v[176:179], v[86:89]
	v_mfma_f32_16x16x32_f16 v[82:85], v[200:203], v[176:179], v[82:85]
	v_mfma_f32_16x16x32_f16 v[70:73], v[192:195], v[184:187], v[70:73]
	v_mfma_f32_16x16x32_f16 v[66:69], v[200:203], v[184:187], v[66:69]
	v_mfma_f32_16x16x32_f16 v[118:121], v[196:199], v[164:167], v[118:121]
	v_mfma_f32_16x16x32_f16 v[114:117], v[204:207], v[164:167], v[114:117]
	v_mfma_f32_16x16x32_f16 v[102:105], v[196:199], v[172:175], v[102:105]
	v_mfma_f32_16x16x32_f16 v[98:101], v[204:207], v[172:175], v[98:101]
	v_mfma_f32_16x16x32_f16 v[86:89], v[196:199], v[180:183], v[86:89]
	v_mfma_f32_16x16x32_f16 v[82:85], v[204:207], v[180:183], v[82:85]
	v_mfma_f32_16x16x32_f16 v[70:73], v[196:199], v[188:191], v[70:73]
	v_mfma_f32_16x16x32_f16 v[66:69], v[204:207], v[188:191], v[66:69]
	s_mov_b32 m0, s79
	v_lshl_add_u64 v[208:209], v[212:213], 0, s[86:87]
	s_barrier
	ds_read_b128 v[146:149], v1 offset:49152
	ds_read_b128 v[164:167], v1 offset:50176
	ds_read_b128 v[168:171], v1 offset:51200
	ds_read_b128 v[172:175], v1 offset:52224
	ds_read_b128 v[176:179], v1 offset:53248
	ds_read_b128 v[180:183], v1 offset:54272
	ds_read_b128 v[184:187], v1 offset:55296
	ds_read_b128 v[188:191], v1 offset:56320
	global_load_lds_dwordx4 v[208:209], off
	s_mov_b32 m0, s83
	v_lshl_add_u64 v[208:209], v[214:215], 0, s[86:87]
	global_load_lds_dwordx4 v[208:209], off
	s_barrier
	s_waitcnt lgkmcnt(0)
	s_waitcnt lgkmcnt(0)
	v_mfma_f32_16x16x32_f16 v[62:65], v[130:133], v[146:149], v[62:65]
	v_mfma_f32_16x16x32_f16 v[58:61], v[138:141], v[146:149], v[58:61]
	v_mfma_f32_16x16x32_f16 v[46:49], v[130:133], v[168:171], v[46:49]
	v_mfma_f32_16x16x32_f16 v[42:45], v[138:141], v[168:171], v[42:45]
	v_mfma_f32_16x16x32_f16 v[30:33], v[130:133], v[176:179], v[30:33]
	v_mfma_f32_16x16x32_f16 v[26:29], v[138:141], v[176:179], v[26:29]
	v_mfma_f32_16x16x32_f16 v[14:17], v[130:133], v[184:187], v[14:17]
	v_mfma_f32_16x16x32_f16 v[10:13], v[138:141], v[184:187], v[10:13]
	v_mfma_f32_16x16x32_f16 v[62:65], v[134:137], v[164:167], v[62:65]
	v_mfma_f32_16x16x32_f16 v[58:61], v[142:145], v[164:167], v[58:61]
	v_mfma_f32_16x16x32_f16 v[46:49], v[134:137], v[172:175], v[46:49]
	v_mfma_f32_16x16x32_f16 v[42:45], v[142:145], v[172:175], v[42:45]
	v_mfma_f32_16x16x32_f16 v[30:33], v[134:137], v[180:183], v[30:33]
	v_mfma_f32_16x16x32_f16 v[26:29], v[142:145], v[180:183], v[26:29]
	v_mfma_f32_16x16x32_f16 v[14:17], v[134:137], v[188:191], v[14:17]
	v_mfma_f32_16x16x32_f16 v[10:13], v[142:145], v[188:191], v[10:13]
	s_barrier
	s_add_u32 s20, s20, 0x40080
	s_addc_u32 s21, s21, 0
	s_mov_b32 m0, s90
	v_lshl_add_u64 v[130:131], s[20:21], 0, v[150:151]
	global_load_lds_dwordx4 v[130:131], off
	s_mov_b32 m0, s93
	v_lshl_add_u64 v[130:131], s[20:21], 0, v[152:153]
	global_load_lds_dwordx4 v[130:131], off
	s_waitcnt vmcnt(6)
	s_barrier
	v_mfma_f32_16x16x32_f16 v[54:57], v[192:195], v[146:149], v[54:57]
	v_mfma_f32_16x16x32_f16 v[50:53], v[200:203], v[146:149], v[50:53]
	v_mfma_f32_16x16x32_f16 v[38:41], v[192:195], v[168:171], v[38:41]
	v_mfma_f32_16x16x32_f16 v[34:37], v[200:203], v[168:171], v[34:37]
	v_mfma_f32_16x16x32_f16 v[22:25], v[192:195], v[176:179], v[22:25]
	v_mfma_f32_16x16x32_f16 v[18:21], v[200:203], v[176:179], v[18:21]
	v_mfma_f32_16x16x32_f16 v[6:9], v[192:195], v[184:187], v[6:9]
	v_mfma_f32_16x16x32_f16 v[2:5], v[200:203], v[184:187], v[2:5]
	v_mfma_f32_16x16x32_f16 v[54:57], v[196:199], v[164:167], v[54:57]
	v_mfma_f32_16x16x32_f16 v[50:53], v[204:207], v[164:167], v[50:53]
	v_mfma_f32_16x16x32_f16 v[38:41], v[196:199], v[172:175], v[38:41]
	v_mfma_f32_16x16x32_f16 v[34:37], v[204:207], v[172:175], v[34:37]
	v_mfma_f32_16x16x32_f16 v[22:25], v[196:199], v[180:183], v[22:25]
	v_mfma_f32_16x16x32_f16 v[18:21], v[204:207], v[180:183], v[18:21]
	v_mfma_f32_16x16x32_f16 v[6:9], v[196:199], v[188:191], v[6:9]
	v_mfma_f32_16x16x32_f16 v[2:5], v[204:207], v[188:191], v[2:5]
	s_add_u32 s18, s18, 0x100
	s_addc_u32 s19, s19, 0
	s_add_u32 s75, s75, 0x100
	s_addc_u32 s46, s46, 0
	s_cmp_ge_i32 s74, s25
	s_mov_b32 s20, s74
	s_barrier
	s_cbranch_scc0 .LBB0_2433
	s_mov_b32 s56, 0x8fff
	s_branch .LBB0_2436

; #define G_STAGE(bufoff, gbase, v0, v1) do { \
;     __builtin_amdgcn_global_load_lds((const unsigned*)((const char*)(gbase) + (v0)), (LAS unsigned*)(lds + (bufoff) + ldsw), 16, 0, 0); \
;     __builtin_amdgcn_global_load_lds((const unsigned*)((const char*)(gbase) + (v1)), (LAS unsigned*)(lds + (bufoff) + ldsw + 8192), 16, 0, 0); } while (0)
; #define G_LDA(dst, b, h) do { _Pragma("unroll") for (int m = 0; m < 4; ++m) _Pragma("unroll") for (int k = 0; k < 2; ++k) dst[m][k] = *(const LAS h8*)(lds + G_SA(b, h) + aoff + m * 2048 + k * 1024); } while (0)
; #define G_LDB(dst, b, h) do { _Pragma("unroll") for (int n = 0; n < 2; ++n) _Pragma("unroll") for (int k = 0; k < 2; ++k) dst[n][k] = *(const LAS h8*)(lds + G_SB(b, h) + boff + n * 2048 + k * 1024); } while (0)
; #define G_MMA(ai, bj, At, Bt) do { __builtin_amdgcn_s_setprio(1); _Pragma("unroll") for (int m = 0; m < 4; ++m) _Pragma("unroll") for (int n = 0; n < 2; ++n) _Pragma("unroll") for (int k = 0; k < 2; ++k) \
;     acc[ai][bj][m][n] = __builtin_amdgcn_mfma_f32_16x16x32_f16(Bt[n][k], At[m][k], acc[ai][bj][m][n], 0, 0, 0); __builtin_amdgcn_s_setprio(0); } while (0)
; #define G_WAIT_V(n) asm volatile("s_waitcnt vmcnt(" #n ")" ::: "memory")
; #define G_WAIT_L(n) asm volatile("s_waitcnt lgkmcnt(" #n ")" ::: "memory")
; #define G_BAR __builtin_amdgcn_s_barrier()
; #define G_SCHED __builtin_amdgcn_sched_barrier(0)
; template <bool PERM, class Sched, class Epi>
; DI void gemm256(LAS unsigned char* lds, const Sched& S, const Epi& E, int wv_) {
;     ...
;       const bool last = (t == nt - 2);
;       const char* a1 = cA + (size_t)(t + 1) * kstep;
;       const char* a2 = last ? nA : cA + (size_t)(t + 2) * kstep;
;       const char* b2 = last ? nB : cB + (size_t)(t + 2) * kstep;
;       const char* a3 = a2 + kstep;
;       const char* b3 = b2 + kstep;
;       G_LDB(B0, 0, 0); G_SCHED; G_LDA(At, 0, 0); G_STAGE(G_SA(1, 1), a1 + chA, cvA0, cvA1);
;       G_WAIT_L(8); G_BAR; G_WAIT_L(0); G_MMA(0, 0, At, B0); G_BAR; G_SCHED;
;       G_LDB(B1, 0, 1); G_STAGE(G_SB(0, 0), b2, cvB0, cvB1);
;       G_BAR; G_WAIT_L(0); G_MMA(0, 1, At, B1); G_BAR;
;       G_LDA(At, 0, 1); G_STAGE(G_SA(0, 0), a2, cvA0, cvA1);
;       G_BAR; G_WAIT_L(0); G_MMA(1, 0, At, B0); G_BAR; G_SCHED;
;       G_STAGE(G_SB(0, 1), b2 + chB, cvB0, cvB1);
;       G_WAIT_V(6); G_BAR; G_MMA(1, 1, At, B1); G_BAR;
.LBB0_2581:
	s_add_i32 s68, s14, 2
	ds_read_b128 v[144:147], v216
	ds_read_b128 v[148:151], v216 offset:1024
	ds_read_b128 v[152:155], v216 offset:2048
	ds_read_b128 v[156:159], v216 offset:3072
	s_add_u32 s15, s12, 0xfffc0080
	s_addc_u32 s16, s13, -1
	s_cmp_eq_u32 s11, s14
	s_cselect_b32 s14, s8, s66
	s_cselect_b32 s17, s7, s16
	s_cselect_b32 s16, s6, s15
	s_cselect_b32 s15, s9, s46
	v_lshl_add_u64 v[192:193], s[12:13], 0, v[138:139]
	s_add_i32 m0, s24, 0xc000
	ds_read_b128 v[160:163], v1
	ds_read_b128 v[164:167], v1 offset:1024
	ds_read_b128 v[168:171], v1 offset:2048
	ds_read_b128 v[172:175], v1 offset:3072
	ds_read_b128 v[176:179], v1 offset:4096
	ds_read_b128 v[180:183], v1 offset:5120
	ds_read_b128 v[184:187], v1 offset:6144
	ds_read_b128 v[188:191], v1 offset:7168
	global_load_lds_dwordx4 v[192:193], off
	s_add_i32 m0, s24, 0xe000
	v_lshl_add_u64 v[192:193], s[12:13], 0, v[140:141]
	global_load_lds_dwordx4 v[192:193], off
	s_waitcnt lgkmcnt(8)
	s_barrier
	s_waitcnt lgkmcnt(0)
	s_waitcnt lgkmcnt(0)
	v_mfma_f32_16x16x32_f16 v[126:129], v[144:147], v[160:163], v[126:129]
	v_mfma_f32_16x16x32_f16 v[122:125], v[152:155], v[160:163], v[122:125]
	v_mfma_f32_16x16x32_f16 v[110:113], v[144:147], v[168:171], v[110:113]
	v_mfma_f32_16x16x32_f16 v[106:109], v[152:155], v[168:171], v[106:109]
	v_mfma_f32_16x16x32_f16 v[94:97], v[144:147], v[176:179], v[94:97]
	v_mfma_f32_16x16x32_f16 v[90:93], v[152:155], v[176:179], v[90:93]
	v_mfma_f32_16x16x32_f16 v[78:81], v[144:147], v[184:187], v[78:81]
	v_mfma_f32_16x16x32_f16 v[74:77], v[152:155], v[184:187], v[74:77]
	v_mfma_f32_16x16x32_f16 v[126:129], v[148:151], v[164:167], v[126:129]
	v_mfma_f32_16x16x32_f16 v[122:125], v[156:159], v[164:167], v[122:125]
	v_mfma_f32_16x16x32_f16 v[110:113], v[148:151], v[172:175], v[110:113]
	v_mfma_f32_16x16x32_f16 v[106:109], v[156:159], v[172:175], v[106:109]
	v_mfma_f32_16x16x32_f16 v[94:97], v[148:151], v[180:183], v[94:97]
	v_mfma_f32_16x16x32_f16 v[90:93], v[156:159], v[180:183], v[90:93]
	v_mfma_f32_16x16x32_f16 v[78:81], v[148:151], v[188:191], v[78:81]
	v_mfma_f32_16x16x32_f16 v[74:77], v[156:159], v[188:191], v[74:77]
	s_barrier
	s_mov_b32 m0, s25
	v_lshl_add_u64 v[208:209], s[14:15], 0, v[132:133]
	ds_read_b128 v[192:195], v217
	ds_read_b128 v[196:199], v217 offset:1024
	ds_read_b128 v[200:203], v217 offset:2048
	ds_read_b128 v[204:207], v217 offset:3072
	global_load_lds_dwordx4 v[208:209], off
	s_mov_b32 m0, s26
	v_lshl_add_u64 v[210:211], s[14:15], 0, v[136:137]
	global_load_lds_dwordx4 v[210:211], off
	s_barrier
	s_waitcnt lgkmcnt(0)
	s_waitcnt lgkmcnt(0)
	v_mfma_f32_16x16x32_f16 v[118:121], v[192:195], v[160:163], v[118:121]
	v_mfma_f32_16x16x32_f16 v[114:117], v[200:203], v[160:163], v[114:117]
	v_mfma_f32_16x16x32_f16 v[102:105], v[192:195], v[168:171], v[102:105]
	v_mfma_f32_16x16x32_f16 v[98:101], v[200:203], v[168:171], v[98:101]
	v_mfma_f32_16x16x32_f16 v[86:89], v[192:195], v[176:179], v[86:89]
	v_mfma_f32_16x16x32_f16 v[82:85], v[200:203], v[176:179], v[82:85]
	v_mfma_f32_16x16x32_f16 v[70:73], v[192:195], v[184:187], v[70:73]
	v_mfma_f32_16x16x32_f16 v[66:69], v[200:203], v[184:187], v[66:69]
	v_mfma_f32_16x16x32_f16 v[118:121], v[196:199], v[164:167], v[118:121]
	v_mfma_f32_16x16x32_f16 v[114:117], v[204:207], v[164:167], v[114:117]
	v_mfma_f32_16x16x32_f16 v[102:105], v[196:199], v[172:175], v[102:105]
	v_mfma_f32_16x16x32_f16 v[98:101], v[204:207], v[172:175], v[98:101]
	v_mfma_f32_16x16x32_f16 v[86:89], v[196:199], v[180:183], v[86:89]
	v_mfma_f32_16x16x32_f16 v[82:85], v[204:207], v[180:183], v[82:85]
	v_mfma_f32_16x16x32_f16 v[70:73], v[196:199], v[188:191], v[70:73]
	v_mfma_f32_16x16x32_f16 v[66:69], v[204:207], v[188:191], v[66:69]
	s_mov_b32 m0, s24
	v_lshl_add_u64 v[212:213], s[16:17], 0, v[130:131]
	s_barrier
	ds_read_b128 v[160:163], v1 offset:16384
	ds_read_b128 v[164:167], v1 offset:17408
	ds_read_b128 v[168:171], v1 offset:18432
	ds_read_b128 v[172:175], v1 offset:19456
	ds_read_b128 v[176:179], v1 offset:20480
	ds_read_b128 v[180:183], v1 offset:21504
	ds_read_b128 v[184:187], v1 offset:22528
	ds_read_b128 v[188:191], v1 offset:23552
	global_load_lds_dwordx4 v[212:213], off
	s_mov_b32 m0, s27
	v_lshl_add_u64 v[214:215], s[16:17], 0, v[134:135]
	global_load_lds_dwordx4 v[214:215], off
	s_barrier
	s_waitcnt lgkmcnt(0)
	s_waitcnt lgkmcnt(0)
	v_mfma_f32_16x16x32_f16 v[62:65], v[144:147], v[160:163], v[62:65]
	v_mfma_f32_16x16x32_f16 v[58:61], v[152:155], v[160:163], v[58:61]
	v_mfma_f32_16x16x32_f16 v[46:49], v[144:147], v[168:171], v[46:49]
	v_mfma_f32_16x16x32_f16 v[42:45], v[152:155], v[168:171], v[42:45]
	v_mfma_f32_16x16x32_f16 v[30:33], v[144:147], v[176:179], v[30:33]
	v_mfma_f32_16x16x32_f16 v[26:29], v[152:155], v[176:179], v[26:29]
	v_mfma_f32_16x16x32_f16 v[14:17], v[144:147], v[184:187], v[14:17]
	v_mfma_f32_16x16x32_f16 v[10:13], v[152:155], v[184:187], v[10:13]
	v_mfma_f32_16x16x32_f16 v[62:65], v[148:151], v[164:167], v[62:65]
	v_mfma_f32_16x16x32_f16 v[58:61], v[156:159], v[164:167], v[58:61]
	v_mfma_f32_16x16x32_f16 v[46:49], v[148:151], v[172:175], v[46:49]
	v_mfma_f32_16x16x32_f16 v[42:45], v[156:159], v[172:175], v[42:45]
	v_mfma_f32_16x16x32_f16 v[30:33], v[148:151], v[180:183], v[30:33]
	v_mfma_f32_16x16x32_f16 v[26:29], v[156:159], v[180:183], v[26:29]
	v_mfma_f32_16x16x32_f16 v[14:17], v[148:151], v[188:191], v[14:17]
	v_mfma_f32_16x16x32_f16 v[10:13], v[156:159], v[188:191], v[10:13]
	s_barrier
	s_add_u32 s40, s14, 0x40000
	s_addc_u32 s41, s15, 0
	s_mov_b32 m0, s28
	v_lshl_add_u64 v[144:145], s[40:41], 0, v[132:133]
	global_load_lds_dwordx4 v[144:145], off
	s_mov_b32 m0, s29
	v_lshl_add_u64 v[144:145], s[40:41], 0, v[136:137]
	global_load_lds_dwordx4 v[144:145], off
	s_waitcnt vmcnt(6)
	s_barrier
; #define G_STAGE(bufoff, gbase, v0, v1) do { \
;     __builtin_amdgcn_global_load_lds((const unsigned*)((const char*)(gbase) + (v0)), (LAS unsigned*)(lds + (bufoff) + ldsw), 16, 0, 0); \
;     __builtin_amdgcn_global_load_lds((const unsigned*)((const char*)(gbase) + (v1)), (LAS unsigned*)(lds + (bufoff) + ldsw + 8192), 16, 0, 0); } while (0)
; #define G_LDA(dst, b, h) do { _Pragma("unroll") for (int m = 0; m < 4; ++m) _Pragma("unroll") for (int k = 0; k < 2; ++k) dst[m][k] = *(const LAS h8*)(lds + G_SA(b, h) + aoff + m * 2048 + k * 1024); } while (0)
; #define G_LDB(dst, b, h) do { _Pragma("unroll") for (int n = 0; n < 2; ++n) _Pragma("unroll") for (int k = 0; k < 2; ++k) dst[n][k] = *(const LAS h8*)(lds + G_SB(b, h) + boff + n * 2048 + k * 1024); } while (0)
; #define G_MMA(ai, bj, At, Bt) do { __builtin_amdgcn_s_setprio(1); _Pragma("unroll") for (int m = 0; m < 4; ++m) _Pragma("unroll") for (int n = 0; n < 2; ++n) _Pragma("unroll") for (int k = 0; k < 2; ++k) \
;     acc[ai][bj][m][n] = __builtin_amdgcn_mfma_f32_16x16x32_f16(Bt[n][k], At[m][k], acc[ai][bj][m][n], 0, 0, 0); __builtin_amdgcn_s_setprio(0); } while (0)
; #define G_WAIT_V(n) asm volatile("s_waitcnt vmcnt(" #n ")" ::: "memory")
; #define G_WAIT_L(n) asm volatile("s_waitcnt lgkmcnt(" #n ")" ::: "memory")
; #define G_BAR __builtin_amdgcn_s_barrier()
; #define G_SCHED __builtin_amdgcn_sched_barrier(0)
; template <bool PERM, class Sched, class Epi>
; DI void gemm256(LAS unsigned char* lds, const Sched& S, const Epi& E, int wv_) {
;     ...
;       G_WAIT_V(6); G_BAR; G_MMA(1, 1, At, B1); G_BAR;
;       G_LDB(B0, 1, 0); G_SCHED; G_LDA(At, 1, 0); G_STAGE(G_SA(0, 1), a2 + chA, cvA0, cvA1);
;       G_WAIT_L(8); G_BAR; G_WAIT_L(0); G_MMA(0, 0, At, B0); G_BAR; G_SCHED;
;       G_LDB(B1, 1, 1); G_STAGE(G_SB(1, 0), b3, cvB0, cvB1);
	v_mfma_f32_16x16x32_f16 v[54:57], v[192:195], v[160:163], v[54:57]
	v_mfma_f32_16x16x32_f16 v[50:53], v[200:203], v[160:163], v[50:53]
	v_mfma_f32_16x16x32_f16 v[38:41], v[192:195], v[168:171], v[38:41]
	v_mfma_f32_16x16x32_f16 v[34:37], v[200:203], v[168:171], v[34:37]
	v_mfma_f32_16x16x32_f16 v[22:25], v[192:195], v[176:179], v[22:25]
	v_mfma_f32_16x16x32_f16 v[18:21], v[200:203], v[176:179], v[18:21]
	v_mfma_f32_16x16x32_f16 v[6:9], v[192:195], v[184:187], v[6:9]
	v_mfma_f32_16x16x32_f16 v[2:5], v[200:203], v[184:187], v[2:5]
	v_mfma_f32_16x16x32_f16 v[54:57], v[196:199], v[164:167], v[54:57]
	v_mfma_f32_16x16x32_f16 v[50:53], v[204:207], v[164:167], v[50:53]
	v_mfma_f32_16x16x32_f16 v[38:41], v[196:199], v[172:175], v[38:41]
	v_mfma_f32_16x16x32_f16 v[34:37], v[204:207], v[172:175], v[34:37]
	v_mfma_f32_16x16x32_f16 v[22:25], v[196:199], v[180:183], v[22:25]
	v_mfma_f32_16x16x32_f16 v[18:21], v[204:207], v[180:183], v[18:21]
	v_mfma_f32_16x16x32_f16 v[6:9], v[196:199], v[188:191], v[6:9]
	v_mfma_f32_16x16x32_f16 v[2:5], v[204:207], v[188:191], v[2:5]
	s_barrier
	ds_read_b128 v[144:147], v218
	ds_read_b128 v[148:151], v218 offset:1024
	ds_read_b128 v[152:155], v218 offset:2048
	ds_read_b128 v[156:159], v218 offset:3072
	s_add_u32 s16, s16, 0x40000
	s_addc_u32 s17, s17, 0
	s_mov_b32 m0, s30
	v_lshl_add_u64 v[192:193], s[16:17], 0, v[130:131]
	ds_read_b128 v[160:163], v1 offset:32768
	ds_read_b128 v[164:167], v1 offset:33792
	ds_read_b128 v[168:171], v1 offset:34816
	ds_read_b128 v[172:175], v1 offset:35840
	ds_read_b128 v[176:179], v1 offset:36864
	ds_read_b128 v[180:183], v1 offset:37888
	ds_read_b128 v[184:187], v1 offset:38912
	ds_read_b128 v[188:191], v1 offset:39936
	global_load_lds_dwordx4 v[192:193], off
	s_mov_b32 m0, s31
	v_lshl_add_u64 v[192:193], s[16:17], 0, v[134:135]
	global_load_lds_dwordx4 v[192:193], off
	s_waitcnt lgkmcnt(8)
	s_barrier
	s_waitcnt lgkmcnt(0)
	s_waitcnt lgkmcnt(0)
	v_mfma_f32_16x16x32_f16 v[126:129], v[144:147], v[160:163], v[126:129]
	v_mfma_f32_16x16x32_f16 v[122:125], v[152:155], v[160:163], v[122:125]
	v_mfma_f32_16x16x32_f16 v[110:113], v[144:147], v[168:171], v[110:113]
	v_mfma_f32_16x16x32_f16 v[106:109], v[152:155], v[168:171], v[106:109]
	v_mfma_f32_16x16x32_f16 v[94:97], v[144:147], v[176:179], v[94:97]
	v_mfma_f32_16x16x32_f16 v[90:93], v[152:155], v[176:179], v[90:93]
	v_mfma_f32_16x16x32_f16 v[78:81], v[144:147], v[184:187], v[78:81]
	v_mfma_f32_16x16x32_f16 v[74:77], v[152:155], v[184:187], v[74:77]
	v_mfma_f32_16x16x32_f16 v[126:129], v[148:151], v[164:167], v[126:129]
	v_mfma_f32_16x16x32_f16 v[122:125], v[156:159], v[164:167], v[122:125]
	v_mfma_f32_16x16x32_f16 v[110:113], v[148:151], v[172:175], v[110:113]
	v_mfma_f32_16x16x32_f16 v[106:109], v[156:159], v[172:175], v[106:109]
	v_mfma_f32_16x16x32_f16 v[94:97], v[148:151], v[180:183], v[94:97]
	v_mfma_f32_16x16x32_f16 v[90:93], v[156:159], v[180:183], v[90:93]
	v_mfma_f32_16x16x32_f16 v[78:81], v[148:151], v[188:191], v[78:81]
	v_mfma_f32_16x16x32_f16 v[74:77], v[156:159], v[188:191], v[74:77]
	s_barrier
	s_mov_b32 m0, s35
	v_lshl_add_u64 v[208:209], v[208:209], 0, s[86:87]
	ds_read_b128 v[192:195], v219
	ds_read_b128 v[196:199], v219 offset:1024
	ds_read_b128 v[200:203], v219 offset:2048
	ds_read_b128 v[204:207], v219 offset:3072
	global_load_lds_dwordx4 v[208:209], off
	s_mov_b32 m0, s36
	v_lshl_add_u64 v[208:209], v[210:211], 0, s[86:87]
	global_load_lds_dwordx4 v[208:209], off
	s_barrier
; #define G_STAGE(bufoff, gbase, v0, v1) do { \
;     __builtin_amdgcn_global_load_lds((const unsigned*)((const char*)(gbase) + (v0)), (LAS unsigned*)(lds + (bufoff) + ldsw), 16, 0, 0); \
;     __builtin_amdgcn_global_load_lds((const unsigned*)((const char*)(gbase) + (v1)), (LAS unsigned*)(lds + (bufoff) + ldsw + 8192), 16, 0, 0); } while (0)
; #define G_LDA(dst, b, h) do { _Pragma("unroll") for (int m = 0; m < 4; ++m) _Pragma("unroll") for (int k = 0; k < 2; ++k) dst[m][k] = *(const LAS h8*)(lds + G_SA(b, h) + aoff + m * 2048 + k * 1024); } while (0)
; #define G_MMA(ai, bj, At, Bt) do { __builtin_amdgcn_s_setprio(1); _Pragma("unroll") for (int m = 0; m < 4; ++m) _Pragma("unroll") for (int n = 0; n < 2; ++n) _Pragma("unroll") for (int k = 0; k < 2; ++k) \
;     acc[ai][bj][m][n] = __builtin_amdgcn_mfma_f32_16x16x32_f16(Bt[n][k], At[m][k], acc[ai][bj][m][n], 0, 0, 0); __builtin_amdgcn_s_setprio(0); } while (0)
; #define G_WAIT_V(n) asm volatile("s_waitcnt vmcnt(" #n ")" ::: "memory")
; #define G_WAIT_L(n) asm volatile("s_waitcnt lgkmcnt(" #n ")" ::: "memory")
; #define G_BAR __builtin_amdgcn_s_barrier()
; #define G_SCHED __builtin_amdgcn_sched_barrier(0)
; template <bool PERM, class Sched, class Epi>
; DI void gemm256(LAS unsigned char* lds, const Sched& S, const Epi& E, int wv_) {
;     ...
;       G_BAR; G_WAIT_L(0); G_MMA(0, 1, At, B1); G_BAR;
;       G_LDA(At, 1, 1); G_STAGE(G_SA(1, 0), a3, cvA0, cvA1);
;       G_BAR; G_WAIT_L(0); G_MMA(1, 0, At, B0); G_BAR; G_SCHED;
;       G_STAGE(G_SB(1, 1), b3 + chB, cvB0, cvB1);
;       G_WAIT_V(6); G_BAR; G_MMA(1, 1, At, B1); G_BAR;
;     }
	s_waitcnt lgkmcnt(0)
	s_waitcnt lgkmcnt(0)
	v_mfma_f32_16x16x32_f16 v[118:121], v[192:195], v[160:163], v[118:121]
	v_mfma_f32_16x16x32_f16 v[114:117], v[200:203], v[160:163], v[114:117]
	v_mfma_f32_16x16x32_f16 v[102:105], v[192:195], v[168:171], v[102:105]
	v_mfma_f32_16x16x32_f16 v[98:101], v[200:203], v[168:171], v[98:101]
	v_mfma_f32_16x16x32_f16 v[86:89], v[192:195], v[176:179], v[86:89]
	v_mfma_f32_16x16x32_f16 v[82:85], v[200:203], v[176:179], v[82:85]
	v_mfma_f32_16x16x32_f16 v[70:73], v[192:195], v[184:187], v[70:73]
	v_mfma_f32_16x16x32_f16 v[66:69], v[200:203], v[184:187], v[66:69]
	v_mfma_f32_16x16x32_f16 v[118:121], v[196:199], v[164:167], v[118:121]
	v_mfma_f32_16x16x32_f16 v[114:117], v[204:207], v[164:167], v[114:117]
	v_mfma_f32_16x16x32_f16 v[102:105], v[196:199], v[172:175], v[102:105]
	v_mfma_f32_16x16x32_f16 v[98:101], v[204:207], v[172:175], v[98:101]
	v_mfma_f32_16x16x32_f16 v[86:89], v[196:199], v[180:183], v[86:89]
	v_mfma_f32_16x16x32_f16 v[82:85], v[204:207], v[180:183], v[82:85]
	v_mfma_f32_16x16x32_f16 v[70:73], v[196:199], v[188:191], v[70:73]
	v_mfma_f32_16x16x32_f16 v[66:69], v[204:207], v[188:191], v[66:69]
	s_mov_b32 m0, s37
	v_lshl_add_u64 v[208:209], v[212:213], 0, s[86:87]
	s_barrier
	ds_read_b128 v[160:163], v1 offset:49152
	ds_read_b128 v[164:167], v1 offset:50176
	ds_read_b128 v[168:171], v1 offset:51200
	ds_read_b128 v[172:175], v1 offset:52224
	ds_read_b128 v[176:179], v1 offset:53248
	ds_read_b128 v[180:183], v1 offset:54272
	ds_read_b128 v[184:187], v1 offset:55296
	ds_read_b128 v[188:191], v1 offset:56320
	global_load_lds_dwordx4 v[208:209], off
	s_mov_b32 m0, s52
	v_lshl_add_u64 v[208:209], v[214:215], 0, s[86:87]
	global_load_lds_dwordx4 v[208:209], off
	s_barrier
	s_waitcnt lgkmcnt(0)
	s_waitcnt lgkmcnt(0)
	v_mfma_f32_16x16x32_f16 v[62:65], v[144:147], v[160:163], v[62:65]
	v_mfma_f32_16x16x32_f16 v[58:61], v[152:155], v[160:163], v[58:61]
	v_mfma_f32_16x16x32_f16 v[46:49], v[144:147], v[168:171], v[46:49]
	v_mfma_f32_16x16x32_f16 v[42:45], v[152:155], v[168:171], v[42:45]
	v_mfma_f32_16x16x32_f16 v[30:33], v[144:147], v[176:179], v[30:33]
	v_mfma_f32_16x16x32_f16 v[26:29], v[152:155], v[176:179], v[26:29]
	v_mfma_f32_16x16x32_f16 v[14:17], v[144:147], v[184:187], v[14:17]
	v_mfma_f32_16x16x32_f16 v[10:13], v[152:155], v[184:187], v[10:13]
	v_mfma_f32_16x16x32_f16 v[62:65], v[148:151], v[164:167], v[62:65]
	v_mfma_f32_16x16x32_f16 v[58:61], v[156:159], v[164:167], v[58:61]
	v_mfma_f32_16x16x32_f16 v[46:49], v[148:151], v[172:175], v[46:49]
	v_mfma_f32_16x16x32_f16 v[42:45], v[156:159], v[172:175], v[42:45]
	v_mfma_f32_16x16x32_f16 v[30:33], v[148:151], v[180:183], v[30:33]
	v_mfma_f32_16x16x32_f16 v[26:29], v[156:159], v[180:183], v[26:29]
	v_mfma_f32_16x16x32_f16 v[14:17], v[148:151], v[188:191], v[14:17]
	v_mfma_f32_16x16x32_f16 v[10:13], v[156:159], v[188:191], v[10:13]
	s_barrier
	s_add_u32 s14, s14, 0x40080
	s_addc_u32 s15, s15, 0
	s_mov_b32 m0, s53
	v_lshl_add_u64 v[144:145], s[14:15], 0, v[132:133]
	global_load_lds_dwordx4 v[144:145], off
	s_mov_b32 m0, s56
	v_lshl_add_u64 v[144:145], s[14:15], 0, v[136:137]
	global_load_lds_dwordx4 v[144:145], off
	s_waitcnt vmcnt(6)
	s_barrier
	v_mfma_f32_16x16x32_f16 v[54:57], v[192:195], v[160:163], v[54:57]
	v_mfma_f32_16x16x32_f16 v[50:53], v[200:203], v[160:163], v[50:53]
	v_mfma_f32_16x16x32_f16 v[38:41], v[192:195], v[168:171], v[38:41]
	v_mfma_f32_16x16x32_f16 v[34:37], v[200:203], v[168:171], v[34:37]
	v_mfma_f32_16x16x32_f16 v[22:25], v[192:195], v[176:179], v[22:25]
	v_mfma_f32_16x16x32_f16 v[18:21], v[200:203], v[176:179], v[18:21]
	v_mfma_f32_16x16x32_f16 v[6:9], v[192:195], v[184:187], v[6:9]
	v_mfma_f32_16x16x32_f16 v[2:5], v[200:203], v[184:187], v[2:5]
	v_mfma_f32_16x16x32_f16 v[54:57], v[196:199], v[164:167], v[54:57]
	v_mfma_f32_16x16x32_f16 v[50:53], v[204:207], v[164:167], v[50:53]
	v_mfma_f32_16x16x32_f16 v[38:41], v[196:199], v[172:175], v[38:41]
	v_mfma_f32_16x16x32_f16 v[34:37], v[204:207], v[172:175], v[34:37]
	v_mfma_f32_16x16x32_f16 v[22:25], v[196:199], v[180:183], v[22:25]
	v_mfma_f32_16x16x32_f16 v[18:21], v[204:207], v[180:183], v[18:21]
	v_mfma_f32_16x16x32_f16 v[6:9], v[196:199], v[188:191], v[6:9]
	v_mfma_f32_16x16x32_f16 v[2:5], v[204:207], v[188:191], v[2:5]
	s_add_u32 s12, s12, 0x100
	s_addc_u32 s13, s13, 0
	s_add_u32 s66, s66, 0x100
	s_addc_u32 s46, s46, 0
	s_cmp_ge_i32 s68, s5
	s_mov_b32 s14, s68
	s_barrier
	s_cbranch_scc0 .LBB0_2581
	s_branch .LBB0_2583

; #define G_STAGE(bufoff, gbase, v0, v1) do { \
;     __builtin_amdgcn_global_load_lds((const unsigned*)((const char*)(gbase) + (v0)), (LAS unsigned*)(lds + (bufoff) + ldsw), 16, 0, 0); \
;     __builtin_amdgcn_global_load_lds((const unsigned*)((const char*)(gbase) + (v1)), (LAS unsigned*)(lds + (bufoff) + ldsw + 8192), 16, 0, 0); } while (0)
; #define G_LDA(dst, b, h) do { _Pragma("unroll") for (int m = 0; m < 4; ++m) _Pragma("unroll") for (int k = 0; k < 2; ++k) dst[m][k] = *(const LAS h8*)(lds + G_SA(b, h) + aoff + m * 2048 + k * 1024); } while (0)
; #define G_LDB(dst, b, h) do { _Pragma("unroll") for (int n = 0; n < 2; ++n) _Pragma("unroll") for (int k = 0; k < 2; ++k) dst[n][k] = *(const LAS h8*)(lds + G_SB(b, h) + boff + n * 2048 + k * 1024); } while (0)
; #define G_MMA(ai, bj, At, Bt) do { __builtin_amdgcn_s_setprio(1); _Pragma("unroll") for (int m = 0; m < 4; ++m) _Pragma("unroll") for (int n = 0; n < 2; ++n) _Pragma("unroll") for (int k = 0; k < 2; ++k) \
;     acc[ai][bj][m][n] = __builtin_amdgcn_mfma_f32_16x16x32_f16(Bt[n][k], At[m][k], acc[ai][bj][m][n], 0, 0, 0); __builtin_amdgcn_s_setprio(0); } while (0)
; #define G_WAIT_V(n) asm volatile("s_waitcnt vmcnt(" #n ")" ::: "memory")
; #define G_WAIT_L(n) asm volatile("s_waitcnt lgkmcnt(" #n ")" ::: "memory")
; #define G_BAR __builtin_amdgcn_s_barrier()
; #define G_SCHED __builtin_amdgcn_sched_barrier(0)
; template <bool PERM, class Sched, class Epi>
; DI void gemm256(LAS unsigned char* lds, const Sched& S, const Epi& E, int wv_) {
;     ...
;       const bool last = (t == nt - 2);
;       const char* a1 = cA + (size_t)(t + 1) * kstep;
;       const char* a2 = last ? nA : cA + (size_t)(t + 2) * kstep;
;       const char* b2 = last ? nB : cB + (size_t)(t + 2) * kstep;
;       const char* a3 = a2 + kstep;
;       const char* b3 = b2 + kstep;
;       G_LDB(B0, 0, 0); G_SCHED; G_LDA(At, 0, 0); G_STAGE(G_SA(1, 1), a1 + chA, cvA0, cvA1);
;       G_WAIT_L(8); G_BAR; G_WAIT_L(0); G_MMA(0, 0, At, B0); G_BAR; G_SCHED;
;       G_LDB(B1, 0, 1); G_STAGE(G_SB(0, 0), b2, cvB0, cvB1);
;       G_BAR; G_WAIT_L(0); G_MMA(0, 1, At, B1); G_BAR;
;       G_LDA(At, 0, 1); G_STAGE(G_SA(0, 0), a2, cvA0, cvA1);
;       G_BAR; G_WAIT_L(0); G_MMA(1, 0, At, B0); G_BAR; G_SCHED;
;       G_STAGE(G_SB(0, 1), b2 + chB, cvB0, cvB1);
;       G_WAIT_V(6); G_BAR; G_MMA(1, 1, At, B1); G_BAR;
.LBB0_2656:
	s_waitcnt vmcnt(0)
	s_add_i32 s91, s22, 2
	ds_read_b128 v[130:133], v216
	ds_read_b128 v[134:137], v216 offset:1024
	ds_read_b128 v[138:141], v216 offset:2048
	ds_read_b128 v[142:145], v216 offset:3072
	s_add_u32 s23, s20, 0xfff00080
	s_addc_u32 s24, s21, -1
	s_cmp_eq_u32 s27, s22
	s_cselect_b32 s22, vcc_hi, s46
	s_cselect_b32 s25, s29, s24
	s_cselect_b32 s24, s56, s23
	s_cselect_b32 s23, vcc_lo, s74
	v_lshl_add_u64 v[192:193], s[20:21], 0, v[158:159]
	s_add_i32 m0, s35, 0xc000
	ds_read_b128 v[146:149], v1
	ds_read_b128 v[164:167], v1 offset:1024
	ds_read_b128 v[168:171], v1 offset:2048
	ds_read_b128 v[172:175], v1 offset:3072
	ds_read_b128 v[176:179], v1 offset:4096
	ds_read_b128 v[180:183], v1 offset:5120
	ds_read_b128 v[184:187], v1 offset:6144
	ds_read_b128 v[188:191], v1 offset:7168
	global_load_lds_dwordx4 v[192:193], off
	s_add_i32 m0, s35, 0xe000
	v_lshl_add_u64 v[192:193], s[20:21], 0, v[160:161]
	global_load_lds_dwordx4 v[192:193], off
	s_waitcnt lgkmcnt(8)
	s_barrier
	s_waitcnt lgkmcnt(0)
	s_waitcnt lgkmcnt(0)
	v_mfma_f32_16x16x32_f16 v[126:129], v[130:133], v[146:149], v[126:129]
	v_mfma_f32_16x16x32_f16 v[122:125], v[138:141], v[146:149], v[122:125]
	v_mfma_f32_16x16x32_f16 v[110:113], v[130:133], v[168:171], v[110:113]
	v_mfma_f32_16x16x32_f16 v[106:109], v[138:141], v[168:171], v[106:109]
	v_mfma_f32_16x16x32_f16 v[94:97], v[130:133], v[176:179], v[94:97]
	v_mfma_f32_16x16x32_f16 v[90:93], v[138:141], v[176:179], v[90:93]
	v_mfma_f32_16x16x32_f16 v[78:81], v[130:133], v[184:187], v[78:81]
	v_mfma_f32_16x16x32_f16 v[74:77], v[138:141], v[184:187], v[74:77]
	v_mfma_f32_16x16x32_f16 v[126:129], v[134:137], v[164:167], v[126:129]
	v_mfma_f32_16x16x32_f16 v[122:125], v[142:145], v[164:167], v[122:125]
	v_mfma_f32_16x16x32_f16 v[110:113], v[134:137], v[172:175], v[110:113]
	v_mfma_f32_16x16x32_f16 v[106:109], v[142:145], v[172:175], v[106:109]
	v_mfma_f32_16x16x32_f16 v[94:97], v[134:137], v[180:183], v[94:97]
	v_mfma_f32_16x16x32_f16 v[90:93], v[142:145], v[180:183], v[90:93]
	v_mfma_f32_16x16x32_f16 v[78:81], v[134:137], v[188:191], v[78:81]
	v_mfma_f32_16x16x32_f16 v[74:77], v[142:145], v[188:191], v[74:77]
	s_barrier
	s_mov_b32 m0, s36
	ds_read_b128 v[192:195], v217
	ds_read_b128 v[196:199], v217 offset:1024
	v_lshl_add_u64 v[208:209], s[22:23], 0, v[150:151]
	ds_read_b128 v[200:203], v217 offset:2048
	ds_read_b128 v[204:207], v217 offset:3072
	global_load_lds_dwordx4 v[208:209], off
	s_mov_b32 m0, s37
	v_lshl_add_u64 v[210:211], s[22:23], 0, v[152:153]
	global_load_lds_dwordx4 v[210:211], off
	s_barrier
	s_waitcnt lgkmcnt(0)
	s_waitcnt lgkmcnt(0)
	v_mfma_f32_16x16x32_f16 v[118:121], v[192:195], v[146:149], v[118:121]
	v_mfma_f32_16x16x32_f16 v[114:117], v[200:203], v[146:149], v[114:117]
	v_mfma_f32_16x16x32_f16 v[102:105], v[192:195], v[168:171], v[102:105]
	v_mfma_f32_16x16x32_f16 v[98:101], v[200:203], v[168:171], v[98:101]
	v_mfma_f32_16x16x32_f16 v[86:89], v[192:195], v[176:179], v[86:89]
	v_mfma_f32_16x16x32_f16 v[82:85], v[200:203], v[176:179], v[82:85]
	v_mfma_f32_16x16x32_f16 v[70:73], v[192:195], v[184:187], v[70:73]
	v_mfma_f32_16x16x32_f16 v[66:69], v[200:203], v[184:187], v[66:69]
	v_mfma_f32_16x16x32_f16 v[118:121], v[196:199], v[164:167], v[118:121]
	v_mfma_f32_16x16x32_f16 v[114:117], v[204:207], v[164:167], v[114:117]
	v_mfma_f32_16x16x32_f16 v[102:105], v[196:199], v[172:175], v[102:105]
	v_mfma_f32_16x16x32_f16 v[98:101], v[204:207], v[172:175], v[98:101]
	v_mfma_f32_16x16x32_f16 v[86:89], v[196:199], v[180:183], v[86:89]
	v_mfma_f32_16x16x32_f16 v[82:85], v[204:207], v[180:183], v[82:85]
	v_mfma_f32_16x16x32_f16 v[70:73], v[196:199], v[188:191], v[70:73]
	v_mfma_f32_16x16x32_f16 v[66:69], v[204:207], v[188:191], v[66:69]
	s_mov_b32 m0, s35
	v_lshl_add_u64 v[212:213], s[24:25], 0, v[150:151]
	s_barrier
	ds_read_b128 v[146:149], v1 offset:16384
	ds_read_b128 v[164:167], v1 offset:17408
	ds_read_b128 v[168:171], v1 offset:18432
	ds_read_b128 v[172:175], v1 offset:19456
	ds_read_b128 v[176:179], v1 offset:20480
	ds_read_b128 v[180:183], v1 offset:21504
	ds_read_b128 v[184:187], v1 offset:22528
	ds_read_b128 v[188:191], v1 offset:23552
	global_load_lds_dwordx4 v[212:213], off
	s_mov_b32 m0, s52
	v_lshl_add_u64 v[214:215], s[24:25], 0, v[152:153]
	global_load_lds_dwordx4 v[214:215], off
	s_barrier
	s_waitcnt lgkmcnt(0)
	s_waitcnt lgkmcnt(0)
	v_mfma_f32_16x16x32_f16 v[62:65], v[130:133], v[146:149], v[62:65]
	v_mfma_f32_16x16x32_f16 v[58:61], v[138:141], v[146:149], v[58:61]
	v_mfma_f32_16x16x32_f16 v[46:49], v[130:133], v[168:171], v[46:49]
	v_mfma_f32_16x16x32_f16 v[42:45], v[138:141], v[168:171], v[42:45]
	v_mfma_f32_16x16x32_f16 v[30:33], v[130:133], v[176:179], v[30:33]
	v_mfma_f32_16x16x32_f16 v[26:29], v[138:141], v[176:179], v[26:29]
	v_mfma_f32_16x16x32_f16 v[14:17], v[130:133], v[184:187], v[14:17]
	v_mfma_f32_16x16x32_f16 v[10:13], v[138:141], v[184:187], v[10:13]
	v_mfma_f32_16x16x32_f16 v[62:65], v[134:137], v[164:167], v[62:65]
	v_mfma_f32_16x16x32_f16 v[58:61], v[142:145], v[164:167], v[58:61]
	v_mfma_f32_16x16x32_f16 v[46:49], v[134:137], v[172:175], v[46:49]
	v_mfma_f32_16x16x32_f16 v[42:45], v[142:145], v[172:175], v[42:45]
	v_mfma_f32_16x16x32_f16 v[30:33], v[134:137], v[180:183], v[30:33]
	v_mfma_f32_16x16x32_f16 v[26:29], v[142:145], v[180:183], v[26:29]
	v_mfma_f32_16x16x32_f16 v[14:17], v[134:137], v[188:191], v[14:17]
	v_mfma_f32_16x16x32_f16 v[10:13], v[142:145], v[188:191], v[10:13]
	s_barrier
	s_add_u32 s40, s22, 0x100000
	s_addc_u32 s41, s23, 0
	s_mov_b32 m0, s53
	v_lshl_add_u64 v[130:131], s[40:41], 0, v[150:151]
	global_load_lds_dwordx4 v[130:131], off
	s_mov_b32 m0, s58
	v_lshl_add_u64 v[130:131], s[40:41], 0, v[152:153]
	global_load_lds_dwordx4 v[130:131], off
	s_waitcnt vmcnt(6)
	s_barrier
; #define G_STAGE(bufoff, gbase, v0, v1) do { \
;     __builtin_amdgcn_global_load_lds((const unsigned*)((const char*)(gbase) + (v0)), (LAS unsigned*)(lds + (bufoff) + ldsw), 16, 0, 0); \
;     __builtin_amdgcn_global_load_lds((const unsigned*)((const char*)(gbase) + (v1)), (LAS unsigned*)(lds + (bufoff) + ldsw + 8192), 16, 0, 0); } while (0)
; #define G_LDA(dst, b, h) do { _Pragma("unroll") for (int m = 0; m < 4; ++m) _Pragma("unroll") for (int k = 0; k < 2; ++k) dst[m][k] = *(const LAS h8*)(lds + G_SA(b, h) + aoff + m * 2048 + k * 1024); } while (0)
; #define G_LDB(dst, b, h) do { _Pragma("unroll") for (int n = 0; n < 2; ++n) _Pragma("unroll") for (int k = 0; k < 2; ++k) dst[n][k] = *(const LAS h8*)(lds + G_SB(b, h) + boff + n * 2048 + k * 1024); } while (0)
; #define G_MMA(ai, bj, At, Bt) do { __builtin_amdgcn_s_setprio(1); _Pragma("unroll") for (int m = 0; m < 4; ++m) _Pragma("unroll") for (int n = 0; n < 2; ++n) _Pragma("unroll") for (int k = 0; k < 2; ++k) \
;     acc[ai][bj][m][n] = __builtin_amdgcn_mfma_f32_16x16x32_f16(Bt[n][k], At[m][k], acc[ai][bj][m][n], 0, 0, 0); __builtin_amdgcn_s_setprio(0); } while (0)
; #define G_WAIT_V(n) asm volatile("s_waitcnt vmcnt(" #n ")" ::: "memory")
; #define G_WAIT_L(n) asm volatile("s_waitcnt lgkmcnt(" #n ")" ::: "memory")
; #define G_BAR __builtin_amdgcn_s_barrier()
; #define G_SCHED __builtin_amdgcn_sched_barrier(0)
; template <bool PERM, class Sched, class Epi>
; DI void gemm256(LAS unsigned char* lds, const Sched& S, const Epi& E, int wv_) {
;     ...
;       G_WAIT_V(6); G_BAR; G_MMA(1, 1, At, B1); G_BAR;
;       G_LDB(B0, 1, 0); G_SCHED; G_LDA(At, 1, 0); G_STAGE(G_SA(0, 1), a2 + chA, cvA0, cvA1);
;       G_WAIT_L(8); G_BAR; G_WAIT_L(0); G_MMA(0, 0, At, B0); G_BAR; G_SCHED;
;       G_LDB(B1, 1, 1); G_STAGE(G_SB(1, 0), b3, cvB0, cvB1);
	v_mfma_f32_16x16x32_f16 v[54:57], v[192:195], v[146:149], v[54:57]
	v_mfma_f32_16x16x32_f16 v[50:53], v[200:203], v[146:149], v[50:53]
	v_mfma_f32_16x16x32_f16 v[38:41], v[192:195], v[168:171], v[38:41]
	v_mfma_f32_16x16x32_f16 v[34:37], v[200:203], v[168:171], v[34:37]
	v_mfma_f32_16x16x32_f16 v[22:25], v[192:195], v[176:179], v[22:25]
	v_mfma_f32_16x16x32_f16 v[18:21], v[200:203], v[176:179], v[18:21]
	v_mfma_f32_16x16x32_f16 v[6:9], v[192:195], v[184:187], v[6:9]
	v_mfma_f32_16x16x32_f16 v[2:5], v[200:203], v[184:187], v[2:5]
	v_mfma_f32_16x16x32_f16 v[54:57], v[196:199], v[164:167], v[54:57]
	v_mfma_f32_16x16x32_f16 v[50:53], v[204:207], v[164:167], v[50:53]
	v_mfma_f32_16x16x32_f16 v[38:41], v[196:199], v[172:175], v[38:41]
	v_mfma_f32_16x16x32_f16 v[34:37], v[204:207], v[172:175], v[34:37]
	v_mfma_f32_16x16x32_f16 v[22:25], v[196:199], v[180:183], v[22:25]
	v_mfma_f32_16x16x32_f16 v[18:21], v[204:207], v[180:183], v[18:21]
	v_mfma_f32_16x16x32_f16 v[6:9], v[196:199], v[188:191], v[6:9]
	v_mfma_f32_16x16x32_f16 v[2:5], v[204:207], v[188:191], v[2:5]
	s_barrier
	ds_read_b128 v[130:133], v218
	ds_read_b128 v[134:137], v218 offset:1024
	ds_read_b128 v[138:141], v218 offset:2048
	ds_read_b128 v[142:145], v218 offset:3072
	s_add_u32 s24, s24, 0x100000
	s_addc_u32 s25, s25, 0
	s_mov_b32 m0, s59
	v_lshl_add_u64 v[192:193], s[24:25], 0, v[150:151]
	ds_read_b128 v[146:149], v1 offset:32768
	ds_read_b128 v[164:167], v1 offset:33792
	ds_read_b128 v[168:171], v1 offset:34816
	ds_read_b128 v[172:175], v1 offset:35840
	ds_read_b128 v[176:179], v1 offset:36864
	ds_read_b128 v[180:183], v1 offset:37888
	ds_read_b128 v[184:187], v1 offset:38912
	ds_read_b128 v[188:191], v1 offset:39936
	global_load_lds_dwordx4 v[192:193], off
	s_mov_b32 m0, s61
	v_lshl_add_u64 v[192:193], s[24:25], 0, v[152:153]
	global_load_lds_dwordx4 v[192:193], off
	s_waitcnt lgkmcnt(8)
	s_barrier
	s_waitcnt lgkmcnt(0)
	s_waitcnt lgkmcnt(0)
	v_mfma_f32_16x16x32_f16 v[126:129], v[130:133], v[146:149], v[126:129]
	v_mfma_f32_16x16x32_f16 v[122:125], v[138:141], v[146:149], v[122:125]
	v_mfma_f32_16x16x32_f16 v[110:113], v[130:133], v[168:171], v[110:113]
	v_mfma_f32_16x16x32_f16 v[106:109], v[138:141], v[168:171], v[106:109]
	v_mfma_f32_16x16x32_f16 v[94:97], v[130:133], v[176:179], v[94:97]
	v_mfma_f32_16x16x32_f16 v[90:93], v[138:141], v[176:179], v[90:93]
	v_mfma_f32_16x16x32_f16 v[78:81], v[130:133], v[184:187], v[78:81]
	v_mfma_f32_16x16x32_f16 v[74:77], v[138:141], v[184:187], v[74:77]
	v_mfma_f32_16x16x32_f16 v[126:129], v[134:137], v[164:167], v[126:129]
	v_mfma_f32_16x16x32_f16 v[122:125], v[142:145], v[164:167], v[122:125]
	v_mfma_f32_16x16x32_f16 v[110:113], v[134:137], v[172:175], v[110:113]
	v_mfma_f32_16x16x32_f16 v[106:109], v[142:145], v[172:175], v[106:109]
	v_mfma_f32_16x16x32_f16 v[94:97], v[134:137], v[180:183], v[94:97]
	v_mfma_f32_16x16x32_f16 v[90:93], v[142:145], v[180:183], v[90:93]
	v_mfma_f32_16x16x32_f16 v[78:81], v[134:137], v[188:191], v[78:81]
	v_mfma_f32_16x16x32_f16 v[74:77], v[142:145], v[188:191], v[74:77]
	s_barrier
	s_mov_b32 m0, s69
	ds_read_b128 v[192:195], v219
	ds_read_b128 v[196:199], v219 offset:1024
	v_lshl_add_u64 v[208:209], v[208:209], 0, s[86:87]
	ds_read_b128 v[200:203], v219 offset:2048
	ds_read_b128 v[204:207], v219 offset:3072
	global_load_lds_dwordx4 v[208:209], off
	s_mov_b32 m0, s78
	v_lshl_add_u64 v[208:209], v[210:211], 0, s[86:87]
	global_load_lds_dwordx4 v[208:209], off
	s_barrier
; #define G_STAGE(bufoff, gbase, v0, v1) do { \
;     __builtin_amdgcn_global_load_lds((const unsigned*)((const char*)(gbase) + (v0)), (LAS unsigned*)(lds + (bufoff) + ldsw), 16, 0, 0); \
;     __builtin_amdgcn_global_load_lds((const unsigned*)((const char*)(gbase) + (v1)), (LAS unsigned*)(lds + (bufoff) + ldsw + 8192), 16, 0, 0); } while (0)
; #define G_LDA(dst, b, h) do { _Pragma("unroll") for (int m = 0; m < 4; ++m) _Pragma("unroll") for (int k = 0; k < 2; ++k) dst[m][k] = *(const LAS h8*)(lds + G_SA(b, h) + aoff + m * 2048 + k * 1024); } while (0)
; #define G_MMA(ai, bj, At, Bt) do { __builtin_amdgcn_s_setprio(1); _Pragma("unroll") for (int m = 0; m < 4; ++m) _Pragma("unroll") for (int n = 0; n < 2; ++n) _Pragma("unroll") for (int k = 0; k < 2; ++k) \
;     acc[ai][bj][m][n] = __builtin_amdgcn_mfma_f32_16x16x32_f16(Bt[n][k], At[m][k], acc[ai][bj][m][n], 0, 0, 0); __builtin_amdgcn_s_setprio(0); } while (0)
; #define G_WAIT_V(n) asm volatile("s_waitcnt vmcnt(" #n ")" ::: "memory")
; #define G_WAIT_L(n) asm volatile("s_waitcnt lgkmcnt(" #n ")" ::: "memory")
; #define G_BAR __builtin_amdgcn_s_barrier()
; #define G_SCHED __builtin_amdgcn_sched_barrier(0)
; template <bool PERM, class Sched, class Epi>
; DI void gemm256(LAS unsigned char* lds, const Sched& S, const Epi& E, int wv_) {
;     ...
;       G_BAR; G_WAIT_L(0); G_MMA(0, 1, At, B1); G_BAR;
;       G_LDA(At, 1, 1); G_STAGE(G_SA(1, 0), a3, cvA0, cvA1);
;       G_BAR; G_WAIT_L(0); G_MMA(1, 0, At, B0); G_BAR; G_SCHED;
;       G_STAGE(G_SB(1, 1), b3 + chB, cvB0, cvB1);
;       G_WAIT_V(6); G_BAR; G_MMA(1, 1, At, B1); G_BAR;
;     }
	s_waitcnt lgkmcnt(0)
	s_waitcnt lgkmcnt(0)
	v_mfma_f32_16x16x32_f16 v[118:121], v[192:195], v[146:149], v[118:121]
	v_mfma_f32_16x16x32_f16 v[114:117], v[200:203], v[146:149], v[114:117]
	v_mfma_f32_16x16x32_f16 v[102:105], v[192:195], v[168:171], v[102:105]
	v_mfma_f32_16x16x32_f16 v[98:101], v[200:203], v[168:171], v[98:101]
	v_mfma_f32_16x16x32_f16 v[86:89], v[192:195], v[176:179], v[86:89]
	v_mfma_f32_16x16x32_f16 v[82:85], v[200:203], v[176:179], v[82:85]
	v_mfma_f32_16x16x32_f16 v[70:73], v[192:195], v[184:187], v[70:73]
	v_mfma_f32_16x16x32_f16 v[66:69], v[200:203], v[184:187], v[66:69]
	v_mfma_f32_16x16x32_f16 v[118:121], v[196:199], v[164:167], v[118:121]
	v_mfma_f32_16x16x32_f16 v[114:117], v[204:207], v[164:167], v[114:117]
	v_mfma_f32_16x16x32_f16 v[102:105], v[196:199], v[172:175], v[102:105]
	v_mfma_f32_16x16x32_f16 v[98:101], v[204:207], v[172:175], v[98:101]
	v_mfma_f32_16x16x32_f16 v[86:89], v[196:199], v[180:183], v[86:89]
	v_mfma_f32_16x16x32_f16 v[82:85], v[204:207], v[180:183], v[82:85]
	v_mfma_f32_16x16x32_f16 v[70:73], v[196:199], v[188:191], v[70:73]
	v_mfma_f32_16x16x32_f16 v[66:69], v[204:207], v[188:191], v[66:69]
	s_mov_b32 m0, s79
	v_lshl_add_u64 v[208:209], v[212:213], 0, s[86:87]
	s_barrier
	ds_read_b128 v[146:149], v1 offset:49152
	ds_read_b128 v[164:167], v1 offset:50176
	ds_read_b128 v[168:171], v1 offset:51200
	ds_read_b128 v[172:175], v1 offset:52224
	ds_read_b128 v[176:179], v1 offset:53248
	ds_read_b128 v[180:183], v1 offset:54272
	ds_read_b128 v[184:187], v1 offset:55296
	ds_read_b128 v[188:191], v1 offset:56320
	global_load_lds_dwordx4 v[208:209], off
	s_mov_b32 m0, s83
	v_lshl_add_u64 v[208:209], v[214:215], 0, s[86:87]
	global_load_lds_dwordx4 v[208:209], off
	s_barrier
	s_waitcnt lgkmcnt(0)
	s_waitcnt lgkmcnt(0)
	v_mfma_f32_16x16x32_f16 v[62:65], v[130:133], v[146:149], v[62:65]
	v_mfma_f32_16x16x32_f16 v[58:61], v[138:141], v[146:149], v[58:61]
	v_mfma_f32_16x16x32_f16 v[46:49], v[130:133], v[168:171], v[46:49]
	v_mfma_f32_16x16x32_f16 v[42:45], v[138:141], v[168:171], v[42:45]
	v_mfma_f32_16x16x32_f16 v[30:33], v[130:133], v[176:179], v[30:33]
	v_mfma_f32_16x16x32_f16 v[26:29], v[138:141], v[176:179], v[26:29]
	v_mfma_f32_16x16x32_f16 v[14:17], v[130:133], v[184:187], v[14:17]
	v_mfma_f32_16x16x32_f16 v[10:13], v[138:141], v[184:187], v[10:13]
	v_mfma_f32_16x16x32_f16 v[62:65], v[134:137], v[164:167], v[62:65]
	v_mfma_f32_16x16x32_f16 v[58:61], v[142:145], v[164:167], v[58:61]
	v_mfma_f32_16x16x32_f16 v[46:49], v[134:137], v[172:175], v[46:49]
	v_mfma_f32_16x16x32_f16 v[42:45], v[142:145], v[172:175], v[42:45]
	v_mfma_f32_16x16x32_f16 v[30:33], v[134:137], v[180:183], v[30:33]
	v_mfma_f32_16x16x32_f16 v[26:29], v[142:145], v[180:183], v[26:29]
	v_mfma_f32_16x16x32_f16 v[14:17], v[134:137], v[188:191], v[14:17]
	v_mfma_f32_16x16x32_f16 v[10:13], v[142:145], v[188:191], v[10:13]
	s_barrier
	s_add_u32 s22, s22, 0x100080
	s_addc_u32 s23, s23, 0
	s_mov_b32 m0, s84
	v_lshl_add_u64 v[130:131], s[22:23], 0, v[150:151]
	global_load_lds_dwordx4 v[130:131], off
	s_mov_b32 m0, s85
	v_lshl_add_u64 v[130:131], s[22:23], 0, v[152:153]
	global_load_lds_dwordx4 v[130:131], off
	s_waitcnt vmcnt(6)
	s_barrier
	v_mfma_f32_16x16x32_f16 v[54:57], v[192:195], v[146:149], v[54:57]
	v_mfma_f32_16x16x32_f16 v[50:53], v[200:203], v[146:149], v[50:53]
	v_mfma_f32_16x16x32_f16 v[38:41], v[192:195], v[168:171], v[38:41]
	v_mfma_f32_16x16x32_f16 v[34:37], v[200:203], v[168:171], v[34:37]
	v_mfma_f32_16x16x32_f16 v[22:25], v[192:195], v[176:179], v[22:25]
	v_mfma_f32_16x16x32_f16 v[18:21], v[200:203], v[176:179], v[18:21]
	v_mfma_f32_16x16x32_f16 v[6:9], v[192:195], v[184:187], v[6:9]
	v_mfma_f32_16x16x32_f16 v[2:5], v[200:203], v[184:187], v[2:5]
	v_mfma_f32_16x16x32_f16 v[54:57], v[196:199], v[164:167], v[54:57]
	v_mfma_f32_16x16x32_f16 v[50:53], v[204:207], v[164:167], v[50:53]
	v_mfma_f32_16x16x32_f16 v[38:41], v[196:199], v[172:175], v[38:41]
	v_mfma_f32_16x16x32_f16 v[34:37], v[204:207], v[172:175], v[34:37]
	v_mfma_f32_16x16x32_f16 v[22:25], v[196:199], v[180:183], v[22:25]
	v_mfma_f32_16x16x32_f16 v[18:21], v[204:207], v[180:183], v[18:21]
	v_mfma_f32_16x16x32_f16 v[6:9], v[196:199], v[188:191], v[6:9]
	v_mfma_f32_16x16x32_f16 v[2:5], v[204:207], v[188:191], v[2:5]
	s_add_u32 s20, s20, 0x100
	s_addc_u32 s21, s21, 0
	s_add_u32 s46, s46, 0x100
	s_addc_u32 s74, s74, 0
	s_cmp_ge_i32 s91, s75
	s_mov_b32 s22, s91
	s_barrier
	s_cbranch_scc0 .LBB0_2656
	v_readlane_b32 s91, v254, 47
	s_mov_b32 s56, 0x8fff
	s_branch .LBB0_2659
